# GEMM K-loops: in every load segment the two LDS-DMA pieces (with M0/address set-up) issue before the ds_read_b128 burst instead of after it
# speedup vs baseline: 1.0027x; 1.0027x over previous
.LBB0_34:
	v_add_u32_e32 v162, 0xc000, v147
	v_lshl_add_u64 v[204:205], v[138:139], 0, s[12:13]
	v_readfirstlane_b32 s1, v162
	v_lshl_add_u64 v[210:211], v[204:205], 0, s[60:61]
	s_mov_b32 m0, s1
	v_add_u32_e32 v163, 0xe000, v147
	global_load_lds_dwordx4 v[210:211], off
	v_lshl_add_u64 v[210:211], v[140:141], 0, s[12:13]
	v_readfirstlane_b32 s1, v163
	v_lshl_add_u64 v[216:217], v[210:211], 0, s[60:61]
	s_mov_b32 m0, s1
	s_nop 0
	global_load_lds_dwordx4 v[216:217], off
	ds_read_b128 v[164:167], v151
	ds_read_b128 v[168:171], v151 offset:1024
	ds_read_b128 v[172:175], v151 offset:2048
	ds_read_b128 v[176:179], v151 offset:3072
	ds_read_b128 v[180:183], v0
	ds_read_b128 v[184:187], v0 offset:1024
	ds_read_b128 v[188:191], v0 offset:2048
	ds_read_b128 v[192:195], v0 offset:3072
	ds_read_b128 v[196:199], v0 offset:4096
	ds_read_b128 v[200:203], v0 offset:5120
	ds_read_b128 v[222:225], v0 offset:6144
	ds_read_b128 v[232:235], v0 offset:7168
	s_waitcnt lgkmcnt(8)
	s_barrier
	s_waitcnt lgkmcnt(0)
	s_setprio 1
	s_waitcnt lgkmcnt(0)
	v_mfma_f32_16x16x32_bf16 v[126:129], v[164:167], v[180:183], v[126:129]
	v_mfma_f32_16x16x32_bf16 v[122:125], v[172:175], v[180:183], v[122:125]
	v_mfma_f32_16x16x32_bf16 v[118:121], v[164:167], v[188:191], v[118:121]
	v_mfma_f32_16x16x32_bf16 v[114:117], v[172:175], v[188:191], v[114:117]
	v_mfma_f32_16x16x32_bf16 v[110:113], v[164:167], v[196:199], v[110:113]
	v_mfma_f32_16x16x32_bf16 v[106:109], v[172:175], v[196:199], v[106:109]
	v_mfma_f32_16x16x32_bf16 v[102:105], v[164:167], v[222:225], v[102:105]
	v_mfma_f32_16x16x32_bf16 v[98:101], v[172:175], v[222:225], v[98:101]
	v_mfma_f32_16x16x32_bf16 v[126:129], v[168:171], v[184:187], v[126:129]
	v_mfma_f32_16x16x32_bf16 v[122:125], v[176:179], v[184:187], v[122:125]
	v_mfma_f32_16x16x32_bf16 v[118:121], v[168:171], v[192:195], v[118:121]
	v_mfma_f32_16x16x32_bf16 v[114:117], v[176:179], v[192:195], v[114:117]
	v_mfma_f32_16x16x32_bf16 v[110:113], v[168:171], v[200:203], v[110:113]
	v_mfma_f32_16x16x32_bf16 v[106:109], v[176:179], v[200:203], v[106:109]
	v_mfma_f32_16x16x32_bf16 v[102:105], v[168:171], v[232:235], v[102:105]
	v_mfma_f32_16x16x32_bf16 v[98:101], v[176:179], v[232:235], v[98:101]
	s_setprio 0
	s_barrier
	v_lshl_add_u64 v[216:217], v[134:135], 0, s[12:13]
	v_readfirstlane_b32 s1, v149
	v_lshl_add_u64 v[218:219], v[216:217], 0, s[74:75]
	s_mov_b32 m0, s1
	global_load_lds_dwordx4 v[218:219], off
	v_lshl_add_u64 v[218:219], v[136:137], 0, s[12:13]
	v_readfirstlane_b32 s1, v150
	v_lshl_add_u64 v[228:229], v[218:219], 0, s[74:75]
	s_mov_b32 m0, s1
	s_nop 0
	global_load_lds_dwordx4 v[228:229], off
	ds_read_b128 v[236:239], v151 offset:16384
	ds_read_b128 v[240:243], v151 offset:17408
	ds_read_b128 v[244:247], v151 offset:18432
	ds_read_b128 v[248:251], v151 offset:19456
	s_barrier
	s_waitcnt lgkmcnt(0)
	s_setprio 1
	s_waitcnt lgkmcnt(0)
	v_mfma_f32_16x16x32_bf16 v[94:97], v[236:239], v[180:183], v[94:97]
	v_mfma_f32_16x16x32_bf16 v[90:93], v[244:247], v[180:183], v[90:93]
	v_mfma_f32_16x16x32_bf16 v[86:89], v[236:239], v[188:191], v[86:89]
	v_mfma_f32_16x16x32_bf16 v[70:73], v[244:247], v[188:191], v[70:73]
	v_mfma_f32_16x16x32_bf16 v[62:65], v[236:239], v[196:199], v[62:65]
	v_mfma_f32_16x16x32_bf16 v[58:61], v[244:247], v[196:199], v[58:61]
	v_mfma_f32_16x16x32_bf16 v[54:57], v[236:239], v[222:225], v[54:57]
	v_mfma_f32_16x16x32_bf16 v[50:53], v[244:247], v[222:225], v[50:53]
	v_mfma_f32_16x16x32_bf16 v[94:97], v[240:243], v[184:187], v[94:97]
	v_mfma_f32_16x16x32_bf16 v[90:93], v[248:251], v[184:187], v[90:93]
	v_mfma_f32_16x16x32_bf16 v[86:89], v[240:243], v[192:195], v[86:89]
	v_mfma_f32_16x16x32_bf16 v[70:73], v[248:251], v[192:195], v[70:73]
	v_mfma_f32_16x16x32_bf16 v[62:65], v[240:243], v[200:203], v[62:65]
	v_mfma_f32_16x16x32_bf16 v[58:61], v[248:251], v[200:203], v[58:61]
	v_mfma_f32_16x16x32_bf16 v[54:57], v[240:243], v[232:235], v[54:57]
	v_mfma_f32_16x16x32_bf16 v[50:53], v[248:251], v[232:235], v[50:53]
	s_setprio 0
	v_readfirstlane_b32 s1, v147
	v_lshl_add_u64 v[228:229], v[204:205], 0, s[74:75]
	s_mov_b32 m0, s1
	v_readfirstlane_b32 s1, v148
	s_barrier
	global_load_lds_dwordx4 v[228:229], off
	v_lshl_add_u64 v[228:229], v[210:211], 0, s[74:75]
	s_mov_b32 m0, s1
	s_nop 0
	global_load_lds_dwordx4 v[228:229], off
	ds_read_b128 v[180:183], v0 offset:16384
	ds_read_b128 v[184:187], v0 offset:17408
	ds_read_b128 v[188:191], v0 offset:18432
	ds_read_b128 v[192:195], v0 offset:19456
	ds_read_b128 v[196:199], v0 offset:20480
	ds_read_b128 v[200:203], v0 offset:21504
	ds_read_b128 v[222:225], v0 offset:22528
	ds_read_b128 v[232:235], v0 offset:23552
	s_barrier
	s_waitcnt lgkmcnt(0)
	s_setprio 1
	s_waitcnt lgkmcnt(0)
	v_mfma_f32_16x16x32_bf16 v[46:49], v[164:167], v[180:183], v[46:49]
	v_mfma_f32_16x16x32_bf16 v[42:45], v[172:175], v[180:183], v[42:45]
	v_mfma_f32_16x16x32_bf16 v[38:41], v[164:167], v[188:191], v[38:41]
	v_mfma_f32_16x16x32_bf16 v[34:37], v[172:175], v[188:191], v[34:37]
	v_mfma_f32_16x16x32_bf16 v[30:33], v[164:167], v[196:199], v[30:33]
	v_mfma_f32_16x16x32_bf16 v[26:29], v[172:175], v[196:199], v[26:29]
	v_mfma_f32_16x16x32_bf16 v[22:25], v[164:167], v[222:225], v[22:25]
	v_mfma_f32_16x16x32_bf16 v[18:21], v[172:175], v[222:225], v[18:21]
	v_mfma_f32_16x16x32_bf16 v[46:49], v[168:171], v[184:187], v[46:49]
	v_mfma_f32_16x16x32_bf16 v[42:45], v[176:179], v[184:187], v[42:45]
	v_mfma_f32_16x16x32_bf16 v[38:41], v[168:171], v[192:195], v[38:41]
	v_mfma_f32_16x16x32_bf16 v[34:37], v[176:179], v[192:195], v[34:37]
	v_mfma_f32_16x16x32_bf16 v[30:33], v[168:171], v[200:203], v[30:33]
	v_mfma_f32_16x16x32_bf16 v[26:29], v[176:179], v[200:203], v[26:29]
	v_mfma_f32_16x16x32_bf16 v[22:25], v[168:171], v[232:235], v[22:25]
	v_mfma_f32_16x16x32_bf16 v[18:21], v[176:179], v[232:235], v[18:21]
	s_setprio 0
	s_barrier
	v_readfirstlane_b32 s1, v152
	v_lshl_add_u64 v[164:165], v[216:217], 0, s[18:19]
	s_mov_b32 m0, s1
	v_readfirstlane_b32 s1, v153
	global_load_lds_dwordx4 v[164:165], off
	v_lshl_add_u64 v[164:165], v[218:219], 0, s[18:19]
	s_mov_b32 m0, s1
	s_nop 0
	global_load_lds_dwordx4 v[164:165], off
	s_waitcnt vmcnt(6)
	s_barrier
	s_setprio 1
	v_mfma_f32_16x16x32_bf16 v[14:17], v[236:239], v[180:183], v[14:17]
	v_mfma_f32_16x16x32_bf16 v[10:13], v[244:247], v[180:183], v[10:13]
	v_mfma_f32_16x16x32_bf16 v[6:9], v[236:239], v[188:191], v[6:9]
	v_mfma_f32_16x16x32_bf16 v[2:5], v[244:247], v[188:191], v[2:5]
	v_mfma_f32_16x16x32_bf16 v[66:69], v[236:239], v[196:199], v[66:69]
	v_mfma_f32_16x16x32_bf16 v[74:77], v[244:247], v[196:199], v[74:77]
	v_mfma_f32_16x16x32_bf16 v[78:81], v[236:239], v[222:225], v[78:81]
	v_mfma_f32_16x16x32_bf16 v[82:85], v[244:247], v[222:225], v[82:85]
	v_mfma_f32_16x16x32_bf16 v[14:17], v[240:243], v[184:187], v[14:17]
	v_mfma_f32_16x16x32_bf16 v[10:13], v[248:251], v[184:187], v[10:13]
	v_mfma_f32_16x16x32_bf16 v[6:9], v[240:243], v[192:195], v[6:9]
	v_mfma_f32_16x16x32_bf16 v[2:5], v[248:251], v[192:195], v[2:5]
	v_mfma_f32_16x16x32_bf16 v[66:69], v[240:243], v[200:203], v[66:69]
	v_mfma_f32_16x16x32_bf16 v[74:77], v[248:251], v[200:203], v[74:77]
	v_mfma_f32_16x16x32_bf16 v[78:81], v[240:243], v[232:235], v[78:81]
	v_mfma_f32_16x16x32_bf16 v[82:85], v[248:251], v[232:235], v[82:85]
	s_setprio 0
	s_barrier
	v_readfirstlane_b32 s1, v154
	v_lshl_add_u64 v[228:229], v[204:205], 0, s[18:19]
	s_mov_b32 m0, s1
	v_readfirstlane_b32 s1, v155
	global_load_lds_dwordx4 v[228:229], off
	v_lshl_add_u64 v[228:229], v[210:211], 0, s[18:19]
	s_mov_b32 m0, s1
	s_nop 0
	global_load_lds_dwordx4 v[228:229], off
	ds_read_b128 v[164:167], v151 offset:32768
	ds_read_b128 v[168:171], v151 offset:33792
	ds_read_b128 v[172:175], v151 offset:34816
	ds_read_b128 v[176:179], v151 offset:35840
	ds_read_b128 v[180:183], v0 offset:32768
	ds_read_b128 v[184:187], v0 offset:33792
	ds_read_b128 v[188:191], v0 offset:34816
	ds_read_b128 v[192:195], v0 offset:35840
	ds_read_b128 v[196:199], v0 offset:36864
	ds_read_b128 v[200:203], v0 offset:37888
	ds_read_b128 v[222:225], v0 offset:38912
	ds_read_b128 v[232:235], v0 offset:39936
	s_waitcnt lgkmcnt(8)
	s_barrier
	s_waitcnt lgkmcnt(0)
	s_setprio 1
	s_waitcnt lgkmcnt(0)
	v_mfma_f32_16x16x32_bf16 v[126:129], v[164:167], v[180:183], v[126:129]
	v_mfma_f32_16x16x32_bf16 v[122:125], v[172:175], v[180:183], v[122:125]
	v_mfma_f32_16x16x32_bf16 v[118:121], v[164:167], v[188:191], v[118:121]
	v_mfma_f32_16x16x32_bf16 v[114:117], v[172:175], v[188:191], v[114:117]
	v_mfma_f32_16x16x32_bf16 v[110:113], v[164:167], v[196:199], v[110:113]
	v_mfma_f32_16x16x32_bf16 v[106:109], v[172:175], v[196:199], v[106:109]
	v_mfma_f32_16x16x32_bf16 v[102:105], v[164:167], v[222:225], v[102:105]
	v_mfma_f32_16x16x32_bf16 v[98:101], v[172:175], v[222:225], v[98:101]
	v_mfma_f32_16x16x32_bf16 v[126:129], v[168:171], v[184:187], v[126:129]
	v_mfma_f32_16x16x32_bf16 v[122:125], v[176:179], v[184:187], v[122:125]
	v_mfma_f32_16x16x32_bf16 v[118:121], v[168:171], v[192:195], v[118:121]
	v_mfma_f32_16x16x32_bf16 v[114:117], v[176:179], v[192:195], v[114:117]
	v_mfma_f32_16x16x32_bf16 v[110:113], v[168:171], v[200:203], v[110:113]
	v_mfma_f32_16x16x32_bf16 v[106:109], v[176:179], v[200:203], v[106:109]
	v_mfma_f32_16x16x32_bf16 v[102:105], v[168:171], v[232:235], v[102:105]
	v_mfma_f32_16x16x32_bf16 v[98:101], v[176:179], v[232:235], v[98:101]
	s_setprio 0
	s_barrier
	v_readfirstlane_b32 s1, v156
	v_lshl_add_u64 v[228:229], v[216:217], 0, s[28:29]
	s_mov_b32 m0, s1
	v_readfirstlane_b32 s1, v157
	global_load_lds_dwordx4 v[228:229], off
	v_lshl_add_u64 v[228:229], v[218:219], 0, s[28:29]
	s_mov_b32 m0, s1
	s_nop 0
	global_load_lds_dwordx4 v[228:229], off
	ds_read_b128 v[236:239], v151 offset:49152
	ds_read_b128 v[240:243], v151 offset:50176
	ds_read_b128 v[244:247], v151 offset:51200
	ds_read_b128 v[248:251], v151 offset:52224
	s_barrier
	s_waitcnt lgkmcnt(0)
	s_setprio 1
	s_waitcnt lgkmcnt(0)
	v_mfma_f32_16x16x32_bf16 v[94:97], v[236:239], v[180:183], v[94:97]
	v_mfma_f32_16x16x32_bf16 v[90:93], v[244:247], v[180:183], v[90:93]
	v_mfma_f32_16x16x32_bf16 v[86:89], v[236:239], v[188:191], v[86:89]
	v_mfma_f32_16x16x32_bf16 v[70:73], v[244:247], v[188:191], v[70:73]
	v_mfma_f32_16x16x32_bf16 v[62:65], v[236:239], v[196:199], v[62:65]
	v_mfma_f32_16x16x32_bf16 v[58:61], v[244:247], v[196:199], v[58:61]
	v_mfma_f32_16x16x32_bf16 v[54:57], v[236:239], v[222:225], v[54:57]
	v_mfma_f32_16x16x32_bf16 v[50:53], v[244:247], v[222:225], v[50:53]
	v_mfma_f32_16x16x32_bf16 v[94:97], v[240:243], v[184:187], v[94:97]
	v_mfma_f32_16x16x32_bf16 v[90:93], v[248:251], v[184:187], v[90:93]
	v_mfma_f32_16x16x32_bf16 v[86:89], v[240:243], v[192:195], v[86:89]
	v_mfma_f32_16x16x32_bf16 v[70:73], v[248:251], v[192:195], v[70:73]
	v_mfma_f32_16x16x32_bf16 v[62:65], v[240:243], v[200:203], v[62:65]
	v_mfma_f32_16x16x32_bf16 v[58:61], v[248:251], v[200:203], v[58:61]
	v_mfma_f32_16x16x32_bf16 v[54:57], v[240:243], v[232:235], v[54:57]
	v_mfma_f32_16x16x32_bf16 v[50:53], v[248:251], v[232:235], v[50:53]
	s_setprio 0
	v_readfirstlane_b32 s1, v158
	v_lshl_add_u64 v[204:205], v[204:205], 0, s[28:29]
	s_mov_b32 m0, s1
	v_readfirstlane_b32 s1, v159
	s_barrier
	global_load_lds_dwordx4 v[204:205], off
	v_lshl_add_u64 v[204:205], v[210:211], 0, s[28:29]
	s_mov_b32 m0, s1
	s_nop 0
	global_load_lds_dwordx4 v[204:205], off
	ds_read_b128 v[180:183], v0 offset:49152
	ds_read_b128 v[184:187], v0 offset:50176
	ds_read_b128 v[188:191], v0 offset:51200
	ds_read_b128 v[192:195], v0 offset:52224
	ds_read_b128 v[196:199], v0 offset:53248
	ds_read_b128 v[200:203], v0 offset:54272
	ds_read_b128 v[222:225], v0 offset:55296
	ds_read_b128 v[232:235], v0 offset:56320
	s_barrier
	s_waitcnt lgkmcnt(0)
	s_setprio 1
	s_waitcnt lgkmcnt(0)
	v_mfma_f32_16x16x32_bf16 v[46:49], v[164:167], v[180:183], v[46:49]
	v_mfma_f32_16x16x32_bf16 v[42:45], v[172:175], v[180:183], v[42:45]
	v_mfma_f32_16x16x32_bf16 v[38:41], v[164:167], v[188:191], v[38:41]
	v_mfma_f32_16x16x32_bf16 v[34:37], v[172:175], v[188:191], v[34:37]
	v_mfma_f32_16x16x32_bf16 v[30:33], v[164:167], v[196:199], v[30:33]
	v_mfma_f32_16x16x32_bf16 v[26:29], v[172:175], v[196:199], v[26:29]
	v_mfma_f32_16x16x32_bf16 v[22:25], v[164:167], v[222:225], v[22:25]
	v_mfma_f32_16x16x32_bf16 v[18:21], v[172:175], v[222:225], v[18:21]
	v_mfma_f32_16x16x32_bf16 v[46:49], v[168:171], v[184:187], v[46:49]
	v_mfma_f32_16x16x32_bf16 v[42:45], v[176:179], v[184:187], v[42:45]
	v_mfma_f32_16x16x32_bf16 v[38:41], v[168:171], v[192:195], v[38:41]
	v_mfma_f32_16x16x32_bf16 v[34:37], v[176:179], v[192:195], v[34:37]
	v_mfma_f32_16x16x32_bf16 v[30:33], v[168:171], v[200:203], v[30:33]
	v_mfma_f32_16x16x32_bf16 v[26:29], v[176:179], v[200:203], v[26:29]
	v_mfma_f32_16x16x32_bf16 v[22:25], v[168:171], v[232:235], v[22:25]
	v_mfma_f32_16x16x32_bf16 v[18:21], v[176:179], v[232:235], v[18:21]
	s_setprio 0
	s_barrier
	v_readfirstlane_b32 s1, v160
	v_lshl_add_u64 v[164:165], v[216:217], 0, s[30:31]
	s_mov_b32 m0, s1
	v_readfirstlane_b32 s1, v161
	global_load_lds_dwordx4 v[164:165], off
	v_lshl_add_u64 v[164:165], v[218:219], 0, s[30:31]
	s_mov_b32 m0, s1
	s_nop 0
	global_load_lds_dwordx4 v[164:165], off
	s_waitcnt vmcnt(6)
	s_barrier
	s_setprio 1
	v_mfma_f32_16x16x32_bf16 v[14:17], v[236:239], v[180:183], v[14:17]
	v_mfma_f32_16x16x32_bf16 v[10:13], v[244:247], v[180:183], v[10:13]
	v_mfma_f32_16x16x32_bf16 v[6:9], v[236:239], v[188:191], v[6:9]
	v_mfma_f32_16x16x32_bf16 v[2:5], v[244:247], v[188:191], v[2:5]
	v_mfma_f32_16x16x32_bf16 v[66:69], v[236:239], v[196:199], v[66:69]
	v_mfma_f32_16x16x32_bf16 v[74:77], v[244:247], v[196:199], v[74:77]
	v_mfma_f32_16x16x32_bf16 v[78:81], v[236:239], v[222:225], v[78:81]
	v_mfma_f32_16x16x32_bf16 v[82:85], v[244:247], v[222:225], v[82:85]
	v_mfma_f32_16x16x32_bf16 v[14:17], v[240:243], v[184:187], v[14:17]
	v_mfma_f32_16x16x32_bf16 v[10:13], v[248:251], v[184:187], v[10:13]
	v_mfma_f32_16x16x32_bf16 v[6:9], v[240:243], v[192:195], v[6:9]
	v_mfma_f32_16x16x32_bf16 v[2:5], v[248:251], v[192:195], v[2:5]
	v_mfma_f32_16x16x32_bf16 v[66:69], v[240:243], v[200:203], v[66:69]
	v_mfma_f32_16x16x32_bf16 v[74:77], v[248:251], v[200:203], v[74:77]
	v_mfma_f32_16x16x32_bf16 v[78:81], v[240:243], v[232:235], v[78:81]
	v_mfma_f32_16x16x32_bf16 v[82:85], v[248:251], v[232:235], v[82:85]
	s_setprio 0
	s_add_i32 s0, s0, 2
	s_add_u32 s12, s12, 0x100
	s_addc_u32 s13, s13, 0
	s_cmp_lt_u32 s0, 28
	s_barrier
	s_cbranch_scc1 .LBB0_34
	s_mov_b64 s[12:13], 0xf80
	v_readfirstlane_b32 s0, v162
	v_lshl_add_u64 v[132:133], v[132:133], 0, s[12:13]
	s_mov_b32 m0, s0
	v_readfirstlane_b32 s0, v163
	ds_read_b128 v[134:137], v151
	ds_read_b128 v[138:141], v151 offset:1024
	ds_read_b128 v[152:155], v151 offset:2048
	ds_read_b128 v[156:159], v151 offset:3072
	ds_read_b128 v[164:167], v0
	ds_read_b128 v[168:171], v0 offset:1024
	ds_read_b128 v[172:175], v0 offset:2048
	ds_read_b128 v[176:179], v0 offset:3072
	ds_read_b128 v[180:183], v0 offset:4096
	ds_read_b128 v[184:187], v0 offset:5120
	ds_read_b128 v[188:191], v0 offset:6144
	ds_read_b128 v[192:195], v0 offset:7168
	global_load_lds_dwordx4 v[132:133], off
	v_lshl_add_u64 v[130:131], v[130:131], 0, s[12:13]
	s_mov_b32 m0, s0
	s_nop 0
	global_load_lds_dwordx4 v[130:131], off
	s_barrier
	s_waitcnt lgkmcnt(0)
	s_setprio 1
	s_waitcnt lgkmcnt(0)
	v_mfma_f32_16x16x32_bf16 v[122:125], v[152:155], v[164:167], v[122:125]
	v_mfma_f32_16x16x32_bf16 v[118:121], v[134:137], v[172:175], v[118:121]
	v_mfma_f32_16x16x32_bf16 v[114:117], v[152:155], v[172:175], v[114:117]
	v_mfma_f32_16x16x32_bf16 v[102:105], v[134:137], v[188:191], v[102:105]
	v_mfma_f32_16x16x32_bf16 v[98:101], v[152:155], v[188:191], v[98:101]
	v_mfma_f32_16x16x32_bf16 v[126:129], v[134:137], v[164:167], v[126:129]
	v_mfma_f32_16x16x32_bf16 v[122:125], v[156:159], v[168:171], v[122:125]
	v_mfma_f32_16x16x32_bf16 v[118:121], v[138:141], v[176:179], v[118:121]
	v_mfma_f32_16x16x32_bf16 v[114:117], v[156:159], v[176:179], v[114:117]
	v_mfma_f32_16x16x32_bf16 v[110:113], v[134:137], v[180:183], v[110:113]
	v_mfma_f32_16x16x32_bf16 v[106:109], v[152:155], v[180:183], v[106:109]
	v_mfma_f32_16x16x32_bf16 v[102:105], v[138:141], v[192:195], v[102:105]
	v_mfma_f32_16x16x32_bf16 v[98:101], v[156:159], v[192:195], v[98:101]
	v_mfma_f32_16x16x32_bf16 v[126:129], v[138:141], v[168:171], v[126:129]
	v_mfma_f32_16x16x32_bf16 v[130:133], v[138:141], v[184:187], v[110:113]
	v_mfma_f32_16x16x32_bf16 v[160:163], v[156:159], v[184:187], v[106:109]
	s_setprio 0
	s_barrier
	ds_read_b128 v[106:109], v151 offset:16384
	ds_read_b128 v[110:113], v151 offset:17408
	ds_read_b128 v[196:199], v151 offset:18432
	ds_read_b128 v[200:203], v151 offset:19456
	s_barrier
	s_waitcnt lgkmcnt(0)
	s_setprio 1
	s_waitcnt lgkmcnt(3)
	v_mfma_f32_16x16x32_bf16 v[86:89], v[106:109], v[172:175], v[86:89]
	s_waitcnt lgkmcnt(1)
	v_mfma_f32_16x16x32_bf16 v[70:73], v[196:199], v[172:175], v[70:73]
	v_mfma_f32_16x16x32_bf16 v[62:65], v[106:109], v[180:183], v[62:65]
	v_mfma_f32_16x16x32_bf16 v[58:61], v[196:199], v[180:183], v[58:61]
	v_mfma_f32_16x16x32_bf16 v[54:57], v[106:109], v[188:191], v[54:57]
	v_mfma_f32_16x16x32_bf16 v[50:53], v[196:199], v[188:191], v[50:53]
	v_mfma_f32_16x16x32_bf16 v[94:97], v[106:109], v[164:167], v[94:97]
	v_mfma_f32_16x16x32_bf16 v[90:93], v[196:199], v[164:167], v[90:93]
	v_mfma_f32_16x16x32_bf16 v[86:89], v[110:113], v[176:179], v[86:89]
	s_waitcnt lgkmcnt(0)
	v_mfma_f32_16x16x32_bf16 v[70:73], v[200:203], v[176:179], v[70:73]
	v_mfma_f32_16x16x32_bf16 v[62:65], v[110:113], v[184:187], v[62:65]
	v_mfma_f32_16x16x32_bf16 v[58:61], v[200:203], v[184:187], v[58:61]
	v_mfma_f32_16x16x32_bf16 v[54:57], v[110:113], v[192:195], v[54:57]
	v_mfma_f32_16x16x32_bf16 v[50:53], v[200:203], v[192:195], v[50:53]
	v_mfma_f32_16x16x32_bf16 v[222:225], v[110:113], v[168:171], v[94:97]
	v_mfma_f32_16x16x32_bf16 v[164:167], v[200:203], v[168:171], v[90:93]
	s_setprio 0
	s_barrier
	s_nop 0
	ds_read_b128 v[90:93], v0 offset:16384
	ds_read_b128 v[94:97], v0 offset:17408
	ds_read_b128 v[168:171], v0 offset:18432
	ds_read_b128 v[172:175], v0 offset:19456
	ds_read_b128 v[176:179], v0 offset:20480
	ds_read_b128 v[180:183], v0 offset:21504
	ds_read_b128 v[184:187], v0 offset:22528
	ds_read_b128 v[188:191], v0 offset:23552
	s_waitcnt vmcnt(4)
	s_barrier
	s_waitcnt lgkmcnt(0)
	s_setprio 1
	s_waitcnt lgkmcnt(7)
	v_mfma_f32_16x16x32_bf16 v[46:49], v[134:137], v[90:93], v[46:49]
	v_mfma_f32_16x16x32_bf16 v[42:45], v[152:155], v[90:93], v[42:45]
	s_waitcnt lgkmcnt(5)
	v_mfma_f32_16x16x32_bf16 v[38:41], v[134:137], v[168:171], v[38:41]
	v_mfma_f32_16x16x32_bf16 v[34:37], v[152:155], v[168:171], v[34:37]
	s_waitcnt lgkmcnt(3)
	v_mfma_f32_16x16x32_bf16 v[30:33], v[134:137], v[176:179], v[30:33]
	v_mfma_f32_16x16x32_bf16 v[26:29], v[152:155], v[176:179], v[26:29]
	s_waitcnt lgkmcnt(1)
	v_mfma_f32_16x16x32_bf16 v[22:25], v[134:137], v[184:187], v[22:25]
	v_mfma_f32_16x16x32_bf16 v[18:21], v[152:155], v[184:187], v[18:21]
	v_mfma_f32_16x16x32_bf16 v[46:49], v[138:141], v[94:97], v[46:49]
	v_mfma_f32_16x16x32_bf16 v[42:45], v[156:159], v[94:97], v[42:45]
	v_mfma_f32_16x16x32_bf16 v[38:41], v[138:141], v[172:175], v[38:41]
	v_mfma_f32_16x16x32_bf16 v[34:37], v[156:159], v[172:175], v[34:37]
	v_mfma_f32_16x16x32_bf16 v[30:33], v[138:141], v[180:183], v[30:33]
	v_mfma_f32_16x16x32_bf16 v[26:29], v[156:159], v[180:183], v[26:29]
	s_waitcnt lgkmcnt(0)
	v_mfma_f32_16x16x32_bf16 v[22:25], v[138:141], v[188:191], v[22:25]
	v_mfma_f32_16x16x32_bf16 v[18:21], v[156:159], v[188:191], v[18:21]
	s_setprio 0
	s_setprio 1
	v_mfma_f32_16x16x32_bf16 v[10:13], v[196:199], v[90:93], v[10:13]
	v_mfma_f32_16x16x32_bf16 v[152:155], v[200:203], v[94:97], v[10:13]
	v_mfma_f32_16x16x32_bf16 v[10:13], v[106:109], v[176:179], v[66:69]
	v_mfma_f32_16x16x32_bf16 v[156:159], v[110:113], v[180:183], v[10:13]
	v_mfma_f32_16x16x32_bf16 v[10:13], v[196:199], v[176:179], v[74:77]
	v_mfma_f32_16x16x32_bf16 v[6:9], v[106:109], v[168:171], v[6:9]
	v_mfma_f32_16x16x32_bf16 v[2:5], v[196:199], v[168:171], v[2:5]
	v_mfma_f32_16x16x32_bf16 v[168:171], v[200:203], v[180:183], v[10:13]
	v_mfma_f32_16x16x32_bf16 v[10:13], v[106:109], v[184:187], v[78:81]
	v_mfma_f32_16x16x32_bf16 v[14:17], v[106:109], v[90:93], v[14:17]
	v_mfma_f32_16x16x32_bf16 v[6:9], v[110:113], v[172:175], v[6:9]
	v_mfma_f32_16x16x32_bf16 v[2:5], v[200:203], v[172:175], v[2:5]
	v_mfma_f32_16x16x32_bf16 v[172:175], v[110:113], v[188:191], v[10:13]
	v_mfma_f32_16x16x32_bf16 v[10:13], v[196:199], v[184:187], v[82:85]
	v_mfma_f32_16x16x32_bf16 v[134:137], v[110:113], v[94:97], v[14:17]
	v_mfma_f32_16x16x32_bf16 v[176:179], v[200:203], v[188:191], v[10:13]
	s_setprio 0
	s_barrier
	s_nop 3
	ds_read_b128 v[10:13], v151 offset:32768
	ds_read_b128 v[14:17], v151 offset:33792
	ds_read_b128 v[180:183], v151 offset:34816
	ds_read_b128 v[184:187], v151 offset:35840
	ds_read_b128 v[66:69], v0 offset:32768
	ds_read_b128 v[82:85], v0 offset:33792
	ds_read_b128 v[188:191], v0 offset:34816
	ds_read_b128 v[192:195], v0 offset:35840
	ds_read_b128 v[196:199], v0 offset:36864
	ds_read_b128 v[200:203], v0 offset:37888
	ds_read_b128 v[232:235], v0 offset:38912
	ds_read_b128 v[236:239], v0 offset:39936
	s_waitcnt vmcnt(2)
	s_barrier
	s_waitcnt lgkmcnt(0)
	s_setprio 1
	s_waitcnt lgkmcnt(7)
	v_mfma_f32_16x16x32_bf16 v[74:77], v[10:13], v[66:69], v[126:129]
	s_waitcnt lgkmcnt(6)
	v_mfma_f32_16x16x32_bf16 v[138:141], v[14:17], v[82:85], v[74:77]
	v_mfma_f32_16x16x32_bf16 v[74:77], v[180:183], v[66:69], v[122:125]
	v_mfma_f32_16x16x32_bf16 v[122:125], v[184:187], v[82:85], v[74:77]
	s_waitcnt lgkmcnt(5)
	v_mfma_f32_16x16x32_bf16 v[74:77], v[10:13], v[188:191], v[118:121]
	s_waitcnt lgkmcnt(4)
	v_mfma_f32_16x16x32_bf16 v[110:113], v[14:17], v[192:195], v[74:77]
	v_mfma_f32_16x16x32_bf16 v[74:77], v[180:183], v[188:191], v[114:117]
	v_mfma_f32_16x16x32_bf16 v[106:109], v[184:187], v[192:195], v[74:77]
	s_waitcnt lgkmcnt(3)
	v_mfma_f32_16x16x32_bf16 v[74:77], v[10:13], v[196:199], v[130:133]
	s_waitcnt lgkmcnt(2)
	v_mfma_f32_16x16x32_bf16 v[94:97], v[14:17], v[200:203], v[74:77]
	v_mfma_f32_16x16x32_bf16 v[74:77], v[180:183], v[196:199], v[160:163]
	v_mfma_f32_16x16x32_bf16 v[90:93], v[184:187], v[200:203], v[74:77]
	s_waitcnt lgkmcnt(1)
	v_mfma_f32_16x16x32_bf16 v[74:77], v[10:13], v[232:235], v[102:105]
	s_waitcnt lgkmcnt(0)
	v_mfma_f32_16x16x32_bf16 v[78:81], v[14:17], v[236:239], v[74:77]
	v_mfma_f32_16x16x32_bf16 v[74:77], v[180:183], v[232:235], v[98:101]
	v_mfma_f32_16x16x32_bf16 v[74:77], v[184:187], v[236:239], v[74:77]
	s_setprio 0
	s_barrier
	ds_read_b128 v[126:129], v151 offset:49152
	ds_read_b128 v[130:133], v151 offset:50176
	ds_read_b128 v[160:163], v151 offset:51200
	ds_read_b128 v[148:151], v151 offset:52224
	s_waitcnt vmcnt(0)
	s_barrier
	s_waitcnt lgkmcnt(0)
	s_setprio 1
	s_waitcnt lgkmcnt(3)
	v_mfma_f32_16x16x32_bf16 v[98:101], v[126:129], v[66:69], v[222:225]
	s_waitcnt lgkmcnt(1)
	v_mfma_f32_16x16x32_bf16 v[66:69], v[160:163], v[66:69], v[164:167]
	s_waitcnt lgkmcnt(0)
	v_mfma_f32_16x16x32_bf16 v[114:117], v[148:151], v[82:85], v[66:69]
	v_mfma_f32_16x16x32_bf16 v[66:69], v[126:129], v[188:191], v[86:89]
	v_mfma_f32_16x16x32_bf16 v[102:105], v[130:133], v[192:195], v[66:69]
	v_mfma_f32_16x16x32_bf16 v[66:69], v[160:163], v[188:191], v[70:73]
	v_mfma_f32_16x16x32_bf16 v[62:65], v[126:129], v[196:199], v[62:65]
	v_mfma_f32_16x16x32_bf16 v[58:61], v[160:163], v[196:199], v[58:61]
	v_mfma_f32_16x16x32_bf16 v[54:57], v[126:129], v[232:235], v[54:57]
	v_mfma_f32_16x16x32_bf16 v[50:53], v[160:163], v[232:235], v[50:53]
	v_mfma_f32_16x16x32_bf16 v[118:121], v[130:133], v[82:85], v[98:101]
	v_mfma_f32_16x16x32_bf16 v[98:101], v[148:151], v[192:195], v[66:69]
	v_mfma_f32_16x16x32_bf16 v[86:89], v[130:133], v[200:203], v[62:65]
	v_mfma_f32_16x16x32_bf16 v[82:85], v[148:151], v[200:203], v[58:61]
	v_mfma_f32_16x16x32_bf16 v[70:73], v[130:133], v[236:239], v[54:57]
	v_mfma_f32_16x16x32_bf16 v[66:69], v[148:151], v[236:239], v[50:53]
	s_setprio 0
	s_barrier
	s_nop 0
	ds_read_b128 v[50:53], v0 offset:49152
	ds_read_b128 v[164:167], v0 offset:50176
	ds_read_b128 v[188:191], v0 offset:51200
	ds_read_b128 v[192:195], v0 offset:52224
	ds_read_b128 v[196:199], v0 offset:53248
	ds_read_b128 v[200:203], v0 offset:54272
	ds_read_b128 v[222:225], v0 offset:55296
	ds_read_b128 v[232:235], v0 offset:56320
	s_barrier
	s_waitcnt lgkmcnt(0)
	s_setprio 1
	s_waitcnt lgkmcnt(7)
	v_mfma_f32_16x16x32_bf16 v[46:49], v[10:13], v[50:53], v[46:49]
	s_waitcnt lgkmcnt(5)
	v_mfma_f32_16x16x32_bf16 v[38:41], v[10:13], v[188:191], v[38:41]
	s_waitcnt lgkmcnt(3)
	v_mfma_f32_16x16x32_bf16 v[30:33], v[10:13], v[196:199], v[30:33]
	s_waitcnt lgkmcnt(1)
	v_mfma_f32_16x16x32_bf16 v[10:13], v[10:13], v[222:225], v[22:25]
	v_mfma_f32_16x16x32_bf16 v[62:65], v[14:17], v[164:167], v[46:49]
	v_mfma_f32_16x16x32_bf16 v[42:45], v[180:183], v[50:53], v[42:45]
	v_mfma_f32_16x16x32_bf16 v[46:49], v[14:17], v[192:195], v[38:41]
	v_mfma_f32_16x16x32_bf16 v[34:37], v[180:183], v[188:191], v[34:37]
	v_mfma_f32_16x16x32_bf16 v[30:33], v[14:17], v[200:203], v[30:33]
	v_mfma_f32_16x16x32_bf16 v[26:29], v[180:183], v[196:199], v[26:29]
	s_waitcnt lgkmcnt(0)
	v_mfma_f32_16x16x32_bf16 v[14:17], v[14:17], v[232:235], v[10:13]
	v_mfma_f32_16x16x32_bf16 v[10:13], v[180:183], v[222:225], v[18:21]
	v_mfma_f32_16x16x32_bf16 v[58:61], v[184:187], v[164:167], v[42:45]
	v_mfma_f32_16x16x32_bf16 v[42:45], v[184:187], v[192:195], v[34:37]
	v_mfma_f32_16x16x32_bf16 v[26:29], v[184:187], v[200:203], v[26:29]
	v_mfma_f32_16x16x32_bf16 v[10:13], v[184:187], v[232:235], v[10:13]
	s_setprio 0
	s_setprio 1
	v_mfma_f32_16x16x32_bf16 v[2:5], v[160:163], v[188:191], v[2:5]
	v_mfma_f32_16x16x32_bf16 v[18:21], v[126:129], v[50:53], v[134:137]
	v_mfma_f32_16x16x32_bf16 v[34:37], v[148:151], v[192:195], v[2:5]
	v_mfma_f32_16x16x32_bf16 v[2:5], v[126:129], v[196:199], v[156:159]
	v_mfma_f32_16x16x32_bf16 v[54:57], v[130:133], v[164:167], v[18:21]
	v_mfma_f32_16x16x32_bf16 v[18:21], v[160:163], v[50:53], v[152:155]
	v_mfma_f32_16x16x32_bf16 v[22:25], v[130:133], v[200:203], v[2:5]
	v_mfma_f32_16x16x32_bf16 v[2:5], v[160:163], v[196:199], v[168:171]
	v_mfma_f32_16x16x32_bf16 v[50:53], v[148:151], v[164:167], v[18:21]
	v_mfma_f32_16x16x32_bf16 v[6:9], v[126:129], v[188:191], v[6:9]
	v_mfma_f32_16x16x32_bf16 v[18:21], v[148:151], v[200:203], v[2:5]
	v_mfma_f32_16x16x32_bf16 v[2:5], v[126:129], v[222:225], v[172:175]
	v_mfma_f32_16x16x32_bf16 v[38:41], v[130:133], v[192:195], v[6:9]
	v_mfma_f32_16x16x32_bf16 v[6:9], v[130:133], v[232:235], v[2:5]
	v_mfma_f32_16x16x32_bf16 v[2:5], v[160:163], v[222:225], v[176:179]
	v_mfma_f32_16x16x32_bf16 v[2:5], v[148:151], v[232:235], v[2:5]
	s_setprio 0
	s_movk_i32 s0, 0x100
	v_cmp_gt_u32_e32 vcc, s0, v142
	s_barrier
	s_and_saveexec_b64 s[0:1], vcc
	s_cbranch_execz .LBB0_37
	s_barrier

.LBB0_85:
	v_add_u32_e32 v162, 0xc000, v147
	v_lshl_add_u64 v[204:205], v[138:139], 0, s[10:11]
	v_readfirstlane_b32 s1, v162
	v_lshl_add_u64 v[210:211], v[204:205], 0, s[60:61]
	s_mov_b32 m0, s1
	v_add_u32_e32 v163, 0xe000, v147
	global_load_lds_dwordx4 v[210:211], off
	v_lshl_add_u64 v[210:211], v[140:141], 0, s[10:11]
	v_readfirstlane_b32 s1, v163
	v_lshl_add_u64 v[216:217], v[210:211], 0, s[60:61]
	s_mov_b32 m0, s1
	s_nop 0
	global_load_lds_dwordx4 v[216:217], off
	ds_read_b128 v[164:167], v151
	ds_read_b128 v[168:171], v151 offset:1024
	ds_read_b128 v[172:175], v151 offset:2048
	ds_read_b128 v[176:179], v151 offset:3072
	ds_read_b128 v[180:183], v0
	ds_read_b128 v[184:187], v0 offset:1024
	ds_read_b128 v[188:191], v0 offset:2048
	ds_read_b128 v[192:195], v0 offset:3072
	ds_read_b128 v[196:199], v0 offset:4096
	ds_read_b128 v[200:203], v0 offset:5120
	ds_read_b128 v[222:225], v0 offset:6144
	ds_read_b128 v[232:235], v0 offset:7168
	s_waitcnt lgkmcnt(8)
	s_barrier
	s_waitcnt lgkmcnt(0)
	s_setprio 1
	s_waitcnt lgkmcnt(0)
	v_mfma_f32_16x16x32_bf16 v[126:129], v[164:167], v[180:183], v[126:129]
	v_mfma_f32_16x16x32_bf16 v[122:125], v[172:175], v[180:183], v[122:125]
	v_mfma_f32_16x16x32_bf16 v[118:121], v[164:167], v[188:191], v[118:121]
	v_mfma_f32_16x16x32_bf16 v[114:117], v[172:175], v[188:191], v[114:117]
	v_mfma_f32_16x16x32_bf16 v[110:113], v[164:167], v[196:199], v[110:113]
	v_mfma_f32_16x16x32_bf16 v[106:109], v[172:175], v[196:199], v[106:109]
	v_mfma_f32_16x16x32_bf16 v[102:105], v[164:167], v[222:225], v[102:105]
	v_mfma_f32_16x16x32_bf16 v[98:101], v[172:175], v[222:225], v[98:101]
	v_mfma_f32_16x16x32_bf16 v[126:129], v[168:171], v[184:187], v[126:129]
	v_mfma_f32_16x16x32_bf16 v[122:125], v[176:179], v[184:187], v[122:125]
	v_mfma_f32_16x16x32_bf16 v[118:121], v[168:171], v[192:195], v[118:121]
	v_mfma_f32_16x16x32_bf16 v[114:117], v[176:179], v[192:195], v[114:117]
	v_mfma_f32_16x16x32_bf16 v[110:113], v[168:171], v[200:203], v[110:113]
	v_mfma_f32_16x16x32_bf16 v[106:109], v[176:179], v[200:203], v[106:109]
	v_mfma_f32_16x16x32_bf16 v[102:105], v[168:171], v[232:235], v[102:105]
	v_mfma_f32_16x16x32_bf16 v[98:101], v[176:179], v[232:235], v[98:101]
	s_setprio 0
	s_barrier
	v_lshl_add_u64 v[216:217], v[134:135], 0, s[10:11]
	v_readfirstlane_b32 s1, v149
	v_lshl_add_u64 v[218:219], v[216:217], 0, s[74:75]
	s_mov_b32 m0, s1
	global_load_lds_dwordx4 v[218:219], off
	v_lshl_add_u64 v[218:219], v[136:137], 0, s[10:11]
	v_readfirstlane_b32 s1, v150
	v_lshl_add_u64 v[228:229], v[218:219], 0, s[74:75]
	s_mov_b32 m0, s1
	s_nop 0
	global_load_lds_dwordx4 v[228:229], off
	ds_read_b128 v[236:239], v151 offset:16384
	ds_read_b128 v[240:243], v151 offset:17408
	ds_read_b128 v[244:247], v151 offset:18432
	ds_read_b128 v[248:251], v151 offset:19456
	s_barrier
	s_waitcnt lgkmcnt(0)
	s_setprio 1
	s_waitcnt lgkmcnt(0)
	v_mfma_f32_16x16x32_bf16 v[94:97], v[236:239], v[180:183], v[94:97]
	v_mfma_f32_16x16x32_bf16 v[90:93], v[244:247], v[180:183], v[90:93]
	v_mfma_f32_16x16x32_bf16 v[86:89], v[236:239], v[188:191], v[86:89]
	v_mfma_f32_16x16x32_bf16 v[82:85], v[244:247], v[188:191], v[82:85]
	v_mfma_f32_16x16x32_bf16 v[78:81], v[236:239], v[196:199], v[78:81]
	v_mfma_f32_16x16x32_bf16 v[74:77], v[244:247], v[196:199], v[74:77]
	v_mfma_f32_16x16x32_bf16 v[70:73], v[236:239], v[222:225], v[70:73]
	v_mfma_f32_16x16x32_bf16 v[66:69], v[244:247], v[222:225], v[66:69]
	v_mfma_f32_16x16x32_bf16 v[94:97], v[240:243], v[184:187], v[94:97]
	v_mfma_f32_16x16x32_bf16 v[90:93], v[248:251], v[184:187], v[90:93]
	v_mfma_f32_16x16x32_bf16 v[86:89], v[240:243], v[192:195], v[86:89]
	v_mfma_f32_16x16x32_bf16 v[82:85], v[248:251], v[192:195], v[82:85]
	v_mfma_f32_16x16x32_bf16 v[78:81], v[240:243], v[200:203], v[78:81]
	v_mfma_f32_16x16x32_bf16 v[74:77], v[248:251], v[200:203], v[74:77]
	v_mfma_f32_16x16x32_bf16 v[70:73], v[240:243], v[232:235], v[70:73]
	v_mfma_f32_16x16x32_bf16 v[66:69], v[248:251], v[232:235], v[66:69]
	s_setprio 0
	v_readfirstlane_b32 s1, v147
	v_lshl_add_u64 v[228:229], v[204:205], 0, s[74:75]
	s_mov_b32 m0, s1
	v_readfirstlane_b32 s1, v148
	s_barrier
	global_load_lds_dwordx4 v[228:229], off
	v_lshl_add_u64 v[228:229], v[210:211], 0, s[74:75]
	s_mov_b32 m0, s1
	s_nop 0
	global_load_lds_dwordx4 v[228:229], off
	ds_read_b128 v[180:183], v0 offset:16384
	ds_read_b128 v[184:187], v0 offset:17408
	ds_read_b128 v[188:191], v0 offset:18432
	ds_read_b128 v[192:195], v0 offset:19456
	ds_read_b128 v[196:199], v0 offset:20480
	ds_read_b128 v[200:203], v0 offset:21504
	ds_read_b128 v[222:225], v0 offset:22528
	ds_read_b128 v[232:235], v0 offset:23552
	s_barrier
	s_waitcnt lgkmcnt(0)
	s_setprio 1
	s_waitcnt lgkmcnt(0)
	v_mfma_f32_16x16x32_bf16 v[62:65], v[164:167], v[180:183], v[62:65]
	v_mfma_f32_16x16x32_bf16 v[58:61], v[172:175], v[180:183], v[58:61]
	v_mfma_f32_16x16x32_bf16 v[54:57], v[164:167], v[188:191], v[54:57]
	v_mfma_f32_16x16x32_bf16 v[50:53], v[172:175], v[188:191], v[50:53]
	v_mfma_f32_16x16x32_bf16 v[46:49], v[164:167], v[196:199], v[46:49]
	v_mfma_f32_16x16x32_bf16 v[42:45], v[172:175], v[196:199], v[42:45]
	v_mfma_f32_16x16x32_bf16 v[38:41], v[164:167], v[222:225], v[38:41]
	v_mfma_f32_16x16x32_bf16 v[34:37], v[172:175], v[222:225], v[34:37]
	v_mfma_f32_16x16x32_bf16 v[62:65], v[168:171], v[184:187], v[62:65]
	v_mfma_f32_16x16x32_bf16 v[58:61], v[176:179], v[184:187], v[58:61]
	v_mfma_f32_16x16x32_bf16 v[54:57], v[168:171], v[192:195], v[54:57]
	v_mfma_f32_16x16x32_bf16 v[50:53], v[176:179], v[192:195], v[50:53]
	v_mfma_f32_16x16x32_bf16 v[46:49], v[168:171], v[200:203], v[46:49]
	v_mfma_f32_16x16x32_bf16 v[42:45], v[176:179], v[200:203], v[42:45]
	v_mfma_f32_16x16x32_bf16 v[38:41], v[168:171], v[232:235], v[38:41]
	v_mfma_f32_16x16x32_bf16 v[34:37], v[176:179], v[232:235], v[34:37]
	s_setprio 0
	s_barrier
	v_readfirstlane_b32 s1, v152
	v_lshl_add_u64 v[164:165], v[216:217], 0, s[18:19]
	s_mov_b32 m0, s1
	v_readfirstlane_b32 s1, v153
	global_load_lds_dwordx4 v[164:165], off
	v_lshl_add_u64 v[164:165], v[218:219], 0, s[18:19]
	s_mov_b32 m0, s1
	s_nop 0
	global_load_lds_dwordx4 v[164:165], off
	s_waitcnt vmcnt(6)
	s_barrier
	s_setprio 1
	v_mfma_f32_16x16x32_bf16 v[30:33], v[236:239], v[180:183], v[30:33]
	v_mfma_f32_16x16x32_bf16 v[26:29], v[244:247], v[180:183], v[26:29]
	v_mfma_f32_16x16x32_bf16 v[22:25], v[236:239], v[188:191], v[22:25]
	v_mfma_f32_16x16x32_bf16 v[18:21], v[244:247], v[188:191], v[18:21]
	v_mfma_f32_16x16x32_bf16 v[14:17], v[236:239], v[196:199], v[14:17]
	v_mfma_f32_16x16x32_bf16 v[10:13], v[244:247], v[196:199], v[10:13]
	v_mfma_f32_16x16x32_bf16 v[6:9], v[236:239], v[222:225], v[6:9]
	v_mfma_f32_16x16x32_bf16 v[2:5], v[244:247], v[222:225], v[2:5]
	v_mfma_f32_16x16x32_bf16 v[30:33], v[240:243], v[184:187], v[30:33]
	v_mfma_f32_16x16x32_bf16 v[26:29], v[248:251], v[184:187], v[26:29]
	v_mfma_f32_16x16x32_bf16 v[22:25], v[240:243], v[192:195], v[22:25]
	v_mfma_f32_16x16x32_bf16 v[18:21], v[248:251], v[192:195], v[18:21]
	v_mfma_f32_16x16x32_bf16 v[14:17], v[240:243], v[200:203], v[14:17]
	v_mfma_f32_16x16x32_bf16 v[10:13], v[248:251], v[200:203], v[10:13]
	v_mfma_f32_16x16x32_bf16 v[6:9], v[240:243], v[232:235], v[6:9]
	v_mfma_f32_16x16x32_bf16 v[2:5], v[248:251], v[232:235], v[2:5]
	s_setprio 0
	s_barrier
	v_readfirstlane_b32 s1, v154
	v_lshl_add_u64 v[228:229], v[204:205], 0, s[18:19]
	s_mov_b32 m0, s1
	v_readfirstlane_b32 s1, v155
	global_load_lds_dwordx4 v[228:229], off
	v_lshl_add_u64 v[228:229], v[210:211], 0, s[18:19]
	s_mov_b32 m0, s1
	s_nop 0
	global_load_lds_dwordx4 v[228:229], off
	ds_read_b128 v[164:167], v151 offset:32768
	ds_read_b128 v[168:171], v151 offset:33792
	ds_read_b128 v[172:175], v151 offset:34816
	ds_read_b128 v[176:179], v151 offset:35840
	ds_read_b128 v[180:183], v0 offset:32768
	ds_read_b128 v[184:187], v0 offset:33792
	ds_read_b128 v[188:191], v0 offset:34816
	ds_read_b128 v[192:195], v0 offset:35840
	ds_read_b128 v[196:199], v0 offset:36864
	ds_read_b128 v[200:203], v0 offset:37888
	ds_read_b128 v[222:225], v0 offset:38912
	ds_read_b128 v[232:235], v0 offset:39936
	s_waitcnt lgkmcnt(8)
	s_barrier
	s_waitcnt lgkmcnt(0)
	s_setprio 1
	s_waitcnt lgkmcnt(0)
	v_mfma_f32_16x16x32_bf16 v[126:129], v[164:167], v[180:183], v[126:129]
	v_mfma_f32_16x16x32_bf16 v[122:125], v[172:175], v[180:183], v[122:125]
	v_mfma_f32_16x16x32_bf16 v[118:121], v[164:167], v[188:191], v[118:121]
	v_mfma_f32_16x16x32_bf16 v[114:117], v[172:175], v[188:191], v[114:117]
	v_mfma_f32_16x16x32_bf16 v[110:113], v[164:167], v[196:199], v[110:113]
	v_mfma_f32_16x16x32_bf16 v[106:109], v[172:175], v[196:199], v[106:109]
	v_mfma_f32_16x16x32_bf16 v[102:105], v[164:167], v[222:225], v[102:105]
	v_mfma_f32_16x16x32_bf16 v[98:101], v[172:175], v[222:225], v[98:101]
	v_mfma_f32_16x16x32_bf16 v[126:129], v[168:171], v[184:187], v[126:129]
	v_mfma_f32_16x16x32_bf16 v[122:125], v[176:179], v[184:187], v[122:125]
	v_mfma_f32_16x16x32_bf16 v[118:121], v[168:171], v[192:195], v[118:121]
	v_mfma_f32_16x16x32_bf16 v[114:117], v[176:179], v[192:195], v[114:117]
	v_mfma_f32_16x16x32_bf16 v[110:113], v[168:171], v[200:203], v[110:113]
	v_mfma_f32_16x16x32_bf16 v[106:109], v[176:179], v[200:203], v[106:109]
	v_mfma_f32_16x16x32_bf16 v[102:105], v[168:171], v[232:235], v[102:105]
	v_mfma_f32_16x16x32_bf16 v[98:101], v[176:179], v[232:235], v[98:101]
	s_setprio 0
	s_barrier
	v_readfirstlane_b32 s1, v156
	v_lshl_add_u64 v[228:229], v[216:217], 0, s[28:29]
	s_mov_b32 m0, s1
	v_readfirstlane_b32 s1, v157
	global_load_lds_dwordx4 v[228:229], off
	v_lshl_add_u64 v[228:229], v[218:219], 0, s[28:29]
	s_mov_b32 m0, s1
	s_nop 0
	global_load_lds_dwordx4 v[228:229], off
	ds_read_b128 v[236:239], v151 offset:49152
	ds_read_b128 v[240:243], v151 offset:50176
	ds_read_b128 v[244:247], v151 offset:51200
	ds_read_b128 v[248:251], v151 offset:52224
	s_barrier
	s_waitcnt lgkmcnt(0)
	s_setprio 1
	s_waitcnt lgkmcnt(0)
	v_mfma_f32_16x16x32_bf16 v[94:97], v[236:239], v[180:183], v[94:97]
	v_mfma_f32_16x16x32_bf16 v[90:93], v[244:247], v[180:183], v[90:93]
	v_mfma_f32_16x16x32_bf16 v[86:89], v[236:239], v[188:191], v[86:89]
	v_mfma_f32_16x16x32_bf16 v[82:85], v[244:247], v[188:191], v[82:85]
	v_mfma_f32_16x16x32_bf16 v[78:81], v[236:239], v[196:199], v[78:81]
	v_mfma_f32_16x16x32_bf16 v[74:77], v[244:247], v[196:199], v[74:77]
	v_mfma_f32_16x16x32_bf16 v[70:73], v[236:239], v[222:225], v[70:73]
	v_mfma_f32_16x16x32_bf16 v[66:69], v[244:247], v[222:225], v[66:69]
	v_mfma_f32_16x16x32_bf16 v[94:97], v[240:243], v[184:187], v[94:97]
	v_mfma_f32_16x16x32_bf16 v[90:93], v[248:251], v[184:187], v[90:93]
	v_mfma_f32_16x16x32_bf16 v[86:89], v[240:243], v[192:195], v[86:89]
	v_mfma_f32_16x16x32_bf16 v[82:85], v[248:251], v[192:195], v[82:85]
	v_mfma_f32_16x16x32_bf16 v[78:81], v[240:243], v[200:203], v[78:81]
	v_mfma_f32_16x16x32_bf16 v[74:77], v[248:251], v[200:203], v[74:77]
	v_mfma_f32_16x16x32_bf16 v[70:73], v[240:243], v[232:235], v[70:73]
	v_mfma_f32_16x16x32_bf16 v[66:69], v[248:251], v[232:235], v[66:69]
	s_setprio 0
	v_readfirstlane_b32 s1, v158
	v_lshl_add_u64 v[204:205], v[204:205], 0, s[28:29]
	s_mov_b32 m0, s1
	v_readfirstlane_b32 s1, v159
	s_barrier
	global_load_lds_dwordx4 v[204:205], off
	v_lshl_add_u64 v[204:205], v[210:211], 0, s[28:29]
	s_mov_b32 m0, s1
	s_nop 0
	global_load_lds_dwordx4 v[204:205], off
	ds_read_b128 v[180:183], v0 offset:49152
	ds_read_b128 v[184:187], v0 offset:50176
	ds_read_b128 v[188:191], v0 offset:51200
	ds_read_b128 v[192:195], v0 offset:52224
	ds_read_b128 v[196:199], v0 offset:53248
	ds_read_b128 v[200:203], v0 offset:54272
	ds_read_b128 v[222:225], v0 offset:55296
	ds_read_b128 v[232:235], v0 offset:56320
	s_barrier
	s_waitcnt lgkmcnt(0)
	s_setprio 1
	s_waitcnt lgkmcnt(0)
	v_mfma_f32_16x16x32_bf16 v[62:65], v[164:167], v[180:183], v[62:65]
	v_mfma_f32_16x16x32_bf16 v[58:61], v[172:175], v[180:183], v[58:61]
	v_mfma_f32_16x16x32_bf16 v[54:57], v[164:167], v[188:191], v[54:57]
	v_mfma_f32_16x16x32_bf16 v[50:53], v[172:175], v[188:191], v[50:53]
	v_mfma_f32_16x16x32_bf16 v[46:49], v[164:167], v[196:199], v[46:49]
	v_mfma_f32_16x16x32_bf16 v[42:45], v[172:175], v[196:199], v[42:45]
	v_mfma_f32_16x16x32_bf16 v[38:41], v[164:167], v[222:225], v[38:41]
	v_mfma_f32_16x16x32_bf16 v[34:37], v[172:175], v[222:225], v[34:37]
	v_mfma_f32_16x16x32_bf16 v[62:65], v[168:171], v[184:187], v[62:65]
	v_mfma_f32_16x16x32_bf16 v[58:61], v[176:179], v[184:187], v[58:61]
	v_mfma_f32_16x16x32_bf16 v[54:57], v[168:171], v[192:195], v[54:57]
	v_mfma_f32_16x16x32_bf16 v[50:53], v[176:179], v[192:195], v[50:53]
	v_mfma_f32_16x16x32_bf16 v[46:49], v[168:171], v[200:203], v[46:49]
	v_mfma_f32_16x16x32_bf16 v[42:45], v[176:179], v[200:203], v[42:45]
	v_mfma_f32_16x16x32_bf16 v[38:41], v[168:171], v[232:235], v[38:41]
	v_mfma_f32_16x16x32_bf16 v[34:37], v[176:179], v[232:235], v[34:37]
	s_setprio 0
	s_barrier
	v_readfirstlane_b32 s1, v160
	v_lshl_add_u64 v[164:165], v[216:217], 0, s[30:31]
	s_mov_b32 m0, s1
	v_readfirstlane_b32 s1, v161
	global_load_lds_dwordx4 v[164:165], off
	v_lshl_add_u64 v[164:165], v[218:219], 0, s[30:31]
	s_mov_b32 m0, s1
	s_nop 0
	global_load_lds_dwordx4 v[164:165], off
	s_waitcnt vmcnt(6)
	s_barrier
	s_setprio 1
	v_mfma_f32_16x16x32_bf16 v[30:33], v[236:239], v[180:183], v[30:33]
	v_mfma_f32_16x16x32_bf16 v[26:29], v[244:247], v[180:183], v[26:29]
	v_mfma_f32_16x16x32_bf16 v[22:25], v[236:239], v[188:191], v[22:25]
	v_mfma_f32_16x16x32_bf16 v[18:21], v[244:247], v[188:191], v[18:21]
	v_mfma_f32_16x16x32_bf16 v[14:17], v[236:239], v[196:199], v[14:17]
	v_mfma_f32_16x16x32_bf16 v[10:13], v[244:247], v[196:199], v[10:13]
	v_mfma_f32_16x16x32_bf16 v[6:9], v[236:239], v[222:225], v[6:9]
	v_mfma_f32_16x16x32_bf16 v[2:5], v[244:247], v[222:225], v[2:5]
	v_mfma_f32_16x16x32_bf16 v[30:33], v[240:243], v[184:187], v[30:33]
	v_mfma_f32_16x16x32_bf16 v[26:29], v[248:251], v[184:187], v[26:29]
	v_mfma_f32_16x16x32_bf16 v[22:25], v[240:243], v[192:195], v[22:25]
	v_mfma_f32_16x16x32_bf16 v[18:21], v[248:251], v[192:195], v[18:21]
	v_mfma_f32_16x16x32_bf16 v[14:17], v[240:243], v[200:203], v[14:17]
	v_mfma_f32_16x16x32_bf16 v[10:13], v[248:251], v[200:203], v[10:13]
	v_mfma_f32_16x16x32_bf16 v[6:9], v[240:243], v[232:235], v[6:9]
	v_mfma_f32_16x16x32_bf16 v[2:5], v[248:251], v[232:235], v[2:5]
	s_setprio 0
	s_add_i32 s0, s0, 2
	s_add_u32 s10, s10, 0x100
	s_addc_u32 s11, s11, 0
	s_cmp_lt_u32 s0, 28
	s_barrier
	s_cbranch_scc1 .LBB0_85
	s_mov_b64 s[10:11], 0xf80
	v_readfirstlane_b32 s0, v162
	v_lshl_add_u64 v[132:133], v[132:133], 0, s[10:11]
	s_mov_b32 m0, s0
	v_readfirstlane_b32 s0, v163
	ds_read_b128 v[134:137], v151
	ds_read_b128 v[138:141], v151 offset:1024
	ds_read_b128 v[152:155], v151 offset:2048
	ds_read_b128 v[156:159], v151 offset:3072
	ds_read_b128 v[164:167], v0
	ds_read_b128 v[168:171], v0 offset:1024
	ds_read_b128 v[172:175], v0 offset:2048
	ds_read_b128 v[176:179], v0 offset:3072
	ds_read_b128 v[180:183], v0 offset:4096
	ds_read_b128 v[184:187], v0 offset:5120
	ds_read_b128 v[188:191], v0 offset:6144
	ds_read_b128 v[192:195], v0 offset:7168
	global_load_lds_dwordx4 v[132:133], off
	v_lshl_add_u64 v[130:131], v[130:131], 0, s[10:11]
	s_mov_b32 m0, s0
	s_nop 0
	global_load_lds_dwordx4 v[130:131], off
	s_barrier
	s_waitcnt lgkmcnt(0)
	s_setprio 1
	s_waitcnt lgkmcnt(0)
	v_mfma_f32_16x16x32_bf16 v[126:129], v[134:137], v[164:167], v[126:129]
	v_mfma_f32_16x16x32_bf16 v[122:125], v[152:155], v[164:167], v[122:125]
	v_mfma_f32_16x16x32_bf16 v[114:117], v[152:155], v[172:175], v[114:117]
	v_mfma_f32_16x16x32_bf16 v[106:109], v[152:155], v[180:183], v[106:109]
	v_mfma_f32_16x16x32_bf16 v[98:101], v[152:155], v[188:191], v[98:101]
	v_mfma_f32_16x16x32_bf16 v[126:129], v[138:141], v[168:171], v[126:129]
	v_mfma_f32_16x16x32_bf16 v[122:125], v[156:159], v[168:171], v[122:125]
	v_mfma_f32_16x16x32_bf16 v[118:121], v[134:137], v[172:175], v[118:121]
	v_mfma_f32_16x16x32_bf16 v[114:117], v[156:159], v[176:179], v[114:117]
	v_mfma_f32_16x16x32_bf16 v[110:113], v[134:137], v[180:183], v[110:113]
	v_mfma_f32_16x16x32_bf16 v[106:109], v[156:159], v[184:187], v[106:109]
	v_mfma_f32_16x16x32_bf16 v[102:105], v[134:137], v[188:191], v[102:105]
	v_mfma_f32_16x16x32_bf16 v[98:101], v[156:159], v[192:195], v[98:101]
	v_mfma_f32_16x16x32_bf16 v[130:133], v[138:141], v[176:179], v[118:121]
	v_mfma_f32_16x16x32_bf16 v[160:163], v[138:141], v[184:187], v[110:113]
	v_mfma_f32_16x16x32_bf16 v[196:199], v[138:141], v[192:195], v[102:105]
	s_setprio 0
	s_barrier
	s_nop 0
	ds_read_b128 v[102:105], v151 offset:16384
	ds_read_b128 v[110:113], v151 offset:17408
	ds_read_b128 v[118:121], v151 offset:18432
	ds_read_b128 v[200:203], v151 offset:19456
	s_barrier
	s_waitcnt lgkmcnt(0)
	s_setprio 1
	s_waitcnt lgkmcnt(1)
	v_mfma_f32_16x16x32_bf16 v[90:93], v[118:121], v[164:167], v[90:93]
	v_mfma_f32_16x16x32_bf16 v[86:89], v[102:105], v[172:175], v[86:89]
	v_mfma_f32_16x16x32_bf16 v[82:85], v[118:121], v[172:175], v[82:85]
	v_mfma_f32_16x16x32_bf16 v[78:81], v[102:105], v[180:183], v[78:81]
	v_mfma_f32_16x16x32_bf16 v[70:73], v[102:105], v[188:191], v[70:73]
	v_mfma_f32_16x16x32_bf16 v[94:97], v[102:105], v[164:167], v[94:97]
	s_waitcnt lgkmcnt(0)
	v_mfma_f32_16x16x32_bf16 v[90:93], v[200:203], v[168:171], v[90:93]
	v_mfma_f32_16x16x32_bf16 v[86:89], v[110:113], v[176:179], v[86:89]
	v_mfma_f32_16x16x32_bf16 v[82:85], v[200:203], v[176:179], v[82:85]
	v_mfma_f32_16x16x32_bf16 v[78:81], v[110:113], v[184:187], v[78:81]
	v_mfma_f32_16x16x32_bf16 v[74:77], v[118:121], v[180:183], v[74:77]
	v_mfma_f32_16x16x32_bf16 v[70:73], v[110:113], v[192:195], v[70:73]
	v_mfma_f32_16x16x32_bf16 v[66:69], v[118:121], v[188:191], v[66:69]
	v_mfma_f32_16x16x32_bf16 v[222:225], v[110:113], v[168:171], v[94:97]
	v_mfma_f32_16x16x32_bf16 v[164:167], v[200:203], v[184:187], v[74:77]
	v_mfma_f32_16x16x32_bf16 v[168:171], v[200:203], v[192:195], v[66:69]
	s_setprio 0
	s_barrier
	s_nop 2
	ds_read_b128 v[66:69], v0 offset:16384
	ds_read_b128 v[74:77], v0 offset:17408
	ds_read_b128 v[94:97], v0 offset:18432
	ds_read_b128 v[172:175], v0 offset:19456
	ds_read_b128 v[176:179], v0 offset:20480
	ds_read_b128 v[180:183], v0 offset:21504
	ds_read_b128 v[184:187], v0 offset:22528
	ds_read_b128 v[188:191], v0 offset:23552
	s_waitcnt vmcnt(4)
	s_barrier
	s_waitcnt lgkmcnt(0)
	s_setprio 1
	s_waitcnt lgkmcnt(5)
	v_mfma_f32_16x16x32_bf16 v[54:57], v[134:137], v[94:97], v[54:57]
	v_mfma_f32_16x16x32_bf16 v[50:53], v[152:155], v[94:97], v[50:53]
	v_mfma_f32_16x16x32_bf16 v[62:65], v[134:137], v[66:69], v[62:65]
	v_mfma_f32_16x16x32_bf16 v[58:61], v[152:155], v[66:69], v[58:61]
	s_waitcnt lgkmcnt(4)
	v_mfma_f32_16x16x32_bf16 v[54:57], v[138:141], v[172:175], v[54:57]
	v_mfma_f32_16x16x32_bf16 v[50:53], v[156:159], v[172:175], v[50:53]
	s_waitcnt lgkmcnt(3)
	v_mfma_f32_16x16x32_bf16 v[46:49], v[134:137], v[176:179], v[46:49]
	v_mfma_f32_16x16x32_bf16 v[42:45], v[152:155], v[176:179], v[42:45]
	s_waitcnt lgkmcnt(1)
	v_mfma_f32_16x16x32_bf16 v[38:41], v[134:137], v[184:187], v[38:41]
	v_mfma_f32_16x16x32_bf16 v[34:37], v[152:155], v[184:187], v[34:37]
	v_mfma_f32_16x16x32_bf16 v[192:195], v[138:141], v[74:77], v[62:65]
	v_mfma_f32_16x16x32_bf16 v[232:235], v[156:159], v[74:77], v[58:61]
	v_mfma_f32_16x16x32_bf16 v[236:239], v[138:141], v[180:183], v[46:49]
	v_mfma_f32_16x16x32_bf16 v[240:243], v[156:159], v[180:183], v[42:45]
	s_waitcnt lgkmcnt(0)
	v_mfma_f32_16x16x32_bf16 v[134:137], v[138:141], v[188:191], v[38:41]
	v_mfma_f32_16x16x32_bf16 v[138:141], v[156:159], v[188:191], v[34:37]
	s_setprio 0
	s_setprio 1
	v_mfma_f32_16x16x32_bf16 v[30:33], v[102:105], v[66:69], v[30:33]
	v_mfma_f32_16x16x32_bf16 v[26:29], v[118:121], v[66:69], v[26:29]
	v_mfma_f32_16x16x32_bf16 v[14:17], v[102:105], v[176:179], v[14:17]
	v_mfma_f32_16x16x32_bf16 v[10:13], v[118:121], v[176:179], v[10:13]
	v_mfma_f32_16x16x32_bf16 v[30:33], v[110:113], v[74:77], v[30:33]
	v_mfma_f32_16x16x32_bf16 v[26:29], v[200:203], v[74:77], v[26:29]
	v_mfma_f32_16x16x32_bf16 v[22:25], v[102:105], v[94:97], v[22:25]
	v_mfma_f32_16x16x32_bf16 v[18:21], v[118:121], v[94:97], v[18:21]
	v_mfma_f32_16x16x32_bf16 v[14:17], v[110:113], v[180:183], v[14:17]
	v_mfma_f32_16x16x32_bf16 v[10:13], v[200:203], v[180:183], v[10:13]
	v_mfma_f32_16x16x32_bf16 v[6:9], v[102:105], v[184:187], v[6:9]
	v_mfma_f32_16x16x32_bf16 v[2:5], v[118:121], v[184:187], v[2:5]
	v_mfma_f32_16x16x32_bf16 v[152:155], v[110:113], v[172:175], v[22:25]
	v_mfma_f32_16x16x32_bf16 v[156:159], v[200:203], v[172:175], v[18:21]
	v_mfma_f32_16x16x32_bf16 v[172:175], v[110:113], v[188:191], v[6:9]
	v_mfma_f32_16x16x32_bf16 v[176:179], v[200:203], v[188:191], v[2:5]
	s_setprio 0
	s_barrier
	s_nop 1
	ds_read_b128 v[2:5], v151 offset:32768
	ds_read_b128 v[6:9], v151 offset:33792
	ds_read_b128 v[180:183], v151 offset:34816
	ds_read_b128 v[184:187], v151 offset:35840
	ds_read_b128 v[18:21], v0 offset:32768
	ds_read_b128 v[22:25], v0 offset:33792
	ds_read_b128 v[38:41], v0 offset:34816
	ds_read_b128 v[46:49], v0 offset:35840
	ds_read_b128 v[58:61], v0 offset:36864
	ds_read_b128 v[66:69], v0 offset:37888
	ds_read_b128 v[188:191], v0 offset:38912
	ds_read_b128 v[200:203], v0 offset:39936
	s_waitcnt vmcnt(2)
	s_barrier
	s_waitcnt lgkmcnt(0)
	s_setprio 1
	s_waitcnt lgkmcnt(7)
	v_mfma_f32_16x16x32_bf16 v[34:37], v[2:5], v[18:21], v[126:129]
	s_waitcnt lgkmcnt(6)
	v_mfma_f32_16x16x32_bf16 v[118:121], v[6:9], v[22:25], v[34:37]
	v_mfma_f32_16x16x32_bf16 v[34:37], v[180:183], v[18:21], v[122:125]
	v_mfma_f32_16x16x32_bf16 v[110:113], v[184:187], v[22:25], v[34:37]
	s_waitcnt lgkmcnt(5)
	v_mfma_f32_16x16x32_bf16 v[34:37], v[2:5], v[38:41], v[130:133]
	s_waitcnt lgkmcnt(4)
	v_mfma_f32_16x16x32_bf16 v[102:105], v[6:9], v[46:49], v[34:37]
	v_mfma_f32_16x16x32_bf16 v[34:37], v[180:183], v[38:41], v[114:117]
	v_mfma_f32_16x16x32_bf16 v[94:97], v[184:187], v[46:49], v[34:37]
	s_waitcnt lgkmcnt(3)
	v_mfma_f32_16x16x32_bf16 v[34:37], v[2:5], v[58:61], v[160:163]
	s_waitcnt lgkmcnt(2)
	v_mfma_f32_16x16x32_bf16 v[74:77], v[6:9], v[66:69], v[34:37]
	v_mfma_f32_16x16x32_bf16 v[34:37], v[180:183], v[58:61], v[106:109]
	v_mfma_f32_16x16x32_bf16 v[62:65], v[184:187], v[66:69], v[34:37]
	s_waitcnt lgkmcnt(1)
	v_mfma_f32_16x16x32_bf16 v[34:37], v[2:5], v[188:191], v[196:199]
	s_waitcnt lgkmcnt(0)
	v_mfma_f32_16x16x32_bf16 v[42:45], v[6:9], v[200:203], v[34:37]
	v_mfma_f32_16x16x32_bf16 v[34:37], v[180:183], v[188:191], v[98:101]
	v_mfma_f32_16x16x32_bf16 v[34:37], v[184:187], v[200:203], v[34:37]
	s_setprio 0
	s_barrier
	ds_read_b128 v[130:133], v151 offset:49152
	ds_read_b128 v[160:163], v151 offset:50176
	ds_read_b128 v[196:199], v151 offset:51200
	ds_read_b128 v[148:151], v151 offset:52224
	s_waitcnt vmcnt(0)
	s_barrier
	s_waitcnt lgkmcnt(0)
	s_setprio 1
	s_waitcnt lgkmcnt(3)
	v_mfma_f32_16x16x32_bf16 v[98:101], v[130:133], v[18:21], v[222:225]
	s_waitcnt lgkmcnt(1)
	v_mfma_f32_16x16x32_bf16 v[18:21], v[196:199], v[18:21], v[90:93]
	s_waitcnt lgkmcnt(0)
	v_mfma_f32_16x16x32_bf16 v[122:125], v[148:151], v[22:25], v[18:21]
	v_mfma_f32_16x16x32_bf16 v[18:21], v[130:133], v[38:41], v[86:89]
	v_mfma_f32_16x16x32_bf16 v[114:117], v[160:163], v[46:49], v[18:21]
	v_mfma_f32_16x16x32_bf16 v[18:21], v[196:199], v[38:41], v[82:85]
	v_mfma_f32_16x16x32_bf16 v[106:109], v[148:151], v[46:49], v[18:21]
	v_mfma_f32_16x16x32_bf16 v[18:21], v[130:133], v[58:61], v[78:81]
	v_mfma_f32_16x16x32_bf16 v[126:129], v[160:163], v[22:25], v[98:101]
	v_mfma_f32_16x16x32_bf16 v[98:101], v[160:163], v[66:69], v[18:21]
	v_mfma_f32_16x16x32_bf16 v[18:21], v[196:199], v[58:61], v[164:167]
	v_mfma_f32_16x16x32_bf16 v[90:93], v[148:151], v[66:69], v[18:21]
	v_mfma_f32_16x16x32_bf16 v[18:21], v[130:133], v[188:191], v[70:73]
	v_mfma_f32_16x16x32_bf16 v[66:69], v[160:163], v[200:203], v[18:21]
	v_mfma_f32_16x16x32_bf16 v[18:21], v[196:199], v[188:191], v[168:171]
	v_mfma_f32_16x16x32_bf16 v[58:61], v[148:151], v[200:203], v[18:21]
	s_setprio 0
	s_barrier
	ds_read_b128 v[82:85], v0 offset:49152
	ds_read_b128 v[164:167], v0 offset:50176
	ds_read_b128 v[168:171], v0 offset:51200
	ds_read_b128 v[188:191], v0 offset:52224
	ds_read_b128 v[200:203], v0 offset:53248
	ds_read_b128 v[222:225], v0 offset:54272
	ds_read_b128 v[244:247], v0 offset:55296
	ds_read_b128 v[248:251], v0 offset:56320
	s_barrier
	s_waitcnt lgkmcnt(0)
	s_setprio 1
	s_waitcnt lgkmcnt(7)
	v_mfma_f32_16x16x32_bf16 v[18:21], v[2:5], v[82:85], v[192:195]
	s_waitcnt lgkmcnt(6)
	v_mfma_f32_16x16x32_bf16 v[78:81], v[6:9], v[164:167], v[18:21]
	v_mfma_f32_16x16x32_bf16 v[18:21], v[180:183], v[82:85], v[232:235]
	v_mfma_f32_16x16x32_bf16 v[70:73], v[184:187], v[164:167], v[18:21]
	s_waitcnt lgkmcnt(5)
	v_mfma_f32_16x16x32_bf16 v[18:21], v[2:5], v[168:171], v[54:57]
	s_waitcnt lgkmcnt(4)
	v_mfma_f32_16x16x32_bf16 v[46:49], v[6:9], v[188:191], v[18:21]
	v_mfma_f32_16x16x32_bf16 v[18:21], v[180:183], v[168:171], v[50:53]
	v_mfma_f32_16x16x32_bf16 v[38:41], v[184:187], v[188:191], v[18:21]
	s_waitcnt lgkmcnt(3)
	v_mfma_f32_16x16x32_bf16 v[18:21], v[2:5], v[200:203], v[236:239]
	s_waitcnt lgkmcnt(1)
	v_mfma_f32_16x16x32_bf16 v[2:5], v[2:5], v[244:247], v[134:137]
	v_mfma_f32_16x16x32_bf16 v[22:25], v[6:9], v[222:225], v[18:21]
	v_mfma_f32_16x16x32_bf16 v[18:21], v[180:183], v[200:203], v[240:243]
	s_waitcnt lgkmcnt(0)
	v_mfma_f32_16x16x32_bf16 v[6:9], v[6:9], v[248:251], v[2:5]
	v_mfma_f32_16x16x32_bf16 v[2:5], v[180:183], v[244:247], v[138:141]
	v_mfma_f32_16x16x32_bf16 v[18:21], v[184:187], v[222:225], v[18:21]
	v_mfma_f32_16x16x32_bf16 v[2:5], v[184:187], v[248:251], v[2:5]
	s_setprio 0
	s_setprio 1
	v_mfma_f32_16x16x32_bf16 v[26:29], v[196:199], v[82:85], v[26:29]
	v_mfma_f32_16x16x32_bf16 v[30:33], v[130:133], v[82:85], v[30:33]
	v_mfma_f32_16x16x32_bf16 v[82:85], v[148:151], v[164:167], v[26:29]
	v_mfma_f32_16x16x32_bf16 v[26:29], v[130:133], v[168:171], v[152:155]
	v_mfma_f32_16x16x32_bf16 v[54:57], v[160:163], v[188:191], v[26:29]
	v_mfma_f32_16x16x32_bf16 v[26:29], v[196:199], v[168:171], v[156:159]
	v_mfma_f32_16x16x32_bf16 v[10:13], v[196:199], v[200:203], v[10:13]
	v_mfma_f32_16x16x32_bf16 v[50:53], v[148:151], v[188:191], v[26:29]
	v_mfma_f32_16x16x32_bf16 v[14:17], v[130:133], v[200:203], v[14:17]
	v_mfma_f32_16x16x32_bf16 v[26:29], v[148:151], v[222:225], v[10:13]
	v_mfma_f32_16x16x32_bf16 v[10:13], v[130:133], v[244:247], v[172:175]
	v_mfma_f32_16x16x32_bf16 v[86:89], v[160:163], v[164:167], v[30:33]
	v_mfma_f32_16x16x32_bf16 v[30:33], v[160:163], v[222:225], v[14:17]
	v_mfma_f32_16x16x32_bf16 v[14:17], v[160:163], v[248:251], v[10:13]
	v_mfma_f32_16x16x32_bf16 v[10:13], v[196:199], v[244:247], v[176:179]
	v_mfma_f32_16x16x32_bf16 v[10:13], v[148:151], v[248:251], v[10:13]
	s_setprio 0
	s_movk_i32 s0, 0x100
	v_cmp_gt_u32_e32 vcc, s0, v142
	s_barrier
	s_and_saveexec_b64 s[0:1], vcc
	s_cbranch_execz .LBB0_81
	s_barrier
	s_branch .LBB0_81

.LBB0_108:
	v_add_u32_e32 v102, 0xc000, v87
	v_lshl_add_u64 v[152:153], v[74:75], 0, s[10:11]
	v_readfirstlane_b32 s1, v102
	v_lshl_add_u64 v[154:155], v[152:153], 0, s[60:61]
	s_mov_b32 m0, s1
	v_add_u32_e32 v103, 0xe000, v87
	global_load_lds_dwordx4 v[154:155], off
	v_lshl_add_u64 v[154:155], v[76:77], 0, s[10:11]
	v_readfirstlane_b32 s1, v103
	v_lshl_add_u64 v[156:157], v[154:155], 0, s[60:61]
	s_mov_b32 m0, s1
	s_nop 0
	global_load_lds_dwordx4 v[156:157], off
	ds_read_b128 v[104:107], v99
	ds_read_b128 v[108:111], v99 offset:1024
	ds_read_b128 v[112:115], v99 offset:2048
	ds_read_b128 v[116:119], v99 offset:3072
	ds_read_b128 v[120:123], v0
	ds_read_b128 v[124:127], v0 offset:1024
	ds_read_b128 v[128:131], v0 offset:2048
	ds_read_b128 v[132:135], v0 offset:3072
	ds_read_b128 v[136:139], v0 offset:4096
	ds_read_b128 v[140:143], v0 offset:5120
	ds_read_b128 v[144:147], v0 offset:6144
	ds_read_b128 v[148:151], v0 offset:7168
	s_waitcnt lgkmcnt(8)
	s_barrier
	s_waitcnt lgkmcnt(0)
	s_setprio 1
	s_waitcnt lgkmcnt(0)
	v_mfma_f32_16x16x32_bf16 v[62:65], v[104:107], v[120:123], v[62:65]
	v_mfma_f32_16x16x32_bf16 v[58:61], v[112:115], v[120:123], v[58:61]
	v_mfma_f32_16x16x32_bf16 v[54:57], v[104:107], v[128:131], v[54:57]
	v_mfma_f32_16x16x32_bf16 v[50:53], v[112:115], v[128:131], v[50:53]
	v_mfma_f32_16x16x32_bf16 v[46:49], v[104:107], v[136:139], v[46:49]
	v_mfma_f32_16x16x32_bf16 v[42:45], v[112:115], v[136:139], v[42:45]
	v_mfma_f32_16x16x32_bf16 v[38:41], v[104:107], v[144:147], v[38:41]
	v_mfma_f32_16x16x32_bf16 v[34:37], v[112:115], v[144:147], v[34:37]
	v_mfma_f32_16x16x32_bf16 v[62:65], v[108:111], v[124:127], v[62:65]
	v_mfma_f32_16x16x32_bf16 v[58:61], v[116:119], v[124:127], v[58:61]
	v_mfma_f32_16x16x32_bf16 v[54:57], v[108:111], v[132:135], v[54:57]
	v_mfma_f32_16x16x32_bf16 v[50:53], v[116:119], v[132:135], v[50:53]
	v_mfma_f32_16x16x32_bf16 v[46:49], v[108:111], v[140:143], v[46:49]
	v_mfma_f32_16x16x32_bf16 v[42:45], v[116:119], v[140:143], v[42:45]
	v_mfma_f32_16x16x32_bf16 v[38:41], v[108:111], v[148:151], v[38:41]
	v_mfma_f32_16x16x32_bf16 v[34:37], v[116:119], v[148:151], v[34:37]
	s_setprio 0
	s_barrier
	v_lshl_add_u64 v[156:157], v[70:71], 0, s[10:11]
	v_readfirstlane_b32 s1, v89
	v_lshl_add_u64 v[120:121], v[156:157], 0, s[74:75]
	s_mov_b32 m0, s1
	v_lshl_add_u64 v[158:159], v[72:73], 0, s[10:11]
	v_readfirstlane_b32 s1, v90
	global_load_lds_dwordx4 v[120:121], off
	v_lshl_add_u64 v[120:121], v[158:159], 0, s[74:75]
	s_mov_b32 m0, s1
	v_readfirstlane_b32 s1, v87
	global_load_lds_dwordx4 v[120:121], off
	v_lshl_add_u64 v[160:161], v[152:153], 0, s[74:75]
	s_mov_b32 m0, s1
	v_readfirstlane_b32 s1, v88
	s_barrier
	s_waitcnt lgkmcnt(0)
	s_barrier
	global_load_lds_dwordx4 v[160:161], off
	v_lshl_add_u64 v[160:161], v[154:155], 0, s[74:75]
	s_mov_b32 m0, s1
	s_nop 0
	global_load_lds_dwordx4 v[160:161], off
	ds_read_b128 v[120:123], v0 offset:16384
	ds_read_b128 v[124:127], v0 offset:17408
	ds_read_b128 v[128:131], v0 offset:18432
	ds_read_b128 v[132:135], v0 offset:19456
	ds_read_b128 v[136:139], v0 offset:20480
	ds_read_b128 v[140:143], v0 offset:21504
	ds_read_b128 v[144:147], v0 offset:22528
	ds_read_b128 v[148:151], v0 offset:23552
	s_barrier
	s_waitcnt lgkmcnt(0)
	s_setprio 1
	s_waitcnt lgkmcnt(0)
	v_mfma_f32_16x16x32_bf16 v[2:5], v[104:107], v[120:123], v[2:5]
	v_mfma_f32_16x16x32_bf16 v[6:9], v[112:115], v[120:123], v[6:9]
	v_mfma_f32_16x16x32_bf16 v[10:13], v[104:107], v[128:131], v[10:13]
	v_mfma_f32_16x16x32_bf16 v[14:17], v[112:115], v[128:131], v[14:17]
	v_mfma_f32_16x16x32_bf16 v[18:21], v[104:107], v[136:139], v[18:21]
	v_mfma_f32_16x16x32_bf16 v[22:25], v[112:115], v[136:139], v[22:25]
	v_mfma_f32_16x16x32_bf16 v[26:29], v[104:107], v[144:147], v[26:29]
	v_mfma_f32_16x16x32_bf16 v[30:33], v[112:115], v[144:147], v[30:33]
	v_mfma_f32_16x16x32_bf16 v[2:5], v[108:111], v[124:127], v[2:5]
	v_mfma_f32_16x16x32_bf16 v[6:9], v[116:119], v[124:127], v[6:9]
	v_mfma_f32_16x16x32_bf16 v[10:13], v[108:111], v[132:135], v[10:13]
	v_mfma_f32_16x16x32_bf16 v[14:17], v[116:119], v[132:135], v[14:17]
	v_mfma_f32_16x16x32_bf16 v[18:21], v[108:111], v[140:143], v[18:21]
	v_mfma_f32_16x16x32_bf16 v[22:25], v[116:119], v[140:143], v[22:25]
	v_mfma_f32_16x16x32_bf16 v[26:29], v[108:111], v[148:151], v[26:29]
	v_mfma_f32_16x16x32_bf16 v[30:33], v[116:119], v[148:151], v[30:33]
	s_setprio 0
	s_barrier
	v_lshl_add_u64 v[160:161], v[78:79], 0, s[10:11]
	v_readfirstlane_b32 s1, v91
	v_lshl_add_u64 v[104:105], v[160:161], 0, s[74:75]
	s_mov_b32 m0, s1
	v_lshl_add_u64 v[162:163], v[80:81], 0, s[10:11]
	v_readfirstlane_b32 s1, v92
	global_load_lds_dwordx4 v[104:105], off
	v_lshl_add_u64 v[104:105], v[162:163], 0, s[74:75]
	s_mov_b32 m0, s1
	s_nop 0
	global_load_lds_dwordx4 v[104:105], off
	s_waitcnt vmcnt(6)
	s_barrier
	s_barrier
	v_readfirstlane_b32 s1, v93
	v_lshl_add_u64 v[164:165], v[152:153], 0, s[18:19]
	s_mov_b32 m0, s1
	v_readfirstlane_b32 s1, v94
	global_load_lds_dwordx4 v[164:165], off
	v_lshl_add_u64 v[164:165], v[154:155], 0, s[18:19]
	s_mov_b32 m0, s1
	s_nop 0
	global_load_lds_dwordx4 v[164:165], off
	ds_read_b128 v[104:107], v99 offset:32768
	ds_read_b128 v[108:111], v99 offset:33792
	ds_read_b128 v[112:115], v99 offset:34816
	ds_read_b128 v[116:119], v99 offset:35840
	ds_read_b128 v[120:123], v0 offset:32768
	ds_read_b128 v[124:127], v0 offset:33792
	ds_read_b128 v[128:131], v0 offset:34816
	ds_read_b128 v[132:135], v0 offset:35840
	ds_read_b128 v[136:139], v0 offset:36864
	ds_read_b128 v[140:143], v0 offset:37888
	ds_read_b128 v[144:147], v0 offset:38912
	ds_read_b128 v[148:151], v0 offset:39936
	s_waitcnt lgkmcnt(8)
	s_barrier
	s_waitcnt lgkmcnt(0)
	s_setprio 1
	s_waitcnt lgkmcnt(0)
	v_mfma_f32_16x16x32_bf16 v[62:65], v[104:107], v[120:123], v[62:65]
	v_mfma_f32_16x16x32_bf16 v[58:61], v[112:115], v[120:123], v[58:61]
	v_mfma_f32_16x16x32_bf16 v[54:57], v[104:107], v[128:131], v[54:57]
	v_mfma_f32_16x16x32_bf16 v[50:53], v[112:115], v[128:131], v[50:53]
	v_mfma_f32_16x16x32_bf16 v[46:49], v[104:107], v[136:139], v[46:49]
	v_mfma_f32_16x16x32_bf16 v[42:45], v[112:115], v[136:139], v[42:45]
	v_mfma_f32_16x16x32_bf16 v[38:41], v[104:107], v[144:147], v[38:41]
	v_mfma_f32_16x16x32_bf16 v[34:37], v[112:115], v[144:147], v[34:37]
	v_mfma_f32_16x16x32_bf16 v[62:65], v[108:111], v[124:127], v[62:65]
	v_mfma_f32_16x16x32_bf16 v[58:61], v[116:119], v[124:127], v[58:61]
	v_mfma_f32_16x16x32_bf16 v[54:57], v[108:111], v[132:135], v[54:57]
	v_mfma_f32_16x16x32_bf16 v[50:53], v[116:119], v[132:135], v[50:53]
	v_mfma_f32_16x16x32_bf16 v[46:49], v[108:111], v[140:143], v[46:49]
	v_mfma_f32_16x16x32_bf16 v[42:45], v[116:119], v[140:143], v[42:45]
	v_mfma_f32_16x16x32_bf16 v[38:41], v[108:111], v[148:151], v[38:41]
	v_mfma_f32_16x16x32_bf16 v[34:37], v[116:119], v[148:151], v[34:37]
	s_setprio 0
	s_barrier
	v_readfirstlane_b32 s1, v95
	v_lshl_add_u64 v[120:121], v[156:157], 0, s[28:29]
	s_mov_b32 m0, s1
	v_readfirstlane_b32 s1, v96
	global_load_lds_dwordx4 v[120:121], off
	v_lshl_add_u64 v[120:121], v[158:159], 0, s[28:29]
	s_mov_b32 m0, s1
	v_readfirstlane_b32 s1, v97
	global_load_lds_dwordx4 v[120:121], off
	v_lshl_add_u64 v[152:153], v[152:153], 0, s[28:29]
	s_mov_b32 m0, s1
	v_readfirstlane_b32 s1, v98
	s_barrier
	s_waitcnt lgkmcnt(0)
	s_barrier
	global_load_lds_dwordx4 v[152:153], off
	v_lshl_add_u64 v[152:153], v[154:155], 0, s[28:29]
	s_mov_b32 m0, s1
	s_nop 0
	global_load_lds_dwordx4 v[152:153], off
	ds_read_b128 v[120:123], v0 offset:49152
	ds_read_b128 v[124:127], v0 offset:50176
	ds_read_b128 v[128:131], v0 offset:51200
	ds_read_b128 v[132:135], v0 offset:52224
	ds_read_b128 v[136:139], v0 offset:53248
	ds_read_b128 v[140:143], v0 offset:54272
	ds_read_b128 v[144:147], v0 offset:55296
	ds_read_b128 v[148:151], v0 offset:56320
	s_barrier
	s_waitcnt lgkmcnt(0)
	s_setprio 1
	s_waitcnt lgkmcnt(0)
	v_mfma_f32_16x16x32_bf16 v[2:5], v[104:107], v[120:123], v[2:5]
	v_mfma_f32_16x16x32_bf16 v[6:9], v[112:115], v[120:123], v[6:9]
	v_mfma_f32_16x16x32_bf16 v[10:13], v[104:107], v[128:131], v[10:13]
	v_mfma_f32_16x16x32_bf16 v[14:17], v[112:115], v[128:131], v[14:17]
	v_mfma_f32_16x16x32_bf16 v[18:21], v[104:107], v[136:139], v[18:21]
	v_mfma_f32_16x16x32_bf16 v[22:25], v[112:115], v[136:139], v[22:25]
	v_mfma_f32_16x16x32_bf16 v[26:29], v[104:107], v[144:147], v[26:29]
	v_mfma_f32_16x16x32_bf16 v[30:33], v[112:115], v[144:147], v[30:33]
	v_mfma_f32_16x16x32_bf16 v[2:5], v[108:111], v[124:127], v[2:5]
	v_mfma_f32_16x16x32_bf16 v[6:9], v[116:119], v[124:127], v[6:9]
	v_mfma_f32_16x16x32_bf16 v[10:13], v[108:111], v[132:135], v[10:13]
	v_mfma_f32_16x16x32_bf16 v[14:17], v[116:119], v[132:135], v[14:17]
	v_mfma_f32_16x16x32_bf16 v[18:21], v[108:111], v[140:143], v[18:21]
	v_mfma_f32_16x16x32_bf16 v[22:25], v[116:119], v[140:143], v[22:25]
	v_mfma_f32_16x16x32_bf16 v[26:29], v[108:111], v[148:151], v[26:29]
	v_mfma_f32_16x16x32_bf16 v[30:33], v[116:119], v[148:151], v[30:33]
	s_setprio 0
	s_barrier
	v_readfirstlane_b32 s1, v100
	v_lshl_add_u64 v[104:105], v[160:161], 0, s[28:29]
	s_mov_b32 m0, s1
	v_readfirstlane_b32 s1, v101
	global_load_lds_dwordx4 v[104:105], off
	v_lshl_add_u64 v[104:105], v[162:163], 0, s[28:29]
	s_mov_b32 m0, s1
	s_add_i32 s0, s0, 2
	global_load_lds_dwordx4 v[104:105], off
	s_waitcnt vmcnt(6)
	s_add_u32 s10, s10, 0x100
	s_addc_u32 s11, s11, 0
	s_cmp_lt_u32 s0, 28
	s_barrier
	s_barrier
	s_cbranch_scc1 .LBB0_108
	s_mov_b64 s[10:11], 0xf80
	v_readfirstlane_b32 s0, v102
	v_lshl_add_u64 v[68:69], v[68:69], 0, s[10:11]
	s_mov_b32 m0, s0
	v_readfirstlane_b32 s0, v103
	ds_read_b128 v[70:73], v99
	ds_read_b128 v[74:77], v99 offset:1024
	ds_read_b128 v[78:81], v99 offset:2048
	ds_read_b128 v[88:91], v99 offset:3072
	ds_read_b128 v[92:95], v0
	ds_read_b128 v[104:107], v0 offset:1024
	ds_read_b128 v[108:111], v0 offset:2048
	ds_read_b128 v[112:115], v0 offset:3072
	ds_read_b128 v[116:119], v0 offset:4096
	ds_read_b128 v[120:123], v0 offset:5120
	ds_read_b128 v[124:127], v0 offset:6144
	ds_read_b128 v[128:131], v0 offset:7168
	global_load_lds_dwordx4 v[68:69], off
	v_lshl_add_u64 v[66:67], v[66:67], 0, s[10:11]
	s_mov_b32 m0, s0
	s_nop 0
	global_load_lds_dwordx4 v[66:67], off
	s_barrier
	s_waitcnt lgkmcnt(0)
	s_setprio 1
	s_waitcnt lgkmcnt(0)
	v_mfma_f32_16x16x32_bf16 v[62:65], v[70:73], v[92:95], v[62:65]
	v_mfma_f32_16x16x32_bf16 v[58:61], v[78:81], v[92:95], v[58:61]
	v_mfma_f32_16x16x32_bf16 v[54:57], v[70:73], v[108:111], v[54:57]
	v_mfma_f32_16x16x32_bf16 v[50:53], v[78:81], v[108:111], v[50:53]
	v_mfma_f32_16x16x32_bf16 v[46:49], v[70:73], v[116:119], v[46:49]
	v_mfma_f32_16x16x32_bf16 v[42:45], v[78:81], v[116:119], v[42:45]
	v_mfma_f32_16x16x32_bf16 v[38:41], v[70:73], v[124:127], v[38:41]
	v_mfma_f32_16x16x32_bf16 v[34:37], v[78:81], v[124:127], v[34:37]
	v_mfma_f32_16x16x32_bf16 v[62:65], v[74:77], v[104:107], v[62:65]
	v_mfma_f32_16x16x32_bf16 v[58:61], v[88:91], v[104:107], v[58:61]
	v_mfma_f32_16x16x32_bf16 v[54:57], v[74:77], v[112:115], v[54:57]
	v_mfma_f32_16x16x32_bf16 v[50:53], v[88:91], v[112:115], v[50:53]
	v_mfma_f32_16x16x32_bf16 v[46:49], v[74:77], v[120:123], v[46:49]
	v_mfma_f32_16x16x32_bf16 v[42:45], v[88:91], v[120:123], v[42:45]
	v_mfma_f32_16x16x32_bf16 v[38:41], v[74:77], v[128:131], v[38:41]
	v_mfma_f32_16x16x32_bf16 v[34:37], v[88:91], v[128:131], v[34:37]
	s_setprio 0
	s_barrier
	s_barrier
	s_waitcnt lgkmcnt(0)
	s_barrier
	ds_read_b128 v[66:69], v0 offset:16384
	ds_read_b128 v[92:95], v0 offset:17408
	ds_read_b128 v[100:103], v0 offset:18432
	ds_read_b128 v[104:107], v0 offset:19456
	ds_read_b128 v[108:111], v0 offset:20480
	ds_read_b128 v[112:115], v0 offset:21504
	ds_read_b128 v[116:119], v0 offset:22528
	ds_read_b128 v[120:123], v0 offset:23552
	s_waitcnt vmcnt(4)
	s_barrier
	s_waitcnt lgkmcnt(0)
	s_setprio 1
	s_waitcnt lgkmcnt(3)
	v_mfma_f32_16x16x32_bf16 v[18:21], v[70:73], v[108:111], v[18:21]
	v_mfma_f32_16x16x32_bf16 v[2:5], v[70:73], v[66:69], v[2:5]
	v_mfma_f32_16x16x32_bf16 v[6:9], v[78:81], v[66:69], v[6:9]
	s_waitcnt lgkmcnt(2)
	v_mfma_f32_16x16x32_bf16 v[66:69], v[74:77], v[112:115], v[18:21]
	v_mfma_f32_16x16x32_bf16 v[18:21], v[78:81], v[108:111], v[22:25]
	v_mfma_f32_16x16x32_bf16 v[2:5], v[74:77], v[92:95], v[2:5]
	v_mfma_f32_16x16x32_bf16 v[6:9], v[88:91], v[92:95], v[6:9]
	v_mfma_f32_16x16x32_bf16 v[10:13], v[70:73], v[100:103], v[10:13]
	v_mfma_f32_16x16x32_bf16 v[14:17], v[78:81], v[100:103], v[14:17]
	v_mfma_f32_16x16x32_bf16 v[92:95], v[88:91], v[112:115], v[18:21]
	s_waitcnt lgkmcnt(1)
	v_mfma_f32_16x16x32_bf16 v[18:21], v[70:73], v[116:119], v[26:29]
	v_mfma_f32_16x16x32_bf16 v[10:13], v[74:77], v[104:107], v[10:13]
	v_mfma_f32_16x16x32_bf16 v[14:17], v[88:91], v[104:107], v[14:17]
	s_waitcnt lgkmcnt(0)
	v_mfma_f32_16x16x32_bf16 v[70:73], v[74:77], v[120:123], v[18:21]
	v_mfma_f32_16x16x32_bf16 v[18:21], v[78:81], v[116:119], v[30:33]
	v_mfma_f32_16x16x32_bf16 v[74:77], v[88:91], v[120:123], v[18:21]
	s_setprio 0
	s_barrier
	ds_read_b128 v[78:81], v99 offset:32768
	ds_read_b128 v[88:91], v99 offset:33792
	ds_read_b128 v[100:103], v99 offset:34816
	ds_read_b128 v[96:99], v99 offset:35840
	s_nop 0
	ds_read_b128 v[18:21], v0 offset:32768
	ds_read_b128 v[22:25], v0 offset:33792
	ds_read_b128 v[26:29], v0 offset:34816
	ds_read_b128 v[30:33], v0 offset:35840
	ds_read_b128 v[104:107], v0 offset:36864
	ds_read_b128 v[108:111], v0 offset:37888
	ds_read_b128 v[112:115], v0 offset:38912
	ds_read_b128 v[116:119], v0 offset:39936
	s_waitcnt vmcnt(2)
	s_barrier
	s_waitcnt lgkmcnt(0)
	s_setprio 1
	s_waitcnt lgkmcnt(7)
	v_mfma_f32_16x16x32_bf16 v[62:65], v[78:81], v[18:21], v[62:65]
	v_mfma_f32_16x16x32_bf16 v[18:21], v[100:103], v[18:21], v[58:61]
	s_waitcnt lgkmcnt(6)
	v_mfma_f32_16x16x32_bf16 v[58:61], v[96:99], v[22:25], v[18:21]
	s_waitcnt lgkmcnt(5)
	v_mfma_f32_16x16x32_bf16 v[18:21], v[78:81], v[26:29], v[54:57]
	s_waitcnt lgkmcnt(4)
	v_mfma_f32_16x16x32_bf16 v[54:57], v[88:91], v[30:33], v[18:21]
	v_mfma_f32_16x16x32_bf16 v[18:21], v[100:103], v[26:29], v[50:53]
	v_mfma_f32_16x16x32_bf16 v[50:53], v[96:99], v[30:33], v[18:21]
	s_waitcnt lgkmcnt(3)
	v_mfma_f32_16x16x32_bf16 v[18:21], v[78:81], v[104:107], v[46:49]
	s_waitcnt lgkmcnt(2)
	v_mfma_f32_16x16x32_bf16 v[46:49], v[88:91], v[108:111], v[18:21]
	v_mfma_f32_16x16x32_bf16 v[18:21], v[100:103], v[104:107], v[42:45]
	v_mfma_f32_16x16x32_bf16 v[42:45], v[96:99], v[108:111], v[18:21]
	s_waitcnt lgkmcnt(1)
	v_mfma_f32_16x16x32_bf16 v[18:21], v[78:81], v[112:115], v[38:41]
	s_waitcnt lgkmcnt(0)
	v_mfma_f32_16x16x32_bf16 v[38:41], v[88:91], v[116:119], v[18:21]
	v_mfma_f32_16x16x32_bf16 v[18:21], v[100:103], v[112:115], v[34:37]
	v_mfma_f32_16x16x32_bf16 v[62:65], v[88:91], v[22:25], v[62:65]
	v_mfma_f32_16x16x32_bf16 v[34:37], v[96:99], v[116:119], v[18:21]
	s_setprio 0
	s_barrier
	s_waitcnt vmcnt(0)
	s_barrier
	s_waitcnt lgkmcnt(0)
	s_barrier
	s_nop 1
	ds_read_b128 v[18:21], v0 offset:49152
	ds_read_b128 v[22:25], v0 offset:50176
	ds_read_b128 v[104:107], v0 offset:51200
	ds_read_b128 v[108:111], v0 offset:52224
	ds_read_b128 v[112:115], v0 offset:53248
	ds_read_b128 v[116:119], v0 offset:54272
	ds_read_b128 v[120:123], v0 offset:55296
	ds_read_b128 v[124:127], v0 offset:56320
	s_barrier
	s_waitcnt lgkmcnt(0)
	s_setprio 1
	s_waitcnt lgkmcnt(7)
	v_mfma_f32_16x16x32_bf16 v[2:5], v[78:81], v[18:21], v[2:5]
	s_waitcnt lgkmcnt(6)
	v_mfma_f32_16x16x32_bf16 v[30:33], v[88:91], v[22:25], v[2:5]
	v_mfma_f32_16x16x32_bf16 v[2:5], v[100:103], v[18:21], v[6:9]
	v_mfma_f32_16x16x32_bf16 v[26:29], v[96:99], v[22:25], v[2:5]
	s_waitcnt lgkmcnt(5)
	v_mfma_f32_16x16x32_bf16 v[2:5], v[78:81], v[104:107], v[10:13]
	s_waitcnt lgkmcnt(4)
	v_mfma_f32_16x16x32_bf16 v[22:25], v[88:91], v[108:111], v[2:5]
	v_mfma_f32_16x16x32_bf16 v[2:5], v[100:103], v[104:107], v[14:17]
	v_mfma_f32_16x16x32_bf16 v[18:21], v[96:99], v[108:111], v[2:5]
	s_waitcnt lgkmcnt(3)
	v_mfma_f32_16x16x32_bf16 v[2:5], v[78:81], v[112:115], v[66:69]
	s_waitcnt lgkmcnt(2)
	v_mfma_f32_16x16x32_bf16 v[14:17], v[88:91], v[116:119], v[2:5]
	v_mfma_f32_16x16x32_bf16 v[2:5], v[100:103], v[112:115], v[92:95]
	v_mfma_f32_16x16x32_bf16 v[10:13], v[96:99], v[116:119], v[2:5]
	s_waitcnt lgkmcnt(1)
	v_mfma_f32_16x16x32_bf16 v[2:5], v[78:81], v[120:123], v[70:73]
	s_waitcnt lgkmcnt(0)
	v_mfma_f32_16x16x32_bf16 v[6:9], v[88:91], v[124:127], v[2:5]
	v_mfma_f32_16x16x32_bf16 v[2:5], v[100:103], v[120:123], v[74:77]
	v_mfma_f32_16x16x32_bf16 v[2:5], v[96:99], v[124:127], v[2:5]
	s_setprio 0
	s_movk_i32 s0, 0x100
	v_cmp_gt_u32_e32 vcc, s0, v82
	s_barrier
	s_and_saveexec_b64 s[0:1], vcc
	s_cbranch_execz .LBB0_111
	s_barrier

.LBB0_180:
	v_add_u32_e32 v162, 0xc000, v147
	v_lshl_add_u64 v[204:205], v[138:139], 0, s[12:13]
	v_readfirstlane_b32 s1, v162
	v_lshl_add_u64 v[210:211], v[204:205], 0, s[60:61]
	s_mov_b32 m0, s1
	v_add_u32_e32 v163, 0xe000, v147
	global_load_lds_dwordx4 v[210:211], off
	v_lshl_add_u64 v[210:211], v[140:141], 0, s[12:13]
	v_readfirstlane_b32 s1, v163
	v_lshl_add_u64 v[216:217], v[210:211], 0, s[60:61]
	s_mov_b32 m0, s1
	s_nop 0
	global_load_lds_dwordx4 v[216:217], off
	ds_read_b128 v[164:167], v151
	ds_read_b128 v[168:171], v151 offset:1024
	ds_read_b128 v[172:175], v151 offset:2048
	ds_read_b128 v[176:179], v151 offset:3072
	ds_read_b128 v[180:183], v0
	ds_read_b128 v[184:187], v0 offset:1024
	ds_read_b128 v[188:191], v0 offset:2048
	ds_read_b128 v[192:195], v0 offset:3072
	ds_read_b128 v[196:199], v0 offset:4096
	ds_read_b128 v[200:203], v0 offset:5120
	ds_read_b128 v[222:225], v0 offset:6144
	ds_read_b128 v[232:235], v0 offset:7168
	s_waitcnt lgkmcnt(8)
	s_barrier
	s_waitcnt lgkmcnt(0)
	s_setprio 1
	s_waitcnt lgkmcnt(0)
	v_mfma_f32_16x16x32_bf16 v[126:129], v[164:167], v[180:183], v[126:129]
	v_mfma_f32_16x16x32_bf16 v[122:125], v[172:175], v[180:183], v[122:125]
	v_mfma_f32_16x16x32_bf16 v[118:121], v[164:167], v[188:191], v[118:121]
	v_mfma_f32_16x16x32_bf16 v[114:117], v[172:175], v[188:191], v[114:117]
	v_mfma_f32_16x16x32_bf16 v[110:113], v[164:167], v[196:199], v[110:113]
	v_mfma_f32_16x16x32_bf16 v[106:109], v[172:175], v[196:199], v[106:109]
	v_mfma_f32_16x16x32_bf16 v[102:105], v[164:167], v[222:225], v[102:105]
	v_mfma_f32_16x16x32_bf16 v[98:101], v[172:175], v[222:225], v[98:101]
	v_mfma_f32_16x16x32_bf16 v[126:129], v[168:171], v[184:187], v[126:129]
	v_mfma_f32_16x16x32_bf16 v[122:125], v[176:179], v[184:187], v[122:125]
	v_mfma_f32_16x16x32_bf16 v[118:121], v[168:171], v[192:195], v[118:121]
	v_mfma_f32_16x16x32_bf16 v[114:117], v[176:179], v[192:195], v[114:117]
	v_mfma_f32_16x16x32_bf16 v[110:113], v[168:171], v[200:203], v[110:113]
	v_mfma_f32_16x16x32_bf16 v[106:109], v[176:179], v[200:203], v[106:109]
	v_mfma_f32_16x16x32_bf16 v[102:105], v[168:171], v[232:235], v[102:105]
	v_mfma_f32_16x16x32_bf16 v[98:101], v[176:179], v[232:235], v[98:101]
	s_setprio 0
	s_barrier
	v_lshl_add_u64 v[216:217], v[134:135], 0, s[12:13]
	v_readfirstlane_b32 s1, v149
	v_lshl_add_u64 v[218:219], v[216:217], 0, s[74:75]
	s_mov_b32 m0, s1
	global_load_lds_dwordx4 v[218:219], off
	v_lshl_add_u64 v[218:219], v[136:137], 0, s[12:13]
	v_readfirstlane_b32 s1, v150
	v_lshl_add_u64 v[228:229], v[218:219], 0, s[74:75]
	s_mov_b32 m0, s1
	s_nop 0
	global_load_lds_dwordx4 v[228:229], off
	ds_read_b128 v[236:239], v151 offset:16384
	ds_read_b128 v[240:243], v151 offset:17408
	ds_read_b128 v[244:247], v151 offset:18432
	ds_read_b128 v[248:251], v151 offset:19456
	s_barrier
	s_waitcnt lgkmcnt(0)
	s_setprio 1
	s_waitcnt lgkmcnt(0)
	v_mfma_f32_16x16x32_bf16 v[94:97], v[236:239], v[180:183], v[94:97]
	v_mfma_f32_16x16x32_bf16 v[90:93], v[244:247], v[180:183], v[90:93]
	v_mfma_f32_16x16x32_bf16 v[86:89], v[236:239], v[188:191], v[86:89]
	v_mfma_f32_16x16x32_bf16 v[82:85], v[244:247], v[188:191], v[82:85]
	v_mfma_f32_16x16x32_bf16 v[78:81], v[236:239], v[196:199], v[78:81]
	v_mfma_f32_16x16x32_bf16 v[74:77], v[244:247], v[196:199], v[74:77]
	v_mfma_f32_16x16x32_bf16 v[70:73], v[236:239], v[222:225], v[70:73]
	v_mfma_f32_16x16x32_bf16 v[66:69], v[244:247], v[222:225], v[66:69]
	v_mfma_f32_16x16x32_bf16 v[94:97], v[240:243], v[184:187], v[94:97]
	v_mfma_f32_16x16x32_bf16 v[90:93], v[248:251], v[184:187], v[90:93]
	v_mfma_f32_16x16x32_bf16 v[86:89], v[240:243], v[192:195], v[86:89]
	v_mfma_f32_16x16x32_bf16 v[82:85], v[248:251], v[192:195], v[82:85]
	v_mfma_f32_16x16x32_bf16 v[78:81], v[240:243], v[200:203], v[78:81]
	v_mfma_f32_16x16x32_bf16 v[74:77], v[248:251], v[200:203], v[74:77]
	v_mfma_f32_16x16x32_bf16 v[70:73], v[240:243], v[232:235], v[70:73]
	v_mfma_f32_16x16x32_bf16 v[66:69], v[248:251], v[232:235], v[66:69]
	s_setprio 0
	v_readfirstlane_b32 s1, v147
	v_lshl_add_u64 v[228:229], v[204:205], 0, s[74:75]
	s_mov_b32 m0, s1
	v_readfirstlane_b32 s1, v148
	s_barrier
	global_load_lds_dwordx4 v[228:229], off
	v_lshl_add_u64 v[228:229], v[210:211], 0, s[74:75]
	s_mov_b32 m0, s1
	s_nop 0
	global_load_lds_dwordx4 v[228:229], off
	ds_read_b128 v[180:183], v0 offset:16384
	ds_read_b128 v[184:187], v0 offset:17408
	ds_read_b128 v[188:191], v0 offset:18432
	ds_read_b128 v[192:195], v0 offset:19456
	ds_read_b128 v[196:199], v0 offset:20480
	ds_read_b128 v[200:203], v0 offset:21504
	ds_read_b128 v[222:225], v0 offset:22528
	ds_read_b128 v[232:235], v0 offset:23552
	s_barrier
	s_waitcnt lgkmcnt(0)
	s_setprio 1
	s_waitcnt lgkmcnt(0)
	v_mfma_f32_16x16x32_bf16 v[62:65], v[164:167], v[180:183], v[62:65]
	v_mfma_f32_16x16x32_bf16 v[58:61], v[172:175], v[180:183], v[58:61]
	v_mfma_f32_16x16x32_bf16 v[54:57], v[164:167], v[188:191], v[54:57]
	v_mfma_f32_16x16x32_bf16 v[50:53], v[172:175], v[188:191], v[50:53]
	v_mfma_f32_16x16x32_bf16 v[46:49], v[164:167], v[196:199], v[46:49]
	v_mfma_f32_16x16x32_bf16 v[42:45], v[172:175], v[196:199], v[42:45]
	v_mfma_f32_16x16x32_bf16 v[38:41], v[164:167], v[222:225], v[38:41]
	v_mfma_f32_16x16x32_bf16 v[34:37], v[172:175], v[222:225], v[34:37]
	v_mfma_f32_16x16x32_bf16 v[62:65], v[168:171], v[184:187], v[62:65]
	v_mfma_f32_16x16x32_bf16 v[58:61], v[176:179], v[184:187], v[58:61]
	v_mfma_f32_16x16x32_bf16 v[54:57], v[168:171], v[192:195], v[54:57]
	v_mfma_f32_16x16x32_bf16 v[50:53], v[176:179], v[192:195], v[50:53]
	v_mfma_f32_16x16x32_bf16 v[46:49], v[168:171], v[200:203], v[46:49]
	v_mfma_f32_16x16x32_bf16 v[42:45], v[176:179], v[200:203], v[42:45]
	v_mfma_f32_16x16x32_bf16 v[38:41], v[168:171], v[232:235], v[38:41]
	v_mfma_f32_16x16x32_bf16 v[34:37], v[176:179], v[232:235], v[34:37]
	s_setprio 0
	s_barrier
	v_readfirstlane_b32 s1, v152
	v_lshl_add_u64 v[164:165], v[216:217], 0, s[18:19]
	s_mov_b32 m0, s1
	v_readfirstlane_b32 s1, v153
	global_load_lds_dwordx4 v[164:165], off
	v_lshl_add_u64 v[164:165], v[218:219], 0, s[18:19]
	s_mov_b32 m0, s1
	s_nop 0
	global_load_lds_dwordx4 v[164:165], off
	s_waitcnt vmcnt(6)
	s_barrier
	s_setprio 1
	v_mfma_f32_16x16x32_bf16 v[30:33], v[236:239], v[180:183], v[30:33]
	v_mfma_f32_16x16x32_bf16 v[26:29], v[244:247], v[180:183], v[26:29]
	v_mfma_f32_16x16x32_bf16 v[22:25], v[236:239], v[188:191], v[22:25]
	v_mfma_f32_16x16x32_bf16 v[18:21], v[244:247], v[188:191], v[18:21]
	v_mfma_f32_16x16x32_bf16 v[14:17], v[236:239], v[196:199], v[14:17]
	v_mfma_f32_16x16x32_bf16 v[10:13], v[244:247], v[196:199], v[10:13]
	v_mfma_f32_16x16x32_bf16 v[6:9], v[236:239], v[222:225], v[6:9]
	v_mfma_f32_16x16x32_bf16 v[2:5], v[244:247], v[222:225], v[2:5]
	v_mfma_f32_16x16x32_bf16 v[30:33], v[240:243], v[184:187], v[30:33]
	v_mfma_f32_16x16x32_bf16 v[26:29], v[248:251], v[184:187], v[26:29]
	v_mfma_f32_16x16x32_bf16 v[22:25], v[240:243], v[192:195], v[22:25]
	v_mfma_f32_16x16x32_bf16 v[18:21], v[248:251], v[192:195], v[18:21]
	v_mfma_f32_16x16x32_bf16 v[14:17], v[240:243], v[200:203], v[14:17]
	v_mfma_f32_16x16x32_bf16 v[10:13], v[248:251], v[200:203], v[10:13]
	v_mfma_f32_16x16x32_bf16 v[6:9], v[240:243], v[232:235], v[6:9]
	v_mfma_f32_16x16x32_bf16 v[2:5], v[248:251], v[232:235], v[2:5]
	s_setprio 0
	s_barrier
	v_readfirstlane_b32 s1, v154
	v_lshl_add_u64 v[228:229], v[204:205], 0, s[18:19]
	s_mov_b32 m0, s1
	v_readfirstlane_b32 s1, v155
	global_load_lds_dwordx4 v[228:229], off
	v_lshl_add_u64 v[228:229], v[210:211], 0, s[18:19]
	s_mov_b32 m0, s1
	s_nop 0
	global_load_lds_dwordx4 v[228:229], off
	ds_read_b128 v[164:167], v151 offset:32768
	ds_read_b128 v[168:171], v151 offset:33792
	ds_read_b128 v[172:175], v151 offset:34816
	ds_read_b128 v[176:179], v151 offset:35840
	ds_read_b128 v[180:183], v0 offset:32768
	ds_read_b128 v[184:187], v0 offset:33792
	ds_read_b128 v[188:191], v0 offset:34816
	ds_read_b128 v[192:195], v0 offset:35840
	ds_read_b128 v[196:199], v0 offset:36864
	ds_read_b128 v[200:203], v0 offset:37888
	ds_read_b128 v[222:225], v0 offset:38912
	ds_read_b128 v[232:235], v0 offset:39936
	s_waitcnt lgkmcnt(8)
	s_barrier
	s_waitcnt lgkmcnt(0)
	s_setprio 1
	s_waitcnt lgkmcnt(0)
	v_mfma_f32_16x16x32_bf16 v[126:129], v[164:167], v[180:183], v[126:129]
	v_mfma_f32_16x16x32_bf16 v[122:125], v[172:175], v[180:183], v[122:125]
	v_mfma_f32_16x16x32_bf16 v[118:121], v[164:167], v[188:191], v[118:121]
	v_mfma_f32_16x16x32_bf16 v[114:117], v[172:175], v[188:191], v[114:117]
	v_mfma_f32_16x16x32_bf16 v[110:113], v[164:167], v[196:199], v[110:113]
	v_mfma_f32_16x16x32_bf16 v[106:109], v[172:175], v[196:199], v[106:109]
	v_mfma_f32_16x16x32_bf16 v[102:105], v[164:167], v[222:225], v[102:105]
	v_mfma_f32_16x16x32_bf16 v[98:101], v[172:175], v[222:225], v[98:101]
	v_mfma_f32_16x16x32_bf16 v[126:129], v[168:171], v[184:187], v[126:129]
	v_mfma_f32_16x16x32_bf16 v[122:125], v[176:179], v[184:187], v[122:125]
	v_mfma_f32_16x16x32_bf16 v[118:121], v[168:171], v[192:195], v[118:121]
	v_mfma_f32_16x16x32_bf16 v[114:117], v[176:179], v[192:195], v[114:117]
	v_mfma_f32_16x16x32_bf16 v[110:113], v[168:171], v[200:203], v[110:113]
	v_mfma_f32_16x16x32_bf16 v[106:109], v[176:179], v[200:203], v[106:109]
	v_mfma_f32_16x16x32_bf16 v[102:105], v[168:171], v[232:235], v[102:105]
	v_mfma_f32_16x16x32_bf16 v[98:101], v[176:179], v[232:235], v[98:101]
	s_setprio 0
	s_barrier
	v_readfirstlane_b32 s1, v156
	v_lshl_add_u64 v[228:229], v[216:217], 0, s[28:29]
	s_mov_b32 m0, s1
	v_readfirstlane_b32 s1, v157
	global_load_lds_dwordx4 v[228:229], off
	v_lshl_add_u64 v[228:229], v[218:219], 0, s[28:29]
	s_mov_b32 m0, s1
	s_nop 0
	global_load_lds_dwordx4 v[228:229], off
	ds_read_b128 v[236:239], v151 offset:49152
	ds_read_b128 v[240:243], v151 offset:50176
	ds_read_b128 v[244:247], v151 offset:51200
	ds_read_b128 v[248:251], v151 offset:52224
	s_barrier
	s_waitcnt lgkmcnt(0)
	s_setprio 1
	s_waitcnt lgkmcnt(0)
	v_mfma_f32_16x16x32_bf16 v[94:97], v[236:239], v[180:183], v[94:97]
	v_mfma_f32_16x16x32_bf16 v[90:93], v[244:247], v[180:183], v[90:93]
	v_mfma_f32_16x16x32_bf16 v[86:89], v[236:239], v[188:191], v[86:89]
	v_mfma_f32_16x16x32_bf16 v[82:85], v[244:247], v[188:191], v[82:85]
	v_mfma_f32_16x16x32_bf16 v[78:81], v[236:239], v[196:199], v[78:81]
	v_mfma_f32_16x16x32_bf16 v[74:77], v[244:247], v[196:199], v[74:77]
	v_mfma_f32_16x16x32_bf16 v[70:73], v[236:239], v[222:225], v[70:73]
	v_mfma_f32_16x16x32_bf16 v[66:69], v[244:247], v[222:225], v[66:69]
	v_mfma_f32_16x16x32_bf16 v[94:97], v[240:243], v[184:187], v[94:97]
	v_mfma_f32_16x16x32_bf16 v[90:93], v[248:251], v[184:187], v[90:93]
	v_mfma_f32_16x16x32_bf16 v[86:89], v[240:243], v[192:195], v[86:89]
	v_mfma_f32_16x16x32_bf16 v[82:85], v[248:251], v[192:195], v[82:85]
	v_mfma_f32_16x16x32_bf16 v[78:81], v[240:243], v[200:203], v[78:81]
	v_mfma_f32_16x16x32_bf16 v[74:77], v[248:251], v[200:203], v[74:77]
	v_mfma_f32_16x16x32_bf16 v[70:73], v[240:243], v[232:235], v[70:73]
	v_mfma_f32_16x16x32_bf16 v[66:69], v[248:251], v[232:235], v[66:69]
	s_setprio 0
	v_readfirstlane_b32 s1, v158
	v_lshl_add_u64 v[204:205], v[204:205], 0, s[28:29]
	s_mov_b32 m0, s1
	v_readfirstlane_b32 s1, v159
	s_barrier
	global_load_lds_dwordx4 v[204:205], off
	v_lshl_add_u64 v[204:205], v[210:211], 0, s[28:29]
	s_mov_b32 m0, s1
	s_nop 0
	global_load_lds_dwordx4 v[204:205], off
	ds_read_b128 v[180:183], v0 offset:49152
	ds_read_b128 v[184:187], v0 offset:50176
	ds_read_b128 v[188:191], v0 offset:51200
	ds_read_b128 v[192:195], v0 offset:52224
	ds_read_b128 v[196:199], v0 offset:53248
	ds_read_b128 v[200:203], v0 offset:54272
	ds_read_b128 v[222:225], v0 offset:55296
	ds_read_b128 v[232:235], v0 offset:56320
	s_barrier
	s_waitcnt lgkmcnt(0)
	s_setprio 1
	s_waitcnt lgkmcnt(0)
	v_mfma_f32_16x16x32_bf16 v[62:65], v[164:167], v[180:183], v[62:65]
	v_mfma_f32_16x16x32_bf16 v[58:61], v[172:175], v[180:183], v[58:61]
	v_mfma_f32_16x16x32_bf16 v[54:57], v[164:167], v[188:191], v[54:57]
	v_mfma_f32_16x16x32_bf16 v[50:53], v[172:175], v[188:191], v[50:53]
	v_mfma_f32_16x16x32_bf16 v[46:49], v[164:167], v[196:199], v[46:49]
	v_mfma_f32_16x16x32_bf16 v[42:45], v[172:175], v[196:199], v[42:45]
	v_mfma_f32_16x16x32_bf16 v[38:41], v[164:167], v[222:225], v[38:41]
	v_mfma_f32_16x16x32_bf16 v[34:37], v[172:175], v[222:225], v[34:37]
	v_mfma_f32_16x16x32_bf16 v[62:65], v[168:171], v[184:187], v[62:65]
	v_mfma_f32_16x16x32_bf16 v[58:61], v[176:179], v[184:187], v[58:61]
	v_mfma_f32_16x16x32_bf16 v[54:57], v[168:171], v[192:195], v[54:57]
	v_mfma_f32_16x16x32_bf16 v[50:53], v[176:179], v[192:195], v[50:53]
	v_mfma_f32_16x16x32_bf16 v[46:49], v[168:171], v[200:203], v[46:49]
	v_mfma_f32_16x16x32_bf16 v[42:45], v[176:179], v[200:203], v[42:45]
	v_mfma_f32_16x16x32_bf16 v[38:41], v[168:171], v[232:235], v[38:41]
	v_mfma_f32_16x16x32_bf16 v[34:37], v[176:179], v[232:235], v[34:37]
	s_setprio 0
	s_barrier
	v_readfirstlane_b32 s1, v160
	v_lshl_add_u64 v[164:165], v[216:217], 0, s[30:31]
	s_mov_b32 m0, s1
	v_readfirstlane_b32 s1, v161
	global_load_lds_dwordx4 v[164:165], off
	v_lshl_add_u64 v[164:165], v[218:219], 0, s[30:31]
	s_mov_b32 m0, s1
	s_nop 0
	global_load_lds_dwordx4 v[164:165], off
	s_waitcnt vmcnt(6)
	s_barrier
	s_setprio 1
	v_mfma_f32_16x16x32_bf16 v[30:33], v[236:239], v[180:183], v[30:33]
	v_mfma_f32_16x16x32_bf16 v[26:29], v[244:247], v[180:183], v[26:29]
	v_mfma_f32_16x16x32_bf16 v[22:25], v[236:239], v[188:191], v[22:25]
	v_mfma_f32_16x16x32_bf16 v[18:21], v[244:247], v[188:191], v[18:21]
	v_mfma_f32_16x16x32_bf16 v[14:17], v[236:239], v[196:199], v[14:17]
	v_mfma_f32_16x16x32_bf16 v[10:13], v[244:247], v[196:199], v[10:13]
	v_mfma_f32_16x16x32_bf16 v[6:9], v[236:239], v[222:225], v[6:9]
	v_mfma_f32_16x16x32_bf16 v[2:5], v[244:247], v[222:225], v[2:5]
	v_mfma_f32_16x16x32_bf16 v[30:33], v[240:243], v[184:187], v[30:33]
	v_mfma_f32_16x16x32_bf16 v[26:29], v[248:251], v[184:187], v[26:29]
	v_mfma_f32_16x16x32_bf16 v[22:25], v[240:243], v[192:195], v[22:25]
	v_mfma_f32_16x16x32_bf16 v[18:21], v[248:251], v[192:195], v[18:21]
	v_mfma_f32_16x16x32_bf16 v[14:17], v[240:243], v[200:203], v[14:17]
	v_mfma_f32_16x16x32_bf16 v[10:13], v[248:251], v[200:203], v[10:13]
	v_mfma_f32_16x16x32_bf16 v[6:9], v[240:243], v[232:235], v[6:9]
	v_mfma_f32_16x16x32_bf16 v[2:5], v[248:251], v[232:235], v[2:5]
	s_setprio 0
	s_add_i32 s0, s0, 2
	s_add_u32 s12, s12, 0x100
	s_addc_u32 s13, s13, 0
	s_cmp_lt_u32 s0, 28
	s_barrier
	s_cbranch_scc1 .LBB0_180
	s_mov_b64 s[12:13], 0xf80
	v_readfirstlane_b32 s0, v162
	v_lshl_add_u64 v[132:133], v[132:133], 0, s[12:13]
	s_mov_b32 m0, s0
	v_readfirstlane_b32 s0, v163
	ds_read_b128 v[134:137], v151
	ds_read_b128 v[138:141], v151 offset:1024
	ds_read_b128 v[152:155], v151 offset:2048
	ds_read_b128 v[156:159], v151 offset:3072
	ds_read_b128 v[164:167], v0
	ds_read_b128 v[168:171], v0 offset:1024
	ds_read_b128 v[172:175], v0 offset:2048
	ds_read_b128 v[176:179], v0 offset:3072
	ds_read_b128 v[180:183], v0 offset:4096
	ds_read_b128 v[184:187], v0 offset:5120
	ds_read_b128 v[188:191], v0 offset:6144
	ds_read_b128 v[192:195], v0 offset:7168
	global_load_lds_dwordx4 v[132:133], off
	v_lshl_add_u64 v[130:131], v[130:131], 0, s[12:13]
	s_mov_b32 m0, s0
	s_nop 0
	global_load_lds_dwordx4 v[130:131], off
	s_barrier
	s_waitcnt lgkmcnt(0)
	s_setprio 1
	s_waitcnt lgkmcnt(0)
	v_mfma_f32_16x16x32_bf16 v[126:129], v[134:137], v[164:167], v[126:129]
	v_mfma_f32_16x16x32_bf16 v[122:125], v[152:155], v[164:167], v[122:125]
	v_mfma_f32_16x16x32_bf16 v[114:117], v[152:155], v[172:175], v[114:117]
	v_mfma_f32_16x16x32_bf16 v[106:109], v[152:155], v[180:183], v[106:109]
	v_mfma_f32_16x16x32_bf16 v[98:101], v[152:155], v[188:191], v[98:101]
	v_mfma_f32_16x16x32_bf16 v[126:129], v[138:141], v[168:171], v[126:129]
	v_mfma_f32_16x16x32_bf16 v[122:125], v[156:159], v[168:171], v[122:125]
	v_mfma_f32_16x16x32_bf16 v[118:121], v[134:137], v[172:175], v[118:121]
	v_mfma_f32_16x16x32_bf16 v[114:117], v[156:159], v[176:179], v[114:117]
	v_mfma_f32_16x16x32_bf16 v[110:113], v[134:137], v[180:183], v[110:113]
	v_mfma_f32_16x16x32_bf16 v[106:109], v[156:159], v[184:187], v[106:109]
	v_mfma_f32_16x16x32_bf16 v[102:105], v[134:137], v[188:191], v[102:105]
	v_mfma_f32_16x16x32_bf16 v[98:101], v[156:159], v[192:195], v[98:101]
	v_mfma_f32_16x16x32_bf16 v[130:133], v[138:141], v[176:179], v[118:121]
	v_mfma_f32_16x16x32_bf16 v[160:163], v[138:141], v[184:187], v[110:113]
	v_mfma_f32_16x16x32_bf16 v[196:199], v[138:141], v[192:195], v[102:105]
	s_setprio 0
	s_barrier
	s_nop 0
	ds_read_b128 v[102:105], v151 offset:16384
	ds_read_b128 v[110:113], v151 offset:17408
	ds_read_b128 v[118:121], v151 offset:18432
	ds_read_b128 v[200:203], v151 offset:19456
	s_barrier
	s_waitcnt lgkmcnt(0)
	s_setprio 1
	s_waitcnt lgkmcnt(1)
	v_mfma_f32_16x16x32_bf16 v[90:93], v[118:121], v[164:167], v[90:93]
	v_mfma_f32_16x16x32_bf16 v[82:85], v[118:121], v[172:175], v[82:85]
	v_mfma_f32_16x16x32_bf16 v[74:77], v[118:121], v[180:183], v[74:77]
	v_mfma_f32_16x16x32_bf16 v[66:69], v[118:121], v[188:191], v[66:69]
	v_mfma_f32_16x16x32_bf16 v[94:97], v[102:105], v[164:167], v[94:97]
	s_waitcnt lgkmcnt(0)
	v_mfma_f32_16x16x32_bf16 v[90:93], v[200:203], v[168:171], v[90:93]
	v_mfma_f32_16x16x32_bf16 v[86:89], v[102:105], v[172:175], v[86:89]
	v_mfma_f32_16x16x32_bf16 v[82:85], v[200:203], v[176:179], v[82:85]
	v_mfma_f32_16x16x32_bf16 v[78:81], v[102:105], v[180:183], v[78:81]
	v_mfma_f32_16x16x32_bf16 v[74:77], v[200:203], v[184:187], v[74:77]
	v_mfma_f32_16x16x32_bf16 v[70:73], v[102:105], v[188:191], v[70:73]
	v_mfma_f32_16x16x32_bf16 v[66:69], v[200:203], v[192:195], v[66:69]
	v_mfma_f32_16x16x32_bf16 v[222:225], v[110:113], v[168:171], v[94:97]
	v_mfma_f32_16x16x32_bf16 v[164:167], v[110:113], v[176:179], v[86:89]
	v_mfma_f32_16x16x32_bf16 v[168:171], v[110:113], v[184:187], v[78:81]
	v_mfma_f32_16x16x32_bf16 v[172:175], v[110:113], v[192:195], v[70:73]
	s_setprio 0
	s_barrier
	s_nop 0
	ds_read_b128 v[70:73], v0 offset:16384
	ds_read_b128 v[78:81], v0 offset:17408
	ds_read_b128 v[86:89], v0 offset:18432
	ds_read_b128 v[94:97], v0 offset:19456
	ds_read_b128 v[176:179], v0 offset:20480
	ds_read_b128 v[180:183], v0 offset:21504
	ds_read_b128 v[184:187], v0 offset:22528
	ds_read_b128 v[188:191], v0 offset:23552
	s_waitcnt vmcnt(4)
	s_barrier
	s_waitcnt lgkmcnt(0)
	s_setprio 1
	s_waitcnt lgkmcnt(7)
	v_mfma_f32_16x16x32_bf16 v[62:65], v[134:137], v[70:73], v[62:65]
	v_mfma_f32_16x16x32_bf16 v[58:61], v[152:155], v[70:73], v[58:61]
	s_waitcnt lgkmcnt(5)
	v_mfma_f32_16x16x32_bf16 v[50:53], v[152:155], v[86:89], v[50:53]
	s_waitcnt lgkmcnt(3)
	v_mfma_f32_16x16x32_bf16 v[42:45], v[152:155], v[176:179], v[42:45]
	s_waitcnt lgkmcnt(1)
	v_mfma_f32_16x16x32_bf16 v[34:37], v[152:155], v[184:187], v[34:37]
	v_mfma_f32_16x16x32_bf16 v[62:65], v[138:141], v[78:81], v[62:65]
	v_mfma_f32_16x16x32_bf16 v[58:61], v[156:159], v[78:81], v[58:61]
	v_mfma_f32_16x16x32_bf16 v[54:57], v[134:137], v[86:89], v[54:57]
	v_mfma_f32_16x16x32_bf16 v[50:53], v[156:159], v[94:97], v[50:53]
	v_mfma_f32_16x16x32_bf16 v[46:49], v[134:137], v[176:179], v[46:49]
	v_mfma_f32_16x16x32_bf16 v[42:45], v[156:159], v[180:183], v[42:45]
	v_mfma_f32_16x16x32_bf16 v[38:41], v[134:137], v[184:187], v[38:41]
	s_waitcnt lgkmcnt(0)
	v_mfma_f32_16x16x32_bf16 v[34:37], v[156:159], v[188:191], v[34:37]
	v_mfma_f32_16x16x32_bf16 v[192:195], v[138:141], v[94:97], v[54:57]
	v_mfma_f32_16x16x32_bf16 v[232:235], v[138:141], v[180:183], v[46:49]
	v_mfma_f32_16x16x32_bf16 v[134:137], v[138:141], v[188:191], v[38:41]
	s_setprio 0
	s_setprio 1
	v_mfma_f32_16x16x32_bf16 v[26:29], v[118:121], v[70:73], v[26:29]
	v_mfma_f32_16x16x32_bf16 v[18:21], v[118:121], v[86:89], v[18:21]
	v_mfma_f32_16x16x32_bf16 v[10:13], v[118:121], v[176:179], v[10:13]
	v_mfma_f32_16x16x32_bf16 v[2:5], v[118:121], v[184:187], v[2:5]
	v_mfma_f32_16x16x32_bf16 v[30:33], v[102:105], v[70:73], v[30:33]
	v_mfma_f32_16x16x32_bf16 v[26:29], v[200:203], v[78:81], v[26:29]
	v_mfma_f32_16x16x32_bf16 v[22:25], v[102:105], v[86:89], v[22:25]
	v_mfma_f32_16x16x32_bf16 v[18:21], v[200:203], v[94:97], v[18:21]
	v_mfma_f32_16x16x32_bf16 v[14:17], v[102:105], v[176:179], v[14:17]
	v_mfma_f32_16x16x32_bf16 v[10:13], v[200:203], v[180:183], v[10:13]
	v_mfma_f32_16x16x32_bf16 v[6:9], v[102:105], v[184:187], v[6:9]
	v_mfma_f32_16x16x32_bf16 v[2:5], v[200:203], v[188:191], v[2:5]
	v_mfma_f32_16x16x32_bf16 v[138:141], v[110:113], v[78:81], v[30:33]
	v_mfma_f32_16x16x32_bf16 v[152:155], v[110:113], v[94:97], v[22:25]
	v_mfma_f32_16x16x32_bf16 v[156:159], v[110:113], v[180:183], v[14:17]
	v_mfma_f32_16x16x32_bf16 v[176:179], v[110:113], v[188:191], v[6:9]
	s_setprio 0
	s_barrier
	s_nop 0
	ds_read_b128 v[6:9], v151 offset:32768
	ds_read_b128 v[14:17], v151 offset:33792
	ds_read_b128 v[180:183], v151 offset:34816
	ds_read_b128 v[184:187], v151 offset:35840
	ds_read_b128 v[22:25], v0 offset:32768
	ds_read_b128 v[30:33], v0 offset:33792
	ds_read_b128 v[38:41], v0 offset:34816
	ds_read_b128 v[46:49], v0 offset:35840
	ds_read_b128 v[54:57], v0 offset:36864
	ds_read_b128 v[188:191], v0 offset:37888
	ds_read_b128 v[200:203], v0 offset:38912
	ds_read_b128 v[236:239], v0 offset:39936
	s_waitcnt vmcnt(2)
	s_barrier
	s_waitcnt lgkmcnt(0)
	s_setprio 1
	s_waitcnt lgkmcnt(7)
	v_mfma_f32_16x16x32_bf16 v[70:73], v[6:9], v[22:25], v[126:129]
	s_waitcnt lgkmcnt(6)
	v_mfma_f32_16x16x32_bf16 v[126:129], v[14:17], v[30:33], v[70:73]
	v_mfma_f32_16x16x32_bf16 v[70:73], v[180:183], v[22:25], v[122:125]
	v_mfma_f32_16x16x32_bf16 v[118:121], v[184:187], v[30:33], v[70:73]
	s_waitcnt lgkmcnt(5)
	v_mfma_f32_16x16x32_bf16 v[70:73], v[6:9], v[38:41], v[130:133]
	s_waitcnt lgkmcnt(4)
	v_mfma_f32_16x16x32_bf16 v[110:113], v[14:17], v[46:49], v[70:73]
	v_mfma_f32_16x16x32_bf16 v[70:73], v[180:183], v[38:41], v[114:117]
	v_mfma_f32_16x16x32_bf16 v[102:105], v[184:187], v[46:49], v[70:73]
	s_waitcnt lgkmcnt(3)
	v_mfma_f32_16x16x32_bf16 v[70:73], v[6:9], v[54:57], v[160:163]
	s_waitcnt lgkmcnt(2)
	v_mfma_f32_16x16x32_bf16 v[94:97], v[14:17], v[188:191], v[70:73]
	v_mfma_f32_16x16x32_bf16 v[70:73], v[180:183], v[54:57], v[106:109]
	v_mfma_f32_16x16x32_bf16 v[86:89], v[184:187], v[188:191], v[70:73]
	s_waitcnt lgkmcnt(1)
	v_mfma_f32_16x16x32_bf16 v[70:73], v[6:9], v[200:203], v[196:199]
	s_waitcnt lgkmcnt(0)
	v_mfma_f32_16x16x32_bf16 v[78:81], v[14:17], v[236:239], v[70:73]
	v_mfma_f32_16x16x32_bf16 v[70:73], v[180:183], v[200:203], v[98:101]
	v_mfma_f32_16x16x32_bf16 v[70:73], v[184:187], v[236:239], v[70:73]
	s_setprio 0
	s_barrier
	ds_read_b128 v[130:133], v151 offset:49152
	ds_read_b128 v[160:163], v151 offset:50176
	ds_read_b128 v[196:199], v151 offset:51200
	ds_read_b128 v[148:151], v151 offset:52224
	s_waitcnt vmcnt(0)
	s_barrier
	s_waitcnt lgkmcnt(0)
	s_setprio 1
	s_waitcnt lgkmcnt(3)
	v_mfma_f32_16x16x32_bf16 v[98:101], v[130:133], v[22:25], v[222:225]
	s_waitcnt lgkmcnt(1)
	v_mfma_f32_16x16x32_bf16 v[22:25], v[196:199], v[22:25], v[90:93]
	s_waitcnt lgkmcnt(0)
	v_mfma_f32_16x16x32_bf16 v[114:117], v[148:151], v[30:33], v[22:25]
	v_mfma_f32_16x16x32_bf16 v[22:25], v[130:133], v[38:41], v[164:167]
	v_mfma_f32_16x16x32_bf16 v[106:109], v[160:163], v[46:49], v[22:25]
	v_mfma_f32_16x16x32_bf16 v[22:25], v[196:199], v[38:41], v[82:85]
	v_mfma_f32_16x16x32_bf16 v[122:125], v[160:163], v[30:33], v[98:101]
	v_mfma_f32_16x16x32_bf16 v[98:101], v[148:151], v[46:49], v[22:25]
	v_mfma_f32_16x16x32_bf16 v[22:25], v[130:133], v[54:57], v[168:171]
	v_mfma_f32_16x16x32_bf16 v[90:93], v[160:163], v[188:191], v[22:25]
	v_mfma_f32_16x16x32_bf16 v[22:25], v[196:199], v[54:57], v[74:77]
	v_mfma_f32_16x16x32_bf16 v[82:85], v[148:151], v[188:191], v[22:25]
	v_mfma_f32_16x16x32_bf16 v[22:25], v[130:133], v[200:203], v[172:175]
	v_mfma_f32_16x16x32_bf16 v[74:77], v[160:163], v[236:239], v[22:25]
	v_mfma_f32_16x16x32_bf16 v[22:25], v[196:199], v[200:203], v[66:69]
	v_mfma_f32_16x16x32_bf16 v[66:69], v[148:151], v[236:239], v[22:25]
	s_setprio 0
	s_barrier
	ds_read_b128 v[164:167], v0 offset:49152
	ds_read_b128 v[168:171], v0 offset:50176
	ds_read_b128 v[172:175], v0 offset:51200
	ds_read_b128 v[188:191], v0 offset:52224
	ds_read_b128 v[200:203], v0 offset:53248
	ds_read_b128 v[222:225], v0 offset:54272
	ds_read_b128 v[236:239], v0 offset:55296
	ds_read_b128 v[240:243], v0 offset:56320
	s_barrier
	s_waitcnt lgkmcnt(0)
	s_setprio 1
	s_waitcnt lgkmcnt(7)
	v_mfma_f32_16x16x32_bf16 v[22:25], v[6:9], v[164:167], v[62:65]
	s_waitcnt lgkmcnt(6)
	v_mfma_f32_16x16x32_bf16 v[62:65], v[14:17], v[168:171], v[22:25]
	v_mfma_f32_16x16x32_bf16 v[22:25], v[180:183], v[164:167], v[58:61]
	v_mfma_f32_16x16x32_bf16 v[54:57], v[184:187], v[168:171], v[22:25]
	s_waitcnt lgkmcnt(5)
	v_mfma_f32_16x16x32_bf16 v[22:25], v[6:9], v[172:175], v[192:195]
	s_waitcnt lgkmcnt(4)
	v_mfma_f32_16x16x32_bf16 v[46:49], v[14:17], v[188:191], v[22:25]
	v_mfma_f32_16x16x32_bf16 v[22:25], v[180:183], v[172:175], v[50:53]
	v_mfma_f32_16x16x32_bf16 v[38:41], v[184:187], v[188:191], v[22:25]
	s_waitcnt lgkmcnt(3)
	v_mfma_f32_16x16x32_bf16 v[22:25], v[6:9], v[200:203], v[232:235]
	s_waitcnt lgkmcnt(1)
	v_mfma_f32_16x16x32_bf16 v[6:9], v[6:9], v[236:239], v[134:137]
	v_mfma_f32_16x16x32_bf16 v[30:33], v[14:17], v[222:225], v[22:25]
	v_mfma_f32_16x16x32_bf16 v[22:25], v[180:183], v[200:203], v[42:45]
	s_waitcnt lgkmcnt(0)
	v_mfma_f32_16x16x32_bf16 v[14:17], v[14:17], v[240:243], v[6:9]
	v_mfma_f32_16x16x32_bf16 v[6:9], v[180:183], v[236:239], v[34:37]
	v_mfma_f32_16x16x32_bf16 v[22:25], v[184:187], v[222:225], v[22:25]
	v_mfma_f32_16x16x32_bf16 v[6:9], v[184:187], v[240:243], v[6:9]
	s_setprio 0
	s_setprio 1
	v_mfma_f32_16x16x32_bf16 v[34:37], v[130:133], v[164:167], v[138:141]
	v_mfma_f32_16x16x32_bf16 v[26:29], v[196:199], v[164:167], v[26:29]
	v_mfma_f32_16x16x32_bf16 v[18:21], v[196:199], v[172:175], v[18:21]
	v_mfma_f32_16x16x32_bf16 v[58:61], v[160:163], v[168:171], v[34:37]
	v_mfma_f32_16x16x32_bf16 v[50:53], v[148:151], v[168:171], v[26:29]
	v_mfma_f32_16x16x32_bf16 v[26:29], v[130:133], v[172:175], v[152:155]
	v_mfma_f32_16x16x32_bf16 v[34:37], v[148:151], v[188:191], v[18:21]
	v_mfma_f32_16x16x32_bf16 v[18:21], v[130:133], v[200:203], v[156:159]
	v_mfma_f32_16x16x32_bf16 v[10:13], v[196:199], v[200:203], v[10:13]
	v_mfma_f32_16x16x32_bf16 v[42:45], v[160:163], v[188:191], v[26:29]
	v_mfma_f32_16x16x32_bf16 v[26:29], v[160:163], v[222:225], v[18:21]
	v_mfma_f32_16x16x32_bf16 v[18:21], v[148:151], v[222:225], v[10:13]
	v_mfma_f32_16x16x32_bf16 v[10:13], v[130:133], v[236:239], v[176:179]
	v_mfma_f32_16x16x32_bf16 v[2:5], v[196:199], v[236:239], v[2:5]
	v_mfma_f32_16x16x32_bf16 v[10:13], v[160:163], v[240:243], v[10:13]
	v_mfma_f32_16x16x32_bf16 v[2:5], v[148:151], v[240:243], v[2:5]
	s_setprio 0
	s_movk_i32 s0, 0x100
	v_cmp_gt_u32_e32 vcc, s0, v142
	s_barrier
	s_and_saveexec_b64 s[0:1], vcc
	s_cbranch_execz .LBB0_183
	s_barrier

.LBB0_678:
	v_add_u32_e32 v162, 0xc000, v147
	v_lshl_add_u64 v[204:205], v[138:139], 0, s[8:9]
	v_readfirstlane_b32 s1, v162
	v_add_u32_e32 v163, 0xe000, v147
	v_lshl_add_u64 v[222:223], v[204:205], 0, s[60:61]
	s_mov_b32 m0, s1
	v_lshl_add_u64 v[216:217], v[140:141], 0, s[8:9]
	v_readfirstlane_b32 s1, v163
	global_load_lds_dwordx4 v[222:223], off
	v_lshl_add_u64 v[222:223], v[216:217], 0, s[60:61]
	s_mov_b32 m0, s1
	s_nop 0
	global_load_lds_dwordx4 v[222:223], off
	ds_read_b128 v[164:167], v151
	ds_read_b128 v[168:171], v151 offset:1024
	ds_read_b128 v[172:175], v151 offset:2048
	ds_read_b128 v[176:179], v151 offset:3072
	ds_read_b128 v[180:183], v0
	ds_read_b128 v[184:187], v0 offset:1024
	ds_read_b128 v[188:191], v0 offset:2048
	ds_read_b128 v[192:195], v0 offset:3072
	ds_read_b128 v[196:199], v0 offset:4096
	ds_read_b128 v[200:203], v0 offset:5120
	ds_read_b128 v[232:235], v0 offset:6144
	ds_read_b128 v[236:239], v0 offset:7168
	s_waitcnt lgkmcnt(8)
	s_barrier
	s_waitcnt lgkmcnt(0)
	s_setprio 1
	s_waitcnt lgkmcnt(0)
	v_mfma_f32_16x16x32_bf16 v[126:129], v[164:167], v[180:183], v[126:129]
	v_mfma_f32_16x16x32_bf16 v[122:125], v[172:175], v[180:183], v[122:125]
	v_mfma_f32_16x16x32_bf16 v[118:121], v[164:167], v[188:191], v[118:121]
	v_mfma_f32_16x16x32_bf16 v[114:117], v[172:175], v[188:191], v[114:117]
	v_mfma_f32_16x16x32_bf16 v[110:113], v[164:167], v[196:199], v[110:113]
	v_mfma_f32_16x16x32_bf16 v[106:109], v[172:175], v[196:199], v[106:109]
	v_mfma_f32_16x16x32_bf16 v[102:105], v[164:167], v[232:235], v[102:105]
	v_mfma_f32_16x16x32_bf16 v[98:101], v[172:175], v[232:235], v[98:101]
	v_mfma_f32_16x16x32_bf16 v[126:129], v[168:171], v[184:187], v[126:129]
	v_mfma_f32_16x16x32_bf16 v[122:125], v[176:179], v[184:187], v[122:125]
	v_mfma_f32_16x16x32_bf16 v[118:121], v[168:171], v[192:195], v[118:121]
	v_mfma_f32_16x16x32_bf16 v[114:117], v[176:179], v[192:195], v[114:117]
	v_mfma_f32_16x16x32_bf16 v[110:113], v[168:171], v[200:203], v[110:113]
	v_mfma_f32_16x16x32_bf16 v[106:109], v[176:179], v[200:203], v[106:109]
	v_mfma_f32_16x16x32_bf16 v[102:105], v[168:171], v[236:239], v[102:105]
	v_mfma_f32_16x16x32_bf16 v[98:101], v[176:179], v[236:239], v[98:101]
	s_setprio 0
	s_barrier
	v_lshl_add_u64 v[210:211], v[134:135], 0, s[8:9]
	v_readfirstlane_b32 s1, v149
	v_lshl_add_u64 v[228:229], v[210:211], 0, s[74:75]
	s_mov_b32 m0, s1
	global_load_lds_dwordx4 v[228:229], off
	v_lshl_add_u64 v[228:229], v[136:137], 0, s[8:9]
	v_readfirstlane_b32 s1, v150
	v_lshl_add_u64 v[218:219], v[228:229], 0, s[74:75]
	s_mov_b32 m0, s1
	s_nop 0
	global_load_lds_dwordx4 v[218:219], off
	ds_read_b128 v[240:243], v151 offset:16384
	ds_read_b128 v[244:247], v151 offset:17408
	ds_read_b128 v[248:251], v151 offset:18432
	ds_read_b128 v[222:225], v151 offset:19456
	s_barrier
	s_waitcnt lgkmcnt(0)
	s_setprio 1
	s_waitcnt lgkmcnt(0)
	v_mfma_f32_16x16x32_bf16 v[94:97], v[240:243], v[180:183], v[94:97]
	v_mfma_f32_16x16x32_bf16 v[90:93], v[248:251], v[180:183], v[90:93]
	v_mfma_f32_16x16x32_bf16 v[86:89], v[240:243], v[188:191], v[86:89]
	v_mfma_f32_16x16x32_bf16 v[82:85], v[248:251], v[188:191], v[82:85]
	v_mfma_f32_16x16x32_bf16 v[78:81], v[240:243], v[196:199], v[78:81]
	v_mfma_f32_16x16x32_bf16 v[74:77], v[248:251], v[196:199], v[74:77]
	v_mfma_f32_16x16x32_bf16 v[70:73], v[240:243], v[232:235], v[70:73]
	v_mfma_f32_16x16x32_bf16 v[66:69], v[248:251], v[232:235], v[66:69]
	v_mfma_f32_16x16x32_bf16 v[94:97], v[244:247], v[184:187], v[94:97]
	v_mfma_f32_16x16x32_bf16 v[90:93], v[222:225], v[184:187], v[90:93]
	v_mfma_f32_16x16x32_bf16 v[86:89], v[244:247], v[192:195], v[86:89]
	v_mfma_f32_16x16x32_bf16 v[82:85], v[222:225], v[192:195], v[82:85]
	v_mfma_f32_16x16x32_bf16 v[78:81], v[244:247], v[200:203], v[78:81]
	v_mfma_f32_16x16x32_bf16 v[74:77], v[222:225], v[200:203], v[74:77]
	v_mfma_f32_16x16x32_bf16 v[70:73], v[244:247], v[236:239], v[70:73]
	v_mfma_f32_16x16x32_bf16 v[66:69], v[222:225], v[236:239], v[66:69]
	s_setprio 0
	v_readfirstlane_b32 s1, v147
	v_lshl_add_u64 v[218:219], v[204:205], 0, s[74:75]
	s_mov_b32 m0, s1
	v_readfirstlane_b32 s1, v148
	s_barrier
	global_load_lds_dwordx4 v[218:219], off
	v_lshl_add_u64 v[218:219], v[216:217], 0, s[74:75]
	s_mov_b32 m0, s1
	s_nop 0
	global_load_lds_dwordx4 v[218:219], off
	ds_read_b128 v[180:183], v0 offset:16384
	ds_read_b128 v[184:187], v0 offset:17408
	ds_read_b128 v[188:191], v0 offset:18432
	ds_read_b128 v[192:195], v0 offset:19456
	ds_read_b128 v[196:199], v0 offset:20480
	ds_read_b128 v[200:203], v0 offset:21504
	ds_read_b128 v[232:235], v0 offset:22528
	ds_read_b128 v[236:239], v0 offset:23552
	s_barrier
	s_waitcnt lgkmcnt(0)
	s_setprio 1
	s_waitcnt lgkmcnt(0)
	v_mfma_f32_16x16x32_bf16 v[62:65], v[164:167], v[180:183], v[62:65]
	v_mfma_f32_16x16x32_bf16 v[58:61], v[172:175], v[180:183], v[58:61]
	v_mfma_f32_16x16x32_bf16 v[54:57], v[164:167], v[188:191], v[54:57]
	v_mfma_f32_16x16x32_bf16 v[50:53], v[172:175], v[188:191], v[50:53]
	v_mfma_f32_16x16x32_bf16 v[46:49], v[164:167], v[196:199], v[46:49]
	v_mfma_f32_16x16x32_bf16 v[42:45], v[172:175], v[196:199], v[42:45]
	v_mfma_f32_16x16x32_bf16 v[38:41], v[164:167], v[232:235], v[38:41]
	v_mfma_f32_16x16x32_bf16 v[34:37], v[172:175], v[232:235], v[34:37]
	v_mfma_f32_16x16x32_bf16 v[62:65], v[168:171], v[184:187], v[62:65]
	v_mfma_f32_16x16x32_bf16 v[58:61], v[176:179], v[184:187], v[58:61]
	v_mfma_f32_16x16x32_bf16 v[54:57], v[168:171], v[192:195], v[54:57]
	v_mfma_f32_16x16x32_bf16 v[50:53], v[176:179], v[192:195], v[50:53]
	v_mfma_f32_16x16x32_bf16 v[46:49], v[168:171], v[200:203], v[46:49]
	v_mfma_f32_16x16x32_bf16 v[42:45], v[176:179], v[200:203], v[42:45]
	v_mfma_f32_16x16x32_bf16 v[38:41], v[168:171], v[236:239], v[38:41]
	v_mfma_f32_16x16x32_bf16 v[34:37], v[176:179], v[236:239], v[34:37]
	s_setprio 0
	s_barrier
	v_readfirstlane_b32 s1, v152
	v_lshl_add_u64 v[164:165], v[210:211], 0, s[18:19]
	s_mov_b32 m0, s1
	v_readfirstlane_b32 s1, v153
	global_load_lds_dwordx4 v[164:165], off
	v_lshl_add_u64 v[164:165], v[228:229], 0, s[18:19]
	s_mov_b32 m0, s1
	s_nop 0
	global_load_lds_dwordx4 v[164:165], off
	s_waitcnt vmcnt(6)
	s_barrier
	s_setprio 1
	v_mfma_f32_16x16x32_bf16 v[30:33], v[240:243], v[180:183], v[30:33]
	v_mfma_f32_16x16x32_bf16 v[26:29], v[248:251], v[180:183], v[26:29]
	v_mfma_f32_16x16x32_bf16 v[22:25], v[240:243], v[188:191], v[22:25]
	v_mfma_f32_16x16x32_bf16 v[18:21], v[248:251], v[188:191], v[18:21]
	v_mfma_f32_16x16x32_bf16 v[14:17], v[240:243], v[196:199], v[14:17]
	v_mfma_f32_16x16x32_bf16 v[10:13], v[248:251], v[196:199], v[10:13]
	v_mfma_f32_16x16x32_bf16 v[6:9], v[240:243], v[232:235], v[6:9]
	v_mfma_f32_16x16x32_bf16 v[2:5], v[248:251], v[232:235], v[2:5]
	v_mfma_f32_16x16x32_bf16 v[30:33], v[244:247], v[184:187], v[30:33]
	v_mfma_f32_16x16x32_bf16 v[26:29], v[222:225], v[184:187], v[26:29]
	v_mfma_f32_16x16x32_bf16 v[22:25], v[244:247], v[192:195], v[22:25]
	v_mfma_f32_16x16x32_bf16 v[18:21], v[222:225], v[192:195], v[18:21]
	v_mfma_f32_16x16x32_bf16 v[14:17], v[244:247], v[200:203], v[14:17]
	v_mfma_f32_16x16x32_bf16 v[10:13], v[222:225], v[200:203], v[10:13]
	v_mfma_f32_16x16x32_bf16 v[6:9], v[244:247], v[236:239], v[6:9]
	v_mfma_f32_16x16x32_bf16 v[2:5], v[222:225], v[236:239], v[2:5]
	s_setprio 0
	s_barrier
	v_readfirstlane_b32 s1, v154
	v_lshl_add_u64 v[218:219], v[204:205], 0, s[18:19]
	s_mov_b32 m0, s1
	v_readfirstlane_b32 s1, v155
	global_load_lds_dwordx4 v[218:219], off
	v_lshl_add_u64 v[218:219], v[216:217], 0, s[18:19]
	s_mov_b32 m0, s1
	s_nop 0
	global_load_lds_dwordx4 v[218:219], off
	ds_read_b128 v[164:167], v151 offset:32768
	ds_read_b128 v[168:171], v151 offset:33792
	ds_read_b128 v[172:175], v151 offset:34816
	ds_read_b128 v[176:179], v151 offset:35840
	ds_read_b128 v[180:183], v0 offset:32768
	ds_read_b128 v[184:187], v0 offset:33792
	ds_read_b128 v[188:191], v0 offset:34816
	ds_read_b128 v[192:195], v0 offset:35840
	ds_read_b128 v[196:199], v0 offset:36864
	ds_read_b128 v[200:203], v0 offset:37888
	ds_read_b128 v[222:225], v0 offset:38912
	ds_read_b128 v[232:235], v0 offset:39936
	s_waitcnt lgkmcnt(8)
	s_barrier
	s_waitcnt lgkmcnt(0)
	s_setprio 1
	s_waitcnt lgkmcnt(0)
	v_mfma_f32_16x16x32_bf16 v[126:129], v[164:167], v[180:183], v[126:129]
	v_mfma_f32_16x16x32_bf16 v[122:125], v[172:175], v[180:183], v[122:125]
	v_mfma_f32_16x16x32_bf16 v[118:121], v[164:167], v[188:191], v[118:121]
	v_mfma_f32_16x16x32_bf16 v[114:117], v[172:175], v[188:191], v[114:117]
	v_mfma_f32_16x16x32_bf16 v[110:113], v[164:167], v[196:199], v[110:113]
	v_mfma_f32_16x16x32_bf16 v[106:109], v[172:175], v[196:199], v[106:109]
	v_mfma_f32_16x16x32_bf16 v[102:105], v[164:167], v[222:225], v[102:105]
	v_mfma_f32_16x16x32_bf16 v[98:101], v[172:175], v[222:225], v[98:101]
	v_mfma_f32_16x16x32_bf16 v[126:129], v[168:171], v[184:187], v[126:129]
	v_mfma_f32_16x16x32_bf16 v[122:125], v[176:179], v[184:187], v[122:125]
	v_mfma_f32_16x16x32_bf16 v[118:121], v[168:171], v[192:195], v[118:121]
	v_mfma_f32_16x16x32_bf16 v[114:117], v[176:179], v[192:195], v[114:117]
	v_mfma_f32_16x16x32_bf16 v[110:113], v[168:171], v[200:203], v[110:113]
	v_mfma_f32_16x16x32_bf16 v[106:109], v[176:179], v[200:203], v[106:109]
	v_mfma_f32_16x16x32_bf16 v[102:105], v[168:171], v[232:235], v[102:105]
	v_mfma_f32_16x16x32_bf16 v[98:101], v[176:179], v[232:235], v[98:101]
	s_setprio 0
	s_barrier
	v_readfirstlane_b32 s1, v156
	v_lshl_add_u64 v[218:219], v[210:211], 0, s[28:29]
	s_mov_b32 m0, s1
	v_readfirstlane_b32 s1, v157
	global_load_lds_dwordx4 v[218:219], off
	v_lshl_add_u64 v[218:219], v[228:229], 0, s[28:29]
	s_mov_b32 m0, s1
	s_nop 0
	global_load_lds_dwordx4 v[218:219], off
	ds_read_b128 v[236:239], v151 offset:49152
	ds_read_b128 v[240:243], v151 offset:50176
	ds_read_b128 v[244:247], v151 offset:51200
	ds_read_b128 v[248:251], v151 offset:52224
	s_barrier
	s_waitcnt lgkmcnt(0)
	s_setprio 1
	s_waitcnt lgkmcnt(0)
	v_mfma_f32_16x16x32_bf16 v[94:97], v[236:239], v[180:183], v[94:97]
	v_mfma_f32_16x16x32_bf16 v[90:93], v[244:247], v[180:183], v[90:93]
	v_mfma_f32_16x16x32_bf16 v[86:89], v[236:239], v[188:191], v[86:89]
	v_mfma_f32_16x16x32_bf16 v[82:85], v[244:247], v[188:191], v[82:85]
	v_mfma_f32_16x16x32_bf16 v[78:81], v[236:239], v[196:199], v[78:81]
	v_mfma_f32_16x16x32_bf16 v[74:77], v[244:247], v[196:199], v[74:77]
	v_mfma_f32_16x16x32_bf16 v[70:73], v[236:239], v[222:225], v[70:73]
	v_mfma_f32_16x16x32_bf16 v[66:69], v[244:247], v[222:225], v[66:69]
	v_mfma_f32_16x16x32_bf16 v[94:97], v[240:243], v[184:187], v[94:97]
	v_mfma_f32_16x16x32_bf16 v[90:93], v[248:251], v[184:187], v[90:93]
	v_mfma_f32_16x16x32_bf16 v[86:89], v[240:243], v[192:195], v[86:89]
	v_mfma_f32_16x16x32_bf16 v[82:85], v[248:251], v[192:195], v[82:85]
	v_mfma_f32_16x16x32_bf16 v[78:81], v[240:243], v[200:203], v[78:81]
	v_mfma_f32_16x16x32_bf16 v[74:77], v[248:251], v[200:203], v[74:77]
	v_mfma_f32_16x16x32_bf16 v[70:73], v[240:243], v[232:235], v[70:73]
	v_mfma_f32_16x16x32_bf16 v[66:69], v[248:251], v[232:235], v[66:69]
	s_setprio 0
	v_readfirstlane_b32 s1, v158
	v_lshl_add_u64 v[204:205], v[204:205], 0, s[28:29]
	s_mov_b32 m0, s1
	v_readfirstlane_b32 s1, v159
	s_barrier
	global_load_lds_dwordx4 v[204:205], off
	v_lshl_add_u64 v[204:205], v[216:217], 0, s[28:29]
	s_mov_b32 m0, s1
	s_nop 0
	global_load_lds_dwordx4 v[204:205], off
	ds_read_b128 v[180:183], v0 offset:49152
	ds_read_b128 v[184:187], v0 offset:50176
	ds_read_b128 v[188:191], v0 offset:51200
	ds_read_b128 v[192:195], v0 offset:52224
	ds_read_b128 v[196:199], v0 offset:53248
	ds_read_b128 v[200:203], v0 offset:54272
	ds_read_b128 v[222:225], v0 offset:55296
	ds_read_b128 v[232:235], v0 offset:56320
	s_barrier
	s_waitcnt lgkmcnt(0)
	s_setprio 1
	s_waitcnt lgkmcnt(0)
	v_mfma_f32_16x16x32_bf16 v[62:65], v[164:167], v[180:183], v[62:65]
	v_mfma_f32_16x16x32_bf16 v[58:61], v[172:175], v[180:183], v[58:61]
	v_mfma_f32_16x16x32_bf16 v[54:57], v[164:167], v[188:191], v[54:57]
	v_mfma_f32_16x16x32_bf16 v[50:53], v[172:175], v[188:191], v[50:53]
	v_mfma_f32_16x16x32_bf16 v[46:49], v[164:167], v[196:199], v[46:49]
	v_mfma_f32_16x16x32_bf16 v[42:45], v[172:175], v[196:199], v[42:45]
	v_mfma_f32_16x16x32_bf16 v[38:41], v[164:167], v[222:225], v[38:41]
	v_mfma_f32_16x16x32_bf16 v[34:37], v[172:175], v[222:225], v[34:37]
	v_mfma_f32_16x16x32_bf16 v[62:65], v[168:171], v[184:187], v[62:65]
	v_mfma_f32_16x16x32_bf16 v[58:61], v[176:179], v[184:187], v[58:61]
	v_mfma_f32_16x16x32_bf16 v[54:57], v[168:171], v[192:195], v[54:57]
	v_mfma_f32_16x16x32_bf16 v[50:53], v[176:179], v[192:195], v[50:53]
	v_mfma_f32_16x16x32_bf16 v[46:49], v[168:171], v[200:203], v[46:49]
	v_mfma_f32_16x16x32_bf16 v[42:45], v[176:179], v[200:203], v[42:45]
	v_mfma_f32_16x16x32_bf16 v[38:41], v[168:171], v[232:235], v[38:41]
	v_mfma_f32_16x16x32_bf16 v[34:37], v[176:179], v[232:235], v[34:37]
	s_setprio 0
	s_barrier
	v_readfirstlane_b32 s1, v160
	v_lshl_add_u64 v[164:165], v[210:211], 0, s[30:31]
	s_mov_b32 m0, s1
	v_readfirstlane_b32 s1, v161
	global_load_lds_dwordx4 v[164:165], off
	v_lshl_add_u64 v[164:165], v[228:229], 0, s[30:31]
	s_mov_b32 m0, s1
	s_nop 0
	global_load_lds_dwordx4 v[164:165], off
	s_waitcnt vmcnt(6)
	s_barrier
	s_setprio 1
	v_mfma_f32_16x16x32_bf16 v[30:33], v[236:239], v[180:183], v[30:33]
	v_mfma_f32_16x16x32_bf16 v[26:29], v[244:247], v[180:183], v[26:29]
	v_mfma_f32_16x16x32_bf16 v[22:25], v[236:239], v[188:191], v[22:25]
	v_mfma_f32_16x16x32_bf16 v[18:21], v[244:247], v[188:191], v[18:21]
	v_mfma_f32_16x16x32_bf16 v[14:17], v[236:239], v[196:199], v[14:17]
	v_mfma_f32_16x16x32_bf16 v[10:13], v[244:247], v[196:199], v[10:13]
	v_mfma_f32_16x16x32_bf16 v[6:9], v[236:239], v[222:225], v[6:9]
	v_mfma_f32_16x16x32_bf16 v[2:5], v[244:247], v[222:225], v[2:5]
	v_mfma_f32_16x16x32_bf16 v[30:33], v[240:243], v[184:187], v[30:33]
	v_mfma_f32_16x16x32_bf16 v[26:29], v[248:251], v[184:187], v[26:29]
	v_mfma_f32_16x16x32_bf16 v[22:25], v[240:243], v[192:195], v[22:25]
	v_mfma_f32_16x16x32_bf16 v[18:21], v[248:251], v[192:195], v[18:21]
	v_mfma_f32_16x16x32_bf16 v[14:17], v[240:243], v[200:203], v[14:17]
	v_mfma_f32_16x16x32_bf16 v[10:13], v[248:251], v[200:203], v[10:13]
	v_mfma_f32_16x16x32_bf16 v[6:9], v[240:243], v[232:235], v[6:9]
	v_mfma_f32_16x16x32_bf16 v[2:5], v[248:251], v[232:235], v[2:5]
	s_setprio 0
	s_add_i32 s0, s0, 2
	s_add_u32 s8, s8, 0x100
	s_addc_u32 s9, s9, 0
	s_cmp_lt_u32 s0, 28
	s_barrier
	s_cbranch_scc1 .LBB0_678
	s_mov_b64 s[8:9], 0xf80
	v_readfirstlane_b32 s0, v162
	v_lshl_add_u64 v[132:133], v[132:133], 0, s[8:9]
	s_mov_b32 m0, s0
	v_readfirstlane_b32 s0, v163
	ds_read_b128 v[134:137], v151
	ds_read_b128 v[138:141], v151 offset:1024
	ds_read_b128 v[152:155], v151 offset:2048
	ds_read_b128 v[156:159], v151 offset:3072
	ds_read_b128 v[164:167], v0
	ds_read_b128 v[168:171], v0 offset:1024
	ds_read_b128 v[172:175], v0 offset:2048
	ds_read_b128 v[176:179], v0 offset:3072
	ds_read_b128 v[180:183], v0 offset:4096
	ds_read_b128 v[184:187], v0 offset:5120
	ds_read_b128 v[188:191], v0 offset:6144
	ds_read_b128 v[192:195], v0 offset:7168
	global_load_lds_dwordx4 v[132:133], off
	v_lshl_add_u64 v[130:131], v[130:131], 0, s[8:9]
	s_mov_b32 m0, s0
	s_nop 0
	global_load_lds_dwordx4 v[130:131], off
	s_barrier
	s_waitcnt lgkmcnt(0)
	s_setprio 1
	s_waitcnt lgkmcnt(0)
	v_mfma_f32_16x16x32_bf16 v[126:129], v[134:137], v[164:167], v[126:129]
	v_mfma_f32_16x16x32_bf16 v[122:125], v[152:155], v[164:167], v[122:125]
	v_mfma_f32_16x16x32_bf16 v[114:117], v[152:155], v[172:175], v[114:117]
	v_mfma_f32_16x16x32_bf16 v[106:109], v[152:155], v[180:183], v[106:109]
	v_mfma_f32_16x16x32_bf16 v[98:101], v[152:155], v[188:191], v[98:101]
	v_mfma_f32_16x16x32_bf16 v[126:129], v[138:141], v[168:171], v[126:129]
	v_mfma_f32_16x16x32_bf16 v[122:125], v[156:159], v[168:171], v[122:125]
	v_mfma_f32_16x16x32_bf16 v[118:121], v[134:137], v[172:175], v[118:121]
	v_mfma_f32_16x16x32_bf16 v[114:117], v[156:159], v[176:179], v[114:117]
	v_mfma_f32_16x16x32_bf16 v[110:113], v[134:137], v[180:183], v[110:113]
	v_mfma_f32_16x16x32_bf16 v[106:109], v[156:159], v[184:187], v[106:109]
	v_mfma_f32_16x16x32_bf16 v[102:105], v[134:137], v[188:191], v[102:105]
	v_mfma_f32_16x16x32_bf16 v[98:101], v[156:159], v[192:195], v[98:101]
	v_mfma_f32_16x16x32_bf16 v[130:133], v[138:141], v[176:179], v[118:121]
	v_mfma_f32_16x16x32_bf16 v[160:163], v[138:141], v[184:187], v[110:113]
	v_mfma_f32_16x16x32_bf16 v[196:199], v[138:141], v[192:195], v[102:105]
	s_setprio 0
	s_barrier
	s_nop 0
	ds_read_b128 v[102:105], v151 offset:16384
	ds_read_b128 v[110:113], v151 offset:17408
	ds_read_b128 v[118:121], v151 offset:18432
	ds_read_b128 v[200:203], v151 offset:19456
	s_barrier
	s_waitcnt lgkmcnt(0)
	s_setprio 1
	s_waitcnt lgkmcnt(1)
	v_mfma_f32_16x16x32_bf16 v[90:93], v[118:121], v[164:167], v[90:93]
	v_mfma_f32_16x16x32_bf16 v[86:89], v[102:105], v[172:175], v[86:89]
	v_mfma_f32_16x16x32_bf16 v[82:85], v[118:121], v[172:175], v[82:85]
	v_mfma_f32_16x16x32_bf16 v[78:81], v[102:105], v[180:183], v[78:81]
	v_mfma_f32_16x16x32_bf16 v[70:73], v[102:105], v[188:191], v[70:73]
	v_mfma_f32_16x16x32_bf16 v[94:97], v[102:105], v[164:167], v[94:97]
	s_waitcnt lgkmcnt(0)
	v_mfma_f32_16x16x32_bf16 v[90:93], v[200:203], v[168:171], v[90:93]
	v_mfma_f32_16x16x32_bf16 v[86:89], v[110:113], v[176:179], v[86:89]
	v_mfma_f32_16x16x32_bf16 v[82:85], v[200:203], v[176:179], v[82:85]
	v_mfma_f32_16x16x32_bf16 v[78:81], v[110:113], v[184:187], v[78:81]
	v_mfma_f32_16x16x32_bf16 v[74:77], v[118:121], v[180:183], v[74:77]
	v_mfma_f32_16x16x32_bf16 v[70:73], v[110:113], v[192:195], v[70:73]
	v_mfma_f32_16x16x32_bf16 v[66:69], v[118:121], v[188:191], v[66:69]
	v_mfma_f32_16x16x32_bf16 v[222:225], v[110:113], v[168:171], v[94:97]
	v_mfma_f32_16x16x32_bf16 v[164:167], v[200:203], v[184:187], v[74:77]
	v_mfma_f32_16x16x32_bf16 v[168:171], v[200:203], v[192:195], v[66:69]
	s_setprio 0
	s_barrier
	s_nop 2
	ds_read_b128 v[66:69], v0 offset:16384
	ds_read_b128 v[74:77], v0 offset:17408
	ds_read_b128 v[94:97], v0 offset:18432
	ds_read_b128 v[172:175], v0 offset:19456
	ds_read_b128 v[176:179], v0 offset:20480
	ds_read_b128 v[180:183], v0 offset:21504
	ds_read_b128 v[184:187], v0 offset:22528
	ds_read_b128 v[188:191], v0 offset:23552
	s_waitcnt vmcnt(4)
	s_barrier
	s_waitcnt lgkmcnt(0)
	s_setprio 1
	s_waitcnt lgkmcnt(5)
	v_mfma_f32_16x16x32_bf16 v[54:57], v[134:137], v[94:97], v[54:57]
	v_mfma_f32_16x16x32_bf16 v[50:53], v[152:155], v[94:97], v[50:53]
	v_mfma_f32_16x16x32_bf16 v[62:65], v[134:137], v[66:69], v[62:65]
	v_mfma_f32_16x16x32_bf16 v[58:61], v[152:155], v[66:69], v[58:61]
	s_waitcnt lgkmcnt(4)
	v_mfma_f32_16x16x32_bf16 v[54:57], v[138:141], v[172:175], v[54:57]
	v_mfma_f32_16x16x32_bf16 v[50:53], v[156:159], v[172:175], v[50:53]
	s_waitcnt lgkmcnt(3)
	v_mfma_f32_16x16x32_bf16 v[46:49], v[134:137], v[176:179], v[46:49]
	v_mfma_f32_16x16x32_bf16 v[42:45], v[152:155], v[176:179], v[42:45]
	s_waitcnt lgkmcnt(1)
	v_mfma_f32_16x16x32_bf16 v[38:41], v[134:137], v[184:187], v[38:41]
	v_mfma_f32_16x16x32_bf16 v[34:37], v[152:155], v[184:187], v[34:37]
	v_mfma_f32_16x16x32_bf16 v[192:195], v[138:141], v[74:77], v[62:65]
	v_mfma_f32_16x16x32_bf16 v[232:235], v[156:159], v[74:77], v[58:61]
	v_mfma_f32_16x16x32_bf16 v[236:239], v[138:141], v[180:183], v[46:49]
	v_mfma_f32_16x16x32_bf16 v[240:243], v[156:159], v[180:183], v[42:45]
	s_waitcnt lgkmcnt(0)
	v_mfma_f32_16x16x32_bf16 v[134:137], v[138:141], v[188:191], v[38:41]
	v_mfma_f32_16x16x32_bf16 v[138:141], v[156:159], v[188:191], v[34:37]
	s_setprio 0
	s_setprio 1
	v_mfma_f32_16x16x32_bf16 v[30:33], v[102:105], v[66:69], v[30:33]
	v_mfma_f32_16x16x32_bf16 v[26:29], v[118:121], v[66:69], v[26:29]
	v_mfma_f32_16x16x32_bf16 v[14:17], v[102:105], v[176:179], v[14:17]
	v_mfma_f32_16x16x32_bf16 v[10:13], v[118:121], v[176:179], v[10:13]
	v_mfma_f32_16x16x32_bf16 v[30:33], v[110:113], v[74:77], v[30:33]
	v_mfma_f32_16x16x32_bf16 v[26:29], v[200:203], v[74:77], v[26:29]
	v_mfma_f32_16x16x32_bf16 v[22:25], v[102:105], v[94:97], v[22:25]
	v_mfma_f32_16x16x32_bf16 v[18:21], v[118:121], v[94:97], v[18:21]
	v_mfma_f32_16x16x32_bf16 v[14:17], v[110:113], v[180:183], v[14:17]
	v_mfma_f32_16x16x32_bf16 v[10:13], v[200:203], v[180:183], v[10:13]
	v_mfma_f32_16x16x32_bf16 v[6:9], v[102:105], v[184:187], v[6:9]
	v_mfma_f32_16x16x32_bf16 v[2:5], v[118:121], v[184:187], v[2:5]
	v_mfma_f32_16x16x32_bf16 v[152:155], v[110:113], v[172:175], v[22:25]
	v_mfma_f32_16x16x32_bf16 v[156:159], v[200:203], v[172:175], v[18:21]
	v_mfma_f32_16x16x32_bf16 v[172:175], v[110:113], v[188:191], v[6:9]
	v_mfma_f32_16x16x32_bf16 v[176:179], v[200:203], v[188:191], v[2:5]
	s_setprio 0
	s_barrier
	s_nop 1
	ds_read_b128 v[2:5], v151 offset:32768
	ds_read_b128 v[6:9], v151 offset:33792
	ds_read_b128 v[180:183], v151 offset:34816
	ds_read_b128 v[184:187], v151 offset:35840
	ds_read_b128 v[18:21], v0 offset:32768
	ds_read_b128 v[22:25], v0 offset:33792
	ds_read_b128 v[38:41], v0 offset:34816
	ds_read_b128 v[46:49], v0 offset:35840
	ds_read_b128 v[58:61], v0 offset:36864
	ds_read_b128 v[66:69], v0 offset:37888
	ds_read_b128 v[188:191], v0 offset:38912
	ds_read_b128 v[200:203], v0 offset:39936
	s_waitcnt vmcnt(2)
	s_barrier
	s_waitcnt lgkmcnt(0)
	s_setprio 1
	s_waitcnt lgkmcnt(7)
	v_mfma_f32_16x16x32_bf16 v[34:37], v[2:5], v[18:21], v[126:129]
	s_waitcnt lgkmcnt(6)
	v_mfma_f32_16x16x32_bf16 v[118:121], v[6:9], v[22:25], v[34:37]
	v_mfma_f32_16x16x32_bf16 v[34:37], v[180:183], v[18:21], v[122:125]
	v_mfma_f32_16x16x32_bf16 v[110:113], v[184:187], v[22:25], v[34:37]
	s_waitcnt lgkmcnt(5)
	v_mfma_f32_16x16x32_bf16 v[34:37], v[2:5], v[38:41], v[130:133]
	s_waitcnt lgkmcnt(4)
	v_mfma_f32_16x16x32_bf16 v[102:105], v[6:9], v[46:49], v[34:37]
	v_mfma_f32_16x16x32_bf16 v[34:37], v[180:183], v[38:41], v[114:117]
	v_mfma_f32_16x16x32_bf16 v[94:97], v[184:187], v[46:49], v[34:37]
	s_waitcnt lgkmcnt(3)
	v_mfma_f32_16x16x32_bf16 v[34:37], v[2:5], v[58:61], v[160:163]
	s_waitcnt lgkmcnt(2)
	v_mfma_f32_16x16x32_bf16 v[74:77], v[6:9], v[66:69], v[34:37]
	v_mfma_f32_16x16x32_bf16 v[34:37], v[180:183], v[58:61], v[106:109]
	v_mfma_f32_16x16x32_bf16 v[62:65], v[184:187], v[66:69], v[34:37]
	s_waitcnt lgkmcnt(1)
	v_mfma_f32_16x16x32_bf16 v[34:37], v[2:5], v[188:191], v[196:199]
	s_waitcnt lgkmcnt(0)
	v_mfma_f32_16x16x32_bf16 v[42:45], v[6:9], v[200:203], v[34:37]
	v_mfma_f32_16x16x32_bf16 v[34:37], v[180:183], v[188:191], v[98:101]
	v_mfma_f32_16x16x32_bf16 v[34:37], v[184:187], v[200:203], v[34:37]
	s_setprio 0
	s_barrier
	ds_read_b128 v[130:133], v151 offset:49152
	ds_read_b128 v[160:163], v151 offset:50176
	ds_read_b128 v[196:199], v151 offset:51200
	ds_read_b128 v[148:151], v151 offset:52224
	s_waitcnt vmcnt(0)
	s_barrier
	s_waitcnt lgkmcnt(0)
	s_setprio 1
	s_waitcnt lgkmcnt(3)
	v_mfma_f32_16x16x32_bf16 v[98:101], v[130:133], v[18:21], v[222:225]
	s_waitcnt lgkmcnt(1)
	v_mfma_f32_16x16x32_bf16 v[18:21], v[196:199], v[18:21], v[90:93]
	s_waitcnt lgkmcnt(0)
	v_mfma_f32_16x16x32_bf16 v[122:125], v[148:151], v[22:25], v[18:21]
	v_mfma_f32_16x16x32_bf16 v[18:21], v[130:133], v[38:41], v[86:89]
	v_mfma_f32_16x16x32_bf16 v[114:117], v[160:163], v[46:49], v[18:21]
	v_mfma_f32_16x16x32_bf16 v[18:21], v[196:199], v[38:41], v[82:85]
	v_mfma_f32_16x16x32_bf16 v[106:109], v[148:151], v[46:49], v[18:21]
	v_mfma_f32_16x16x32_bf16 v[18:21], v[130:133], v[58:61], v[78:81]
	v_mfma_f32_16x16x32_bf16 v[126:129], v[160:163], v[22:25], v[98:101]
	v_mfma_f32_16x16x32_bf16 v[98:101], v[160:163], v[66:69], v[18:21]
	v_mfma_f32_16x16x32_bf16 v[18:21], v[196:199], v[58:61], v[164:167]
	v_mfma_f32_16x16x32_bf16 v[90:93], v[148:151], v[66:69], v[18:21]
	v_mfma_f32_16x16x32_bf16 v[18:21], v[130:133], v[188:191], v[70:73]
	v_mfma_f32_16x16x32_bf16 v[66:69], v[160:163], v[200:203], v[18:21]
	v_mfma_f32_16x16x32_bf16 v[18:21], v[196:199], v[188:191], v[168:171]
	v_mfma_f32_16x16x32_bf16 v[58:61], v[148:151], v[200:203], v[18:21]
	s_setprio 0
	s_barrier
	ds_read_b128 v[82:85], v0 offset:49152
	ds_read_b128 v[164:167], v0 offset:50176
	ds_read_b128 v[168:171], v0 offset:51200
	ds_read_b128 v[188:191], v0 offset:52224
	ds_read_b128 v[200:203], v0 offset:53248
	ds_read_b128 v[222:225], v0 offset:54272
	ds_read_b128 v[244:247], v0 offset:55296
	ds_read_b128 v[248:251], v0 offset:56320
	s_barrier
	s_waitcnt lgkmcnt(0)
	s_setprio 1
	s_waitcnt lgkmcnt(7)
	v_mfma_f32_16x16x32_bf16 v[18:21], v[2:5], v[82:85], v[192:195]
	s_waitcnt lgkmcnt(6)
	v_mfma_f32_16x16x32_bf16 v[78:81], v[6:9], v[164:167], v[18:21]
	v_mfma_f32_16x16x32_bf16 v[18:21], v[180:183], v[82:85], v[232:235]
	v_mfma_f32_16x16x32_bf16 v[70:73], v[184:187], v[164:167], v[18:21]
	s_waitcnt lgkmcnt(5)
	v_mfma_f32_16x16x32_bf16 v[18:21], v[2:5], v[168:171], v[54:57]
	s_waitcnt lgkmcnt(4)
	v_mfma_f32_16x16x32_bf16 v[46:49], v[6:9], v[188:191], v[18:21]
	v_mfma_f32_16x16x32_bf16 v[18:21], v[180:183], v[168:171], v[50:53]
	v_mfma_f32_16x16x32_bf16 v[38:41], v[184:187], v[188:191], v[18:21]
	s_waitcnt lgkmcnt(3)
	v_mfma_f32_16x16x32_bf16 v[18:21], v[2:5], v[200:203], v[236:239]
	s_waitcnt lgkmcnt(1)
	v_mfma_f32_16x16x32_bf16 v[2:5], v[2:5], v[244:247], v[134:137]
	v_mfma_f32_16x16x32_bf16 v[22:25], v[6:9], v[222:225], v[18:21]
	v_mfma_f32_16x16x32_bf16 v[18:21], v[180:183], v[200:203], v[240:243]
	s_waitcnt lgkmcnt(0)
	v_mfma_f32_16x16x32_bf16 v[6:9], v[6:9], v[248:251], v[2:5]
	v_mfma_f32_16x16x32_bf16 v[2:5], v[180:183], v[244:247], v[138:141]
	v_mfma_f32_16x16x32_bf16 v[18:21], v[184:187], v[222:225], v[18:21]
	v_mfma_f32_16x16x32_bf16 v[2:5], v[184:187], v[248:251], v[2:5]
	s_setprio 0
	s_setprio 1
	v_mfma_f32_16x16x32_bf16 v[26:29], v[196:199], v[82:85], v[26:29]
	v_mfma_f32_16x16x32_bf16 v[30:33], v[130:133], v[82:85], v[30:33]
	v_mfma_f32_16x16x32_bf16 v[82:85], v[148:151], v[164:167], v[26:29]
	v_mfma_f32_16x16x32_bf16 v[26:29], v[130:133], v[168:171], v[152:155]
	v_mfma_f32_16x16x32_bf16 v[54:57], v[160:163], v[188:191], v[26:29]
	v_mfma_f32_16x16x32_bf16 v[26:29], v[196:199], v[168:171], v[156:159]
	v_mfma_f32_16x16x32_bf16 v[10:13], v[196:199], v[200:203], v[10:13]
	v_mfma_f32_16x16x32_bf16 v[50:53], v[148:151], v[188:191], v[26:29]
	v_mfma_f32_16x16x32_bf16 v[14:17], v[130:133], v[200:203], v[14:17]
	v_mfma_f32_16x16x32_bf16 v[26:29], v[148:151], v[222:225], v[10:13]
	v_mfma_f32_16x16x32_bf16 v[10:13], v[130:133], v[244:247], v[172:175]
	v_mfma_f32_16x16x32_bf16 v[86:89], v[160:163], v[164:167], v[30:33]
	v_mfma_f32_16x16x32_bf16 v[30:33], v[160:163], v[222:225], v[14:17]
	v_mfma_f32_16x16x32_bf16 v[14:17], v[160:163], v[248:251], v[10:13]
	v_mfma_f32_16x16x32_bf16 v[10:13], v[196:199], v[244:247], v[176:179]
	v_mfma_f32_16x16x32_bf16 v[10:13], v[148:151], v[248:251], v[10:13]
	s_setprio 0
	s_movk_i32 s0, 0x100
	v_cmp_gt_u32_e32 vcc, s0, v142
	s_barrier
	s_and_saveexec_b64 s[0:1], vcc
	s_cbranch_execz .LBB0_674
	s_barrier
	s_branch .LBB0_674

.LBB0_689:
	v_add_u32_e32 v101, 0xc000, v85
	v_lshl_add_u64 v[152:153], v[72:73], 0, s[10:11]
	v_readfirstlane_b32 s1, v101
	v_lshl_add_u64 v[102:103], v[152:153], 0, s[34:35]
	s_mov_b32 m0, s1
	global_load_lds_dwordx4 v[102:103], off
	v_add_u32_e32 v102, 0xe000, v85
	v_lshl_add_u64 v[154:155], v[74:75], 0, s[10:11]
	v_readfirstlane_b32 s1, v102
	v_lshl_add_u64 v[156:157], v[154:155], 0, s[34:35]
	s_mov_b32 m0, s1
	s_nop 0
	global_load_lds_dwordx4 v[156:157], off
	ds_read_b128 v[104:107], v95
	ds_read_b128 v[108:111], v95 offset:1024
	ds_read_b128 v[112:115], v95 offset:2048
	ds_read_b128 v[116:119], v95 offset:3072
	ds_read_b128 v[120:123], v93
	ds_read_b128 v[124:127], v93 offset:1024
	ds_read_b128 v[128:131], v93 offset:2048
	ds_read_b128 v[132:135], v93 offset:3072
	ds_read_b128 v[136:139], v93 offset:4096
	ds_read_b128 v[140:143], v93 offset:5120
	ds_read_b128 v[144:147], v93 offset:6144
	ds_read_b128 v[148:151], v93 offset:7168
	s_waitcnt lgkmcnt(8)
	s_barrier
	s_waitcnt lgkmcnt(0)
	s_setprio 1
	s_waitcnt lgkmcnt(0)
	v_mfma_f32_16x16x32_bf16 v[62:65], v[104:107], v[120:123], v[62:65]
	v_mfma_f32_16x16x32_bf16 v[58:61], v[112:115], v[120:123], v[58:61]
	v_mfma_f32_16x16x32_bf16 v[54:57], v[104:107], v[128:131], v[54:57]
	v_mfma_f32_16x16x32_bf16 v[50:53], v[112:115], v[128:131], v[50:53]
	v_mfma_f32_16x16x32_bf16 v[46:49], v[104:107], v[136:139], v[46:49]
	v_mfma_f32_16x16x32_bf16 v[42:45], v[112:115], v[136:139], v[42:45]
	v_mfma_f32_16x16x32_bf16 v[38:41], v[104:107], v[144:147], v[38:41]
	v_mfma_f32_16x16x32_bf16 v[34:37], v[112:115], v[144:147], v[34:37]
	v_mfma_f32_16x16x32_bf16 v[62:65], v[108:111], v[124:127], v[62:65]
	v_mfma_f32_16x16x32_bf16 v[58:61], v[116:119], v[124:127], v[58:61]
	v_mfma_f32_16x16x32_bf16 v[54:57], v[108:111], v[132:135], v[54:57]
	v_mfma_f32_16x16x32_bf16 v[50:53], v[116:119], v[132:135], v[50:53]
	v_mfma_f32_16x16x32_bf16 v[46:49], v[108:111], v[140:143], v[46:49]
	v_mfma_f32_16x16x32_bf16 v[42:45], v[116:119], v[140:143], v[42:45]
	v_mfma_f32_16x16x32_bf16 v[38:41], v[108:111], v[148:151], v[38:41]
	v_mfma_f32_16x16x32_bf16 v[34:37], v[116:119], v[148:151], v[34:37]
	s_setprio 0
	s_barrier
	v_lshl_add_u64 v[156:157], v[68:69], 0, s[10:11]
	v_readfirstlane_b32 s1, v87
	v_lshl_add_u64 v[120:121], v[156:157], 0, s[74:75]
	s_mov_b32 m0, s1
	v_lshl_add_u64 v[158:159], v[70:71], 0, s[10:11]
	v_readfirstlane_b32 s1, v88
	global_load_lds_dwordx4 v[120:121], off
	v_lshl_add_u64 v[120:121], v[158:159], 0, s[74:75]
	s_mov_b32 m0, s1
	v_readfirstlane_b32 s1, v85
	global_load_lds_dwordx4 v[120:121], off
	v_lshl_add_u64 v[160:161], v[152:153], 0, s[74:75]
	s_mov_b32 m0, s1
	v_readfirstlane_b32 s1, v86
	s_barrier
	s_waitcnt lgkmcnt(0)
	s_barrier
	global_load_lds_dwordx4 v[160:161], off
	v_lshl_add_u64 v[160:161], v[154:155], 0, s[74:75]
	s_mov_b32 m0, s1
	s_nop 0
	global_load_lds_dwordx4 v[160:161], off
	ds_read_b128 v[120:123], v93 offset:16384
	ds_read_b128 v[124:127], v93 offset:17408
	ds_read_b128 v[128:131], v93 offset:18432
	ds_read_b128 v[132:135], v93 offset:19456
	ds_read_b128 v[136:139], v93 offset:20480
	ds_read_b128 v[140:143], v93 offset:21504
	ds_read_b128 v[144:147], v93 offset:22528
	ds_read_b128 v[148:151], v93 offset:23552
	s_barrier
	s_waitcnt lgkmcnt(0)
	s_setprio 1
	s_waitcnt lgkmcnt(0)
	v_mfma_f32_16x16x32_bf16 v[2:5], v[104:107], v[120:123], v[2:5]
	v_mfma_f32_16x16x32_bf16 v[6:9], v[112:115], v[120:123], v[6:9]
	v_mfma_f32_16x16x32_bf16 v[10:13], v[104:107], v[128:131], v[10:13]
	v_mfma_f32_16x16x32_bf16 v[14:17], v[112:115], v[128:131], v[14:17]
	v_mfma_f32_16x16x32_bf16 v[18:21], v[104:107], v[136:139], v[18:21]
	v_mfma_f32_16x16x32_bf16 v[22:25], v[112:115], v[136:139], v[22:25]
	v_mfma_f32_16x16x32_bf16 v[26:29], v[104:107], v[144:147], v[26:29]
	v_mfma_f32_16x16x32_bf16 v[30:33], v[112:115], v[144:147], v[30:33]
	v_mfma_f32_16x16x32_bf16 v[2:5], v[108:111], v[124:127], v[2:5]
	v_mfma_f32_16x16x32_bf16 v[6:9], v[116:119], v[124:127], v[6:9]
	v_mfma_f32_16x16x32_bf16 v[10:13], v[108:111], v[132:135], v[10:13]
	v_mfma_f32_16x16x32_bf16 v[14:17], v[116:119], v[132:135], v[14:17]
	v_mfma_f32_16x16x32_bf16 v[18:21], v[108:111], v[140:143], v[18:21]
	v_mfma_f32_16x16x32_bf16 v[22:25], v[116:119], v[140:143], v[22:25]
	v_mfma_f32_16x16x32_bf16 v[26:29], v[108:111], v[148:151], v[26:29]
	v_mfma_f32_16x16x32_bf16 v[30:33], v[116:119], v[148:151], v[30:33]
	s_setprio 0
	s_barrier
	v_lshl_add_u64 v[160:161], v[76:77], 0, s[10:11]
	v_readfirstlane_b32 s1, v89
	v_lshl_add_u64 v[104:105], v[160:161], 0, s[74:75]
	s_mov_b32 m0, s1
	v_lshl_add_u64 v[162:163], v[78:79], 0, s[10:11]
	v_readfirstlane_b32 s1, v90
	global_load_lds_dwordx4 v[104:105], off
	v_lshl_add_u64 v[104:105], v[162:163], 0, s[74:75]
	s_mov_b32 m0, s1
	s_nop 0
	global_load_lds_dwordx4 v[104:105], off
	s_waitcnt vmcnt(6)
	s_barrier
	s_barrier
	v_readfirstlane_b32 s1, v91
	v_lshl_add_u64 v[164:165], v[152:153], 0, s[78:79]
	s_mov_b32 m0, s1
	v_readfirstlane_b32 s1, v92
	global_load_lds_dwordx4 v[164:165], off
	v_lshl_add_u64 v[164:165], v[154:155], 0, s[78:79]
	s_mov_b32 m0, s1
	s_nop 0
	global_load_lds_dwordx4 v[164:165], off
	ds_read_b128 v[104:107], v95 offset:32768
	ds_read_b128 v[108:111], v95 offset:33792
	ds_read_b128 v[112:115], v95 offset:34816
	ds_read_b128 v[116:119], v95 offset:35840
	ds_read_b128 v[120:123], v93 offset:32768
	ds_read_b128 v[124:127], v93 offset:33792
	ds_read_b128 v[128:131], v93 offset:34816
	ds_read_b128 v[132:135], v93 offset:35840
	ds_read_b128 v[136:139], v93 offset:36864
	ds_read_b128 v[140:143], v93 offset:37888
	ds_read_b128 v[144:147], v93 offset:38912
	ds_read_b128 v[148:151], v93 offset:39936
	s_waitcnt lgkmcnt(8)
	s_barrier
	s_waitcnt lgkmcnt(0)
	s_setprio 1
	s_waitcnt lgkmcnt(0)
	v_mfma_f32_16x16x32_bf16 v[62:65], v[104:107], v[120:123], v[62:65]
	v_mfma_f32_16x16x32_bf16 v[58:61], v[112:115], v[120:123], v[58:61]
	v_mfma_f32_16x16x32_bf16 v[54:57], v[104:107], v[128:131], v[54:57]
	v_mfma_f32_16x16x32_bf16 v[50:53], v[112:115], v[128:131], v[50:53]
	v_mfma_f32_16x16x32_bf16 v[46:49], v[104:107], v[136:139], v[46:49]
	v_mfma_f32_16x16x32_bf16 v[42:45], v[112:115], v[136:139], v[42:45]
	v_mfma_f32_16x16x32_bf16 v[38:41], v[104:107], v[144:147], v[38:41]
	v_mfma_f32_16x16x32_bf16 v[34:37], v[112:115], v[144:147], v[34:37]
	v_mfma_f32_16x16x32_bf16 v[62:65], v[108:111], v[124:127], v[62:65]
	v_mfma_f32_16x16x32_bf16 v[58:61], v[116:119], v[124:127], v[58:61]
	v_mfma_f32_16x16x32_bf16 v[54:57], v[108:111], v[132:135], v[54:57]
	v_mfma_f32_16x16x32_bf16 v[50:53], v[116:119], v[132:135], v[50:53]
	v_mfma_f32_16x16x32_bf16 v[46:49], v[108:111], v[140:143], v[46:49]
	v_mfma_f32_16x16x32_bf16 v[42:45], v[116:119], v[140:143], v[42:45]
	v_mfma_f32_16x16x32_bf16 v[38:41], v[108:111], v[148:151], v[38:41]
	v_mfma_f32_16x16x32_bf16 v[34:37], v[116:119], v[148:151], v[34:37]
	s_setprio 0
	s_barrier
	v_readfirstlane_b32 s1, v94
	v_lshl_add_u64 v[120:121], v[156:157], 0, s[28:29]
	s_mov_b32 m0, s1
	v_readfirstlane_b32 s1, v96
	global_load_lds_dwordx4 v[120:121], off
	v_lshl_add_u64 v[120:121], v[158:159], 0, s[28:29]
	s_mov_b32 m0, s1
	v_readfirstlane_b32 s1, v97
	global_load_lds_dwordx4 v[120:121], off
	v_lshl_add_u64 v[152:153], v[152:153], 0, s[28:29]
	s_mov_b32 m0, s1
	v_readfirstlane_b32 s1, v98
	s_barrier
	s_waitcnt lgkmcnt(0)
	s_barrier
	global_load_lds_dwordx4 v[152:153], off
	v_lshl_add_u64 v[152:153], v[154:155], 0, s[28:29]
	s_mov_b32 m0, s1
	s_nop 0
	global_load_lds_dwordx4 v[152:153], off
	ds_read_b128 v[120:123], v93 offset:49152
	ds_read_b128 v[124:127], v93 offset:50176
	ds_read_b128 v[128:131], v93 offset:51200
	ds_read_b128 v[132:135], v93 offset:52224
	ds_read_b128 v[136:139], v93 offset:53248
	ds_read_b128 v[140:143], v93 offset:54272
	ds_read_b128 v[144:147], v93 offset:55296
	ds_read_b128 v[148:151], v93 offset:56320
	s_barrier
	s_waitcnt lgkmcnt(0)
	s_setprio 1
	s_waitcnt lgkmcnt(0)
	v_mfma_f32_16x16x32_bf16 v[2:5], v[104:107], v[120:123], v[2:5]
	v_mfma_f32_16x16x32_bf16 v[6:9], v[112:115], v[120:123], v[6:9]
	v_mfma_f32_16x16x32_bf16 v[10:13], v[104:107], v[128:131], v[10:13]
	v_mfma_f32_16x16x32_bf16 v[14:17], v[112:115], v[128:131], v[14:17]
	v_mfma_f32_16x16x32_bf16 v[18:21], v[104:107], v[136:139], v[18:21]
	v_mfma_f32_16x16x32_bf16 v[22:25], v[112:115], v[136:139], v[22:25]
	v_mfma_f32_16x16x32_bf16 v[26:29], v[104:107], v[144:147], v[26:29]
	v_mfma_f32_16x16x32_bf16 v[30:33], v[112:115], v[144:147], v[30:33]
	v_mfma_f32_16x16x32_bf16 v[2:5], v[108:111], v[124:127], v[2:5]
	v_mfma_f32_16x16x32_bf16 v[6:9], v[116:119], v[124:127], v[6:9]
	v_mfma_f32_16x16x32_bf16 v[10:13], v[108:111], v[132:135], v[10:13]
	v_mfma_f32_16x16x32_bf16 v[14:17], v[116:119], v[132:135], v[14:17]
	v_mfma_f32_16x16x32_bf16 v[18:21], v[108:111], v[140:143], v[18:21]
	v_mfma_f32_16x16x32_bf16 v[22:25], v[116:119], v[140:143], v[22:25]
	v_mfma_f32_16x16x32_bf16 v[26:29], v[108:111], v[148:151], v[26:29]
	v_mfma_f32_16x16x32_bf16 v[30:33], v[116:119], v[148:151], v[30:33]
	s_setprio 0
	s_barrier
	v_readfirstlane_b32 s1, v99
	v_lshl_add_u64 v[104:105], v[160:161], 0, s[28:29]
	s_mov_b32 m0, s1
	v_readfirstlane_b32 s1, v100
	global_load_lds_dwordx4 v[104:105], off
	v_lshl_add_u64 v[104:105], v[162:163], 0, s[28:29]
	s_mov_b32 m0, s1
	s_add_i32 s0, s0, 2
	global_load_lds_dwordx4 v[104:105], off
	s_waitcnt vmcnt(6)
	s_add_u32 s10, s10, 0x100
	s_addc_u32 s11, s11, 0
	s_cmpk_lt_u32 s0, 0x54
	s_barrier
	s_barrier
	s_cbranch_scc1 .LBB0_689
	s_add_u32 s0, s8, 0x2b80
	s_addc_u32 s1, s9, 0
	v_readfirstlane_b32 s8, v101
	v_lshl_add_u64 v[90:91], s[0:1], 0, v[0:1]
	s_mov_b32 m0, s8
	v_lshl_add_u64 v[66:67], s[0:1], 0, v[66:67]
	v_readfirstlane_b32 s0, v102
	ds_read_b128 v[68:71], v95
	ds_read_b128 v[72:75], v95 offset:1024
	ds_read_b128 v[76:79], v95 offset:2048
	ds_read_b128 v[86:89], v95 offset:3072
	ds_read_b128 v[96:99], v93
	ds_read_b128 v[104:107], v93 offset:1024
	ds_read_b128 v[108:111], v93 offset:2048
	ds_read_b128 v[112:115], v93 offset:3072
	ds_read_b128 v[116:119], v93 offset:4096
	ds_read_b128 v[120:123], v93 offset:5120
	ds_read_b128 v[124:127], v93 offset:6144
	ds_read_b128 v[128:131], v93 offset:7168
	global_load_lds_dwordx4 v[90:91], off
	s_mov_b32 m0, s0
	s_nop 0
	global_load_lds_dwordx4 v[66:67], off
	s_barrier
	s_waitcnt lgkmcnt(0)
	s_setprio 1
	s_waitcnt lgkmcnt(0)
	v_mfma_f32_16x16x32_bf16 v[62:65], v[68:71], v[96:99], v[62:65]
	v_mfma_f32_16x16x32_bf16 v[58:61], v[76:79], v[96:99], v[58:61]
	v_mfma_f32_16x16x32_bf16 v[54:57], v[68:71], v[108:111], v[54:57]
	v_mfma_f32_16x16x32_bf16 v[50:53], v[76:79], v[108:111], v[50:53]
	v_mfma_f32_16x16x32_bf16 v[46:49], v[68:71], v[116:119], v[46:49]
	v_mfma_f32_16x16x32_bf16 v[42:45], v[76:79], v[116:119], v[42:45]
	v_mfma_f32_16x16x32_bf16 v[38:41], v[68:71], v[124:127], v[38:41]
	v_mfma_f32_16x16x32_bf16 v[34:37], v[76:79], v[124:127], v[34:37]
	v_mfma_f32_16x16x32_bf16 v[62:65], v[72:75], v[104:107], v[62:65]
	v_mfma_f32_16x16x32_bf16 v[58:61], v[86:89], v[104:107], v[58:61]
	v_mfma_f32_16x16x32_bf16 v[54:57], v[72:75], v[112:115], v[54:57]
	v_mfma_f32_16x16x32_bf16 v[50:53], v[86:89], v[112:115], v[50:53]
	v_mfma_f32_16x16x32_bf16 v[46:49], v[72:75], v[120:123], v[46:49]
	v_mfma_f32_16x16x32_bf16 v[42:45], v[86:89], v[120:123], v[42:45]
	v_mfma_f32_16x16x32_bf16 v[38:41], v[72:75], v[128:131], v[38:41]
	v_mfma_f32_16x16x32_bf16 v[34:37], v[86:89], v[128:131], v[34:37]
	s_setprio 0
	s_barrier
	s_barrier
	s_waitcnt lgkmcnt(0)
	s_barrier
	ds_read_b128 v[96:99], v93 offset:16384
	ds_read_b128 v[100:103], v93 offset:17408
	ds_read_b128 v[104:107], v93 offset:18432
	ds_read_b128 v[108:111], v93 offset:19456
	ds_read_b128 v[112:115], v93 offset:20480
	ds_read_b128 v[116:119], v93 offset:21504
	ds_read_b128 v[120:123], v93 offset:22528
	ds_read_b128 v[124:127], v93 offset:23552
	s_waitcnt vmcnt(4)
	s_barrier
	s_waitcnt lgkmcnt(0)
	s_setprio 1
	s_waitcnt lgkmcnt(3)
	v_mfma_f32_16x16x32_bf16 v[18:21], v[68:71], v[112:115], v[18:21]
	v_mfma_f32_16x16x32_bf16 v[2:5], v[68:71], v[96:99], v[2:5]
	v_mfma_f32_16x16x32_bf16 v[6:9], v[76:79], v[96:99], v[6:9]
	s_waitcnt lgkmcnt(2)
	v_mfma_f32_16x16x32_bf16 v[96:99], v[72:75], v[116:119], v[18:21]
	v_mfma_f32_16x16x32_bf16 v[18:21], v[76:79], v[112:115], v[22:25]
	v_mfma_f32_16x16x32_bf16 v[2:5], v[72:75], v[100:103], v[2:5]
	v_mfma_f32_16x16x32_bf16 v[6:9], v[86:89], v[100:103], v[6:9]
	v_mfma_f32_16x16x32_bf16 v[10:13], v[68:71], v[104:107], v[10:13]
	v_mfma_f32_16x16x32_bf16 v[14:17], v[76:79], v[104:107], v[14:17]
	v_mfma_f32_16x16x32_bf16 v[100:103], v[86:89], v[116:119], v[18:21]
	s_waitcnt lgkmcnt(1)
	v_mfma_f32_16x16x32_bf16 v[18:21], v[68:71], v[120:123], v[26:29]
	v_mfma_f32_16x16x32_bf16 v[10:13], v[72:75], v[108:111], v[10:13]
	v_mfma_f32_16x16x32_bf16 v[14:17], v[86:89], v[108:111], v[14:17]
	s_waitcnt lgkmcnt(0)
	v_mfma_f32_16x16x32_bf16 v[66:69], v[72:75], v[124:127], v[18:21]
	v_mfma_f32_16x16x32_bf16 v[18:21], v[76:79], v[120:123], v[30:33]
	v_mfma_f32_16x16x32_bf16 v[70:73], v[86:89], v[124:127], v[18:21]
	s_setprio 0
	s_barrier
	ds_read_b128 v[74:77], v95 offset:32768
	ds_read_b128 v[86:89], v95 offset:33792
	ds_read_b128 v[104:107], v95 offset:34816
	ds_read_b128 v[108:111], v95 offset:35840
	s_nop 0
	ds_read_b128 v[18:21], v93 offset:32768
	ds_read_b128 v[22:25], v93 offset:33792
	ds_read_b128 v[26:29], v93 offset:34816
	ds_read_b128 v[30:33], v93 offset:35840
	ds_read_b128 v[112:115], v93 offset:36864
	ds_read_b128 v[116:119], v93 offset:37888
	ds_read_b128 v[120:123], v93 offset:38912
	ds_read_b128 v[124:127], v93 offset:39936
	s_waitcnt vmcnt(2)
	s_barrier
	s_waitcnt lgkmcnt(0)
	s_setprio 1
	s_waitcnt lgkmcnt(7)
	v_mfma_f32_16x16x32_bf16 v[62:65], v[74:77], v[18:21], v[62:65]
	v_mfma_f32_16x16x32_bf16 v[18:21], v[104:107], v[18:21], v[58:61]
	s_waitcnt lgkmcnt(6)
	v_mfma_f32_16x16x32_bf16 v[58:61], v[108:111], v[22:25], v[18:21]
	s_waitcnt lgkmcnt(5)
	v_mfma_f32_16x16x32_bf16 v[18:21], v[74:77], v[26:29], v[54:57]
	s_waitcnt lgkmcnt(4)
	v_mfma_f32_16x16x32_bf16 v[54:57], v[86:89], v[30:33], v[18:21]
	v_mfma_f32_16x16x32_bf16 v[18:21], v[104:107], v[26:29], v[50:53]
	v_mfma_f32_16x16x32_bf16 v[50:53], v[108:111], v[30:33], v[18:21]
	s_waitcnt lgkmcnt(3)
	v_mfma_f32_16x16x32_bf16 v[18:21], v[74:77], v[112:115], v[46:49]
	s_waitcnt lgkmcnt(2)
	v_mfma_f32_16x16x32_bf16 v[46:49], v[86:89], v[116:119], v[18:21]
	v_mfma_f32_16x16x32_bf16 v[18:21], v[104:107], v[112:115], v[42:45]
	v_mfma_f32_16x16x32_bf16 v[42:45], v[108:111], v[116:119], v[18:21]
	s_waitcnt lgkmcnt(1)
	v_mfma_f32_16x16x32_bf16 v[18:21], v[74:77], v[120:123], v[38:41]
	s_waitcnt lgkmcnt(0)
	v_mfma_f32_16x16x32_bf16 v[38:41], v[86:89], v[124:127], v[18:21]
	v_mfma_f32_16x16x32_bf16 v[18:21], v[104:107], v[120:123], v[34:37]
	v_mfma_f32_16x16x32_bf16 v[62:65], v[86:89], v[22:25], v[62:65]
	v_mfma_f32_16x16x32_bf16 v[34:37], v[108:111], v[124:127], v[18:21]
	s_setprio 0
	s_barrier
	s_waitcnt vmcnt(0)
	s_barrier
	s_waitcnt lgkmcnt(0)
	s_barrier
	s_nop 1
	ds_read_b128 v[18:21], v93 offset:49152
	ds_read_b128 v[22:25], v93 offset:50176
	ds_read_b128 v[112:115], v93 offset:51200
	ds_read_b128 v[116:119], v93 offset:52224
	ds_read_b128 v[120:123], v93 offset:53248
	ds_read_b128 v[124:127], v93 offset:54272
	ds_read_b128 v[128:131], v93 offset:55296
	ds_read_b128 v[90:93], v93 offset:56320
	s_barrier
	s_waitcnt lgkmcnt(0)
	s_setprio 1
	s_waitcnt lgkmcnt(7)
	v_mfma_f32_16x16x32_bf16 v[2:5], v[74:77], v[18:21], v[2:5]
	s_waitcnt lgkmcnt(6)
	v_mfma_f32_16x16x32_bf16 v[30:33], v[86:89], v[22:25], v[2:5]
	v_mfma_f32_16x16x32_bf16 v[2:5], v[104:107], v[18:21], v[6:9]
	v_mfma_f32_16x16x32_bf16 v[26:29], v[108:111], v[22:25], v[2:5]
	s_waitcnt lgkmcnt(5)
	v_mfma_f32_16x16x32_bf16 v[2:5], v[74:77], v[112:115], v[10:13]
	s_waitcnt lgkmcnt(4)
	v_mfma_f32_16x16x32_bf16 v[22:25], v[86:89], v[116:119], v[2:5]
	v_mfma_f32_16x16x32_bf16 v[2:5], v[104:107], v[112:115], v[14:17]
	v_mfma_f32_16x16x32_bf16 v[18:21], v[108:111], v[116:119], v[2:5]
	s_waitcnt lgkmcnt(3)
	v_mfma_f32_16x16x32_bf16 v[2:5], v[74:77], v[120:123], v[96:99]
	s_waitcnt lgkmcnt(2)
	v_mfma_f32_16x16x32_bf16 v[14:17], v[86:89], v[124:127], v[2:5]
	v_mfma_f32_16x16x32_bf16 v[2:5], v[104:107], v[120:123], v[100:103]
	v_mfma_f32_16x16x32_bf16 v[10:13], v[108:111], v[124:127], v[2:5]
	s_waitcnt lgkmcnt(1)
	v_mfma_f32_16x16x32_bf16 v[2:5], v[74:77], v[128:131], v[66:69]
	s_waitcnt lgkmcnt(0)
	v_mfma_f32_16x16x32_bf16 v[6:9], v[86:89], v[90:93], v[2:5]
	v_mfma_f32_16x16x32_bf16 v[2:5], v[104:107], v[128:131], v[70:73]
	v_mfma_f32_16x16x32_bf16 v[2:5], v[108:111], v[90:93], v[2:5]
	s_setprio 0
	s_movk_i32 s0, 0x100
	v_cmp_gt_u32_e32 vcc, s0, v80
	s_barrier
	s_and_saveexec_b64 s[0:1], vcc
	s_cbranch_execz .LBB0_692
	s_barrier

.LBB0_761:
	v_add_u32_e32 v161, 0xc000, v145
	v_lshl_add_u64 v[204:205], v[136:137], 0, s[10:11]
	v_readfirstlane_b32 s1, v161
	v_lshl_add_u64 v[162:163], v[204:205], 0, s[34:35]
	s_mov_b32 m0, s1
	global_load_lds_dwordx4 v[162:163], off
	v_add_u32_e32 v162, 0xe000, v145
	v_lshl_add_u64 v[210:211], v[138:139], 0, s[10:11]
	v_readfirstlane_b32 s1, v162
	v_lshl_add_u64 v[216:217], v[210:211], 0, s[34:35]
	s_mov_b32 m0, s1
	s_nop 0
	global_load_lds_dwordx4 v[216:217], off
	ds_read_b128 v[164:167], v148
	ds_read_b128 v[168:171], v148 offset:1024
	ds_read_b128 v[172:175], v148 offset:2048
	ds_read_b128 v[176:179], v148 offset:3072
	ds_read_b128 v[180:183], v147
	ds_read_b128 v[184:187], v147 offset:1024
	ds_read_b128 v[188:191], v147 offset:2048
	ds_read_b128 v[192:195], v147 offset:3072
	ds_read_b128 v[196:199], v147 offset:4096
	ds_read_b128 v[200:203], v147 offset:5120
	ds_read_b128 v[222:225], v147 offset:6144
	ds_read_b128 v[232:235], v147 offset:7168
	s_waitcnt lgkmcnt(8)
	s_barrier
	s_waitcnt lgkmcnt(0)
	s_setprio 1
	s_waitcnt lgkmcnt(0)
	v_mfma_f32_16x16x32_bf16 v[126:129], v[164:167], v[180:183], v[126:129]
	v_mfma_f32_16x16x32_bf16 v[122:125], v[172:175], v[180:183], v[122:125]
	v_mfma_f32_16x16x32_bf16 v[118:121], v[164:167], v[188:191], v[118:121]
	v_mfma_f32_16x16x32_bf16 v[114:117], v[172:175], v[188:191], v[114:117]
	v_mfma_f32_16x16x32_bf16 v[110:113], v[164:167], v[196:199], v[110:113]
	v_mfma_f32_16x16x32_bf16 v[106:109], v[172:175], v[196:199], v[106:109]
	v_mfma_f32_16x16x32_bf16 v[102:105], v[164:167], v[222:225], v[102:105]
	v_mfma_f32_16x16x32_bf16 v[98:101], v[172:175], v[222:225], v[98:101]
	v_mfma_f32_16x16x32_bf16 v[126:129], v[168:171], v[184:187], v[126:129]
	v_mfma_f32_16x16x32_bf16 v[122:125], v[176:179], v[184:187], v[122:125]
	v_mfma_f32_16x16x32_bf16 v[118:121], v[168:171], v[192:195], v[118:121]
	v_mfma_f32_16x16x32_bf16 v[114:117], v[176:179], v[192:195], v[114:117]
	v_mfma_f32_16x16x32_bf16 v[110:113], v[168:171], v[200:203], v[110:113]
	v_mfma_f32_16x16x32_bf16 v[106:109], v[176:179], v[200:203], v[106:109]
	v_mfma_f32_16x16x32_bf16 v[102:105], v[168:171], v[232:235], v[102:105]
	v_mfma_f32_16x16x32_bf16 v[98:101], v[176:179], v[232:235], v[98:101]
	s_setprio 0
	s_barrier
	v_lshl_add_u64 v[216:217], v[132:133], 0, s[10:11]
	v_readfirstlane_b32 s1, v149
	v_lshl_add_u64 v[218:219], v[216:217], 0, s[74:75]
	s_mov_b32 m0, s1
	global_load_lds_dwordx4 v[218:219], off
	v_lshl_add_u64 v[218:219], v[134:135], 0, s[10:11]
	v_readfirstlane_b32 s1, v150
	v_lshl_add_u64 v[228:229], v[218:219], 0, s[74:75]
	s_mov_b32 m0, s1
	s_nop 0
	global_load_lds_dwordx4 v[228:229], off
	ds_read_b128 v[236:239], v148 offset:16384
	ds_read_b128 v[240:243], v148 offset:17408
	ds_read_b128 v[244:247], v148 offset:18432
	ds_read_b128 v[248:251], v148 offset:19456
	s_barrier
	s_waitcnt lgkmcnt(0)
	s_setprio 1
	s_waitcnt lgkmcnt(0)
	v_mfma_f32_16x16x32_bf16 v[94:97], v[236:239], v[180:183], v[94:97]
	v_mfma_f32_16x16x32_bf16 v[90:93], v[244:247], v[180:183], v[90:93]
	v_mfma_f32_16x16x32_bf16 v[86:89], v[236:239], v[188:191], v[86:89]
	v_mfma_f32_16x16x32_bf16 v[82:85], v[244:247], v[188:191], v[82:85]
	v_mfma_f32_16x16x32_bf16 v[78:81], v[236:239], v[196:199], v[78:81]
	v_mfma_f32_16x16x32_bf16 v[74:77], v[244:247], v[196:199], v[74:77]
	v_mfma_f32_16x16x32_bf16 v[70:73], v[236:239], v[222:225], v[70:73]
	v_mfma_f32_16x16x32_bf16 v[66:69], v[244:247], v[222:225], v[66:69]
	v_mfma_f32_16x16x32_bf16 v[94:97], v[240:243], v[184:187], v[94:97]
	v_mfma_f32_16x16x32_bf16 v[90:93], v[248:251], v[184:187], v[90:93]
	v_mfma_f32_16x16x32_bf16 v[86:89], v[240:243], v[192:195], v[86:89]
	v_mfma_f32_16x16x32_bf16 v[82:85], v[248:251], v[192:195], v[82:85]
	v_mfma_f32_16x16x32_bf16 v[78:81], v[240:243], v[200:203], v[78:81]
	v_mfma_f32_16x16x32_bf16 v[74:77], v[248:251], v[200:203], v[74:77]
	v_mfma_f32_16x16x32_bf16 v[70:73], v[240:243], v[232:235], v[70:73]
	v_mfma_f32_16x16x32_bf16 v[66:69], v[248:251], v[232:235], v[66:69]
	s_setprio 0
	v_readfirstlane_b32 s1, v145
	v_lshl_add_u64 v[228:229], v[204:205], 0, s[74:75]
	s_mov_b32 m0, s1
	v_readfirstlane_b32 s1, v146
	s_barrier
	global_load_lds_dwordx4 v[228:229], off
	v_lshl_add_u64 v[228:229], v[210:211], 0, s[74:75]
	s_mov_b32 m0, s1
	s_nop 0
	global_load_lds_dwordx4 v[228:229], off
	ds_read_b128 v[180:183], v147 offset:16384
	ds_read_b128 v[184:187], v147 offset:17408
	ds_read_b128 v[188:191], v147 offset:18432
	ds_read_b128 v[192:195], v147 offset:19456
	ds_read_b128 v[196:199], v147 offset:20480
	ds_read_b128 v[200:203], v147 offset:21504
	ds_read_b128 v[222:225], v147 offset:22528
	ds_read_b128 v[232:235], v147 offset:23552
	s_barrier
	s_waitcnt lgkmcnt(0)
	s_setprio 1
	s_waitcnt lgkmcnt(0)
	v_mfma_f32_16x16x32_bf16 v[62:65], v[164:167], v[180:183], v[62:65]
	v_mfma_f32_16x16x32_bf16 v[58:61], v[172:175], v[180:183], v[58:61]
	v_mfma_f32_16x16x32_bf16 v[54:57], v[164:167], v[188:191], v[54:57]
	v_mfma_f32_16x16x32_bf16 v[50:53], v[172:175], v[188:191], v[50:53]
	v_mfma_f32_16x16x32_bf16 v[46:49], v[164:167], v[196:199], v[46:49]
	v_mfma_f32_16x16x32_bf16 v[42:45], v[172:175], v[196:199], v[42:45]
	v_mfma_f32_16x16x32_bf16 v[38:41], v[164:167], v[222:225], v[38:41]
	v_mfma_f32_16x16x32_bf16 v[34:37], v[172:175], v[222:225], v[34:37]
	v_mfma_f32_16x16x32_bf16 v[62:65], v[168:171], v[184:187], v[62:65]
	v_mfma_f32_16x16x32_bf16 v[58:61], v[176:179], v[184:187], v[58:61]
	v_mfma_f32_16x16x32_bf16 v[54:57], v[168:171], v[192:195], v[54:57]
	v_mfma_f32_16x16x32_bf16 v[50:53], v[176:179], v[192:195], v[50:53]
	v_mfma_f32_16x16x32_bf16 v[46:49], v[168:171], v[200:203], v[46:49]
	v_mfma_f32_16x16x32_bf16 v[42:45], v[176:179], v[200:203], v[42:45]
	v_mfma_f32_16x16x32_bf16 v[38:41], v[168:171], v[232:235], v[38:41]
	v_mfma_f32_16x16x32_bf16 v[34:37], v[176:179], v[232:235], v[34:37]
	s_setprio 0
	s_barrier
	v_readfirstlane_b32 s1, v151
	v_lshl_add_u64 v[164:165], v[216:217], 0, s[78:79]
	s_mov_b32 m0, s1
	v_readfirstlane_b32 s1, v152
	global_load_lds_dwordx4 v[164:165], off
	v_lshl_add_u64 v[164:165], v[218:219], 0, s[78:79]
	s_mov_b32 m0, s1
	s_nop 0
	global_load_lds_dwordx4 v[164:165], off
	s_waitcnt vmcnt(6)
	s_barrier
	s_setprio 1
	v_mfma_f32_16x16x32_bf16 v[30:33], v[236:239], v[180:183], v[30:33]
	v_mfma_f32_16x16x32_bf16 v[26:29], v[244:247], v[180:183], v[26:29]
	v_mfma_f32_16x16x32_bf16 v[22:25], v[236:239], v[188:191], v[22:25]
	v_mfma_f32_16x16x32_bf16 v[18:21], v[244:247], v[188:191], v[18:21]
	v_mfma_f32_16x16x32_bf16 v[14:17], v[236:239], v[196:199], v[14:17]
	v_mfma_f32_16x16x32_bf16 v[10:13], v[244:247], v[196:199], v[10:13]
	v_mfma_f32_16x16x32_bf16 v[6:9], v[236:239], v[222:225], v[6:9]
	v_mfma_f32_16x16x32_bf16 v[2:5], v[244:247], v[222:225], v[2:5]
	v_mfma_f32_16x16x32_bf16 v[30:33], v[240:243], v[184:187], v[30:33]
	v_mfma_f32_16x16x32_bf16 v[26:29], v[248:251], v[184:187], v[26:29]
	v_mfma_f32_16x16x32_bf16 v[22:25], v[240:243], v[192:195], v[22:25]
	v_mfma_f32_16x16x32_bf16 v[18:21], v[248:251], v[192:195], v[18:21]
	v_mfma_f32_16x16x32_bf16 v[14:17], v[240:243], v[200:203], v[14:17]
	v_mfma_f32_16x16x32_bf16 v[10:13], v[248:251], v[200:203], v[10:13]
	v_mfma_f32_16x16x32_bf16 v[6:9], v[240:243], v[232:235], v[6:9]
	v_mfma_f32_16x16x32_bf16 v[2:5], v[248:251], v[232:235], v[2:5]
	s_setprio 0
	s_barrier
	v_readfirstlane_b32 s1, v153
	v_lshl_add_u64 v[228:229], v[204:205], 0, s[78:79]
	s_mov_b32 m0, s1
	v_readfirstlane_b32 s1, v154
	global_load_lds_dwordx4 v[228:229], off
	v_lshl_add_u64 v[228:229], v[210:211], 0, s[78:79]
	s_mov_b32 m0, s1
	s_nop 0
	global_load_lds_dwordx4 v[228:229], off
	ds_read_b128 v[164:167], v148 offset:32768
	ds_read_b128 v[168:171], v148 offset:33792
	ds_read_b128 v[172:175], v148 offset:34816
	ds_read_b128 v[176:179], v148 offset:35840
	ds_read_b128 v[180:183], v147 offset:32768
	ds_read_b128 v[184:187], v147 offset:33792
	ds_read_b128 v[188:191], v147 offset:34816
	ds_read_b128 v[192:195], v147 offset:35840
	ds_read_b128 v[196:199], v147 offset:36864
	ds_read_b128 v[200:203], v147 offset:37888
	ds_read_b128 v[222:225], v147 offset:38912
	ds_read_b128 v[232:235], v147 offset:39936
	s_waitcnt lgkmcnt(8)
	s_barrier
	s_waitcnt lgkmcnt(0)
	s_setprio 1
	s_waitcnt lgkmcnt(0)
	v_mfma_f32_16x16x32_bf16 v[126:129], v[164:167], v[180:183], v[126:129]
	v_mfma_f32_16x16x32_bf16 v[122:125], v[172:175], v[180:183], v[122:125]
	v_mfma_f32_16x16x32_bf16 v[118:121], v[164:167], v[188:191], v[118:121]
	v_mfma_f32_16x16x32_bf16 v[114:117], v[172:175], v[188:191], v[114:117]
	v_mfma_f32_16x16x32_bf16 v[110:113], v[164:167], v[196:199], v[110:113]
	v_mfma_f32_16x16x32_bf16 v[106:109], v[172:175], v[196:199], v[106:109]
	v_mfma_f32_16x16x32_bf16 v[102:105], v[164:167], v[222:225], v[102:105]
	v_mfma_f32_16x16x32_bf16 v[98:101], v[172:175], v[222:225], v[98:101]
	v_mfma_f32_16x16x32_bf16 v[126:129], v[168:171], v[184:187], v[126:129]
	v_mfma_f32_16x16x32_bf16 v[122:125], v[176:179], v[184:187], v[122:125]
	v_mfma_f32_16x16x32_bf16 v[118:121], v[168:171], v[192:195], v[118:121]
	v_mfma_f32_16x16x32_bf16 v[114:117], v[176:179], v[192:195], v[114:117]
	v_mfma_f32_16x16x32_bf16 v[110:113], v[168:171], v[200:203], v[110:113]
	v_mfma_f32_16x16x32_bf16 v[106:109], v[176:179], v[200:203], v[106:109]
	v_mfma_f32_16x16x32_bf16 v[102:105], v[168:171], v[232:235], v[102:105]
	v_mfma_f32_16x16x32_bf16 v[98:101], v[176:179], v[232:235], v[98:101]
	s_setprio 0
	s_barrier
	v_readfirstlane_b32 s1, v155
	v_lshl_add_u64 v[228:229], v[216:217], 0, s[28:29]
	s_mov_b32 m0, s1
	v_readfirstlane_b32 s1, v156
	global_load_lds_dwordx4 v[228:229], off
	v_lshl_add_u64 v[228:229], v[218:219], 0, s[28:29]
	s_mov_b32 m0, s1
	s_nop 0
	global_load_lds_dwordx4 v[228:229], off
	ds_read_b128 v[236:239], v148 offset:49152
	ds_read_b128 v[240:243], v148 offset:50176
	ds_read_b128 v[244:247], v148 offset:51200
	ds_read_b128 v[248:251], v148 offset:52224
	s_barrier
	s_waitcnt lgkmcnt(0)
	s_setprio 1
	s_waitcnt lgkmcnt(0)
	v_mfma_f32_16x16x32_bf16 v[94:97], v[236:239], v[180:183], v[94:97]
	v_mfma_f32_16x16x32_bf16 v[90:93], v[244:247], v[180:183], v[90:93]
	v_mfma_f32_16x16x32_bf16 v[86:89], v[236:239], v[188:191], v[86:89]
	v_mfma_f32_16x16x32_bf16 v[82:85], v[244:247], v[188:191], v[82:85]
	v_mfma_f32_16x16x32_bf16 v[78:81], v[236:239], v[196:199], v[78:81]
	v_mfma_f32_16x16x32_bf16 v[74:77], v[244:247], v[196:199], v[74:77]
	v_mfma_f32_16x16x32_bf16 v[70:73], v[236:239], v[222:225], v[70:73]
	v_mfma_f32_16x16x32_bf16 v[66:69], v[244:247], v[222:225], v[66:69]
	v_mfma_f32_16x16x32_bf16 v[94:97], v[240:243], v[184:187], v[94:97]
	v_mfma_f32_16x16x32_bf16 v[90:93], v[248:251], v[184:187], v[90:93]
	v_mfma_f32_16x16x32_bf16 v[86:89], v[240:243], v[192:195], v[86:89]
	v_mfma_f32_16x16x32_bf16 v[82:85], v[248:251], v[192:195], v[82:85]
	v_mfma_f32_16x16x32_bf16 v[78:81], v[240:243], v[200:203], v[78:81]
	v_mfma_f32_16x16x32_bf16 v[74:77], v[248:251], v[200:203], v[74:77]
	v_mfma_f32_16x16x32_bf16 v[70:73], v[240:243], v[232:235], v[70:73]
	v_mfma_f32_16x16x32_bf16 v[66:69], v[248:251], v[232:235], v[66:69]
	s_setprio 0
	v_readfirstlane_b32 s1, v157
	v_lshl_add_u64 v[204:205], v[204:205], 0, s[28:29]
	s_mov_b32 m0, s1
	v_readfirstlane_b32 s1, v158
	s_barrier
	global_load_lds_dwordx4 v[204:205], off
	v_lshl_add_u64 v[204:205], v[210:211], 0, s[28:29]
	s_mov_b32 m0, s1
	s_nop 0
	global_load_lds_dwordx4 v[204:205], off
	ds_read_b128 v[180:183], v147 offset:49152
	ds_read_b128 v[184:187], v147 offset:50176
	ds_read_b128 v[188:191], v147 offset:51200
	ds_read_b128 v[192:195], v147 offset:52224
	ds_read_b128 v[196:199], v147 offset:53248
	ds_read_b128 v[200:203], v147 offset:54272
	ds_read_b128 v[222:225], v147 offset:55296
	ds_read_b128 v[232:235], v147 offset:56320
	s_barrier
	s_waitcnt lgkmcnt(0)
	s_setprio 1
	s_waitcnt lgkmcnt(0)
	v_mfma_f32_16x16x32_bf16 v[62:65], v[164:167], v[180:183], v[62:65]
	v_mfma_f32_16x16x32_bf16 v[58:61], v[172:175], v[180:183], v[58:61]
	v_mfma_f32_16x16x32_bf16 v[54:57], v[164:167], v[188:191], v[54:57]
	v_mfma_f32_16x16x32_bf16 v[50:53], v[172:175], v[188:191], v[50:53]
	v_mfma_f32_16x16x32_bf16 v[46:49], v[164:167], v[196:199], v[46:49]
	v_mfma_f32_16x16x32_bf16 v[42:45], v[172:175], v[196:199], v[42:45]
	v_mfma_f32_16x16x32_bf16 v[38:41], v[164:167], v[222:225], v[38:41]
	v_mfma_f32_16x16x32_bf16 v[34:37], v[172:175], v[222:225], v[34:37]
	v_mfma_f32_16x16x32_bf16 v[62:65], v[168:171], v[184:187], v[62:65]
	v_mfma_f32_16x16x32_bf16 v[58:61], v[176:179], v[184:187], v[58:61]
	v_mfma_f32_16x16x32_bf16 v[54:57], v[168:171], v[192:195], v[54:57]
	v_mfma_f32_16x16x32_bf16 v[50:53], v[176:179], v[192:195], v[50:53]
	v_mfma_f32_16x16x32_bf16 v[46:49], v[168:171], v[200:203], v[46:49]
	v_mfma_f32_16x16x32_bf16 v[42:45], v[176:179], v[200:203], v[42:45]
	v_mfma_f32_16x16x32_bf16 v[38:41], v[168:171], v[232:235], v[38:41]
	v_mfma_f32_16x16x32_bf16 v[34:37], v[176:179], v[232:235], v[34:37]
	s_setprio 0
	s_barrier
	v_readfirstlane_b32 s1, v159
	v_lshl_add_u64 v[164:165], v[216:217], 0, s[68:69]
	s_mov_b32 m0, s1
	v_readfirstlane_b32 s1, v160
	global_load_lds_dwordx4 v[164:165], off
	v_lshl_add_u64 v[164:165], v[218:219], 0, s[68:69]
	s_mov_b32 m0, s1
	s_nop 0
	global_load_lds_dwordx4 v[164:165], off
	s_waitcnt vmcnt(6)
	s_barrier
	s_setprio 1
	v_mfma_f32_16x16x32_bf16 v[30:33], v[236:239], v[180:183], v[30:33]
	v_mfma_f32_16x16x32_bf16 v[26:29], v[244:247], v[180:183], v[26:29]
	v_mfma_f32_16x16x32_bf16 v[22:25], v[236:239], v[188:191], v[22:25]
	v_mfma_f32_16x16x32_bf16 v[18:21], v[244:247], v[188:191], v[18:21]
	v_mfma_f32_16x16x32_bf16 v[14:17], v[236:239], v[196:199], v[14:17]
	v_mfma_f32_16x16x32_bf16 v[10:13], v[244:247], v[196:199], v[10:13]
	v_mfma_f32_16x16x32_bf16 v[6:9], v[236:239], v[222:225], v[6:9]
	v_mfma_f32_16x16x32_bf16 v[2:5], v[244:247], v[222:225], v[2:5]
	v_mfma_f32_16x16x32_bf16 v[30:33], v[240:243], v[184:187], v[30:33]
	v_mfma_f32_16x16x32_bf16 v[26:29], v[248:251], v[184:187], v[26:29]
	v_mfma_f32_16x16x32_bf16 v[22:25], v[240:243], v[192:195], v[22:25]
	v_mfma_f32_16x16x32_bf16 v[18:21], v[248:251], v[192:195], v[18:21]
	v_mfma_f32_16x16x32_bf16 v[14:17], v[240:243], v[200:203], v[14:17]
	v_mfma_f32_16x16x32_bf16 v[10:13], v[248:251], v[200:203], v[10:13]
	v_mfma_f32_16x16x32_bf16 v[6:9], v[240:243], v[232:235], v[6:9]
	v_mfma_f32_16x16x32_bf16 v[2:5], v[248:251], v[232:235], v[2:5]
	s_setprio 0
	s_add_i32 s0, s0, 2
	s_add_u32 s10, s10, 0x100
	s_addc_u32 s11, s11, 0
	s_cmpk_lt_u32 s0, 0x54
	s_barrier
	s_cbranch_scc1 .LBB0_761
	s_add_u32 s0, s8, 0x162b80
	s_addc_u32 s1, s9, 0
	v_readfirstlane_b32 s8, v161
	v_lshl_add_u64 v[158:159], s[0:1], 0, v[0:1]
	s_mov_b32 m0, s8
	v_lshl_add_u64 v[130:131], s[0:1], 0, v[130:131]
	v_readfirstlane_b32 s0, v162
	ds_read_b128 v[132:135], v148
	ds_read_b128 v[136:139], v148 offset:1024
	ds_read_b128 v[150:153], v148 offset:2048
	ds_read_b128 v[154:157], v148 offset:3072
	ds_read_b128 v[164:167], v147
	ds_read_b128 v[168:171], v147 offset:1024
	ds_read_b128 v[172:175], v147 offset:2048
	ds_read_b128 v[176:179], v147 offset:3072
	ds_read_b128 v[180:183], v147 offset:4096
	ds_read_b128 v[184:187], v147 offset:5120
	ds_read_b128 v[188:191], v147 offset:6144
	ds_read_b128 v[192:195], v147 offset:7168
	global_load_lds_dwordx4 v[158:159], off
	s_mov_b32 m0, s0
	s_nop 0
	global_load_lds_dwordx4 v[130:131], off
	s_barrier
	s_waitcnt lgkmcnt(0)
	s_setprio 1
	s_waitcnt lgkmcnt(0)
	v_mfma_f32_16x16x32_bf16 v[122:125], v[150:153], v[164:167], v[122:125]
	v_mfma_f32_16x16x32_bf16 v[118:121], v[132:135], v[172:175], v[118:121]
	v_mfma_f32_16x16x32_bf16 v[114:117], v[150:153], v[172:175], v[114:117]
	v_mfma_f32_16x16x32_bf16 v[102:105], v[132:135], v[188:191], v[102:105]
	v_mfma_f32_16x16x32_bf16 v[98:101], v[150:153], v[188:191], v[98:101]
	v_mfma_f32_16x16x32_bf16 v[126:129], v[132:135], v[164:167], v[126:129]
	v_mfma_f32_16x16x32_bf16 v[122:125], v[154:157], v[168:171], v[122:125]
	v_mfma_f32_16x16x32_bf16 v[118:121], v[136:139], v[176:179], v[118:121]
	v_mfma_f32_16x16x32_bf16 v[114:117], v[154:157], v[176:179], v[114:117]
	v_mfma_f32_16x16x32_bf16 v[110:113], v[132:135], v[180:183], v[110:113]
	v_mfma_f32_16x16x32_bf16 v[106:109], v[150:153], v[180:183], v[106:109]
	v_mfma_f32_16x16x32_bf16 v[102:105], v[136:139], v[192:195], v[102:105]
	v_mfma_f32_16x16x32_bf16 v[98:101], v[154:157], v[192:195], v[98:101]
	v_mfma_f32_16x16x32_bf16 v[126:129], v[136:139], v[168:171], v[126:129]
	v_mfma_f32_16x16x32_bf16 v[158:161], v[136:139], v[184:187], v[110:113]
	v_mfma_f32_16x16x32_bf16 v[196:199], v[154:157], v[184:187], v[106:109]
	s_setprio 0
	s_barrier
	ds_read_b128 v[106:109], v148 offset:16384
	ds_read_b128 v[110:113], v148 offset:17408
	ds_read_b128 v[200:203], v148 offset:18432
	ds_read_b128 v[222:225], v148 offset:19456
	s_barrier
	s_waitcnt lgkmcnt(0)
	s_setprio 1
	s_waitcnt lgkmcnt(3)
	v_mfma_f32_16x16x32_bf16 v[86:89], v[106:109], v[172:175], v[86:89]
	s_waitcnt lgkmcnt(1)
	v_mfma_f32_16x16x32_bf16 v[82:85], v[200:203], v[172:175], v[82:85]
	v_mfma_f32_16x16x32_bf16 v[70:73], v[106:109], v[188:191], v[70:73]
	v_mfma_f32_16x16x32_bf16 v[66:69], v[200:203], v[188:191], v[66:69]
	v_mfma_f32_16x16x32_bf16 v[94:97], v[106:109], v[164:167], v[94:97]
	v_mfma_f32_16x16x32_bf16 v[90:93], v[200:203], v[164:167], v[90:93]
	v_mfma_f32_16x16x32_bf16 v[86:89], v[110:113], v[176:179], v[86:89]
	s_waitcnt lgkmcnt(0)
	v_mfma_f32_16x16x32_bf16 v[82:85], v[222:225], v[176:179], v[82:85]
	v_mfma_f32_16x16x32_bf16 v[78:81], v[106:109], v[180:183], v[78:81]
	v_mfma_f32_16x16x32_bf16 v[74:77], v[200:203], v[180:183], v[74:77]
	v_mfma_f32_16x16x32_bf16 v[70:73], v[110:113], v[192:195], v[70:73]
	v_mfma_f32_16x16x32_bf16 v[66:69], v[222:225], v[192:195], v[66:69]
	v_mfma_f32_16x16x32_bf16 v[232:235], v[110:113], v[168:171], v[94:97]
	v_mfma_f32_16x16x32_bf16 v[162:165], v[222:225], v[168:171], v[90:93]
	v_mfma_f32_16x16x32_bf16 v[166:169], v[110:113], v[184:187], v[78:81]
	v_mfma_f32_16x16x32_bf16 v[170:173], v[222:225], v[184:187], v[74:77]
	s_setprio 0
	s_barrier
	s_nop 0
	ds_read_b128 v[74:77], v147 offset:16384
	ds_read_b128 v[78:81], v147 offset:17408
	ds_read_b128 v[90:93], v147 offset:18432
	ds_read_b128 v[94:97], v147 offset:19456
	ds_read_b128 v[174:177], v147 offset:20480
	ds_read_b128 v[178:181], v147 offset:21504
	ds_read_b128 v[182:185], v147 offset:22528
	ds_read_b128 v[186:189], v147 offset:23552
	s_waitcnt vmcnt(4)
	s_barrier
	s_waitcnt lgkmcnt(0)
	s_setprio 1
	s_waitcnt lgkmcnt(7)
	v_mfma_f32_16x16x32_bf16 v[62:65], v[132:135], v[74:77], v[62:65]
	v_mfma_f32_16x16x32_bf16 v[58:61], v[150:153], v[74:77], v[58:61]
	s_waitcnt lgkmcnt(5)
	v_mfma_f32_16x16x32_bf16 v[54:57], v[132:135], v[90:93], v[54:57]
	v_mfma_f32_16x16x32_bf16 v[50:53], v[150:153], v[90:93], v[50:53]
	s_waitcnt lgkmcnt(1)
	v_mfma_f32_16x16x32_bf16 v[38:41], v[132:135], v[182:185], v[38:41]
	v_mfma_f32_16x16x32_bf16 v[34:37], v[150:153], v[182:185], v[34:37]
	v_mfma_f32_16x16x32_bf16 v[62:65], v[136:139], v[78:81], v[62:65]
	v_mfma_f32_16x16x32_bf16 v[58:61], v[154:157], v[78:81], v[58:61]
	v_mfma_f32_16x16x32_bf16 v[54:57], v[136:139], v[94:97], v[54:57]
	v_mfma_f32_16x16x32_bf16 v[50:53], v[154:157], v[94:97], v[50:53]
	v_mfma_f32_16x16x32_bf16 v[46:49], v[132:135], v[174:177], v[46:49]
	v_mfma_f32_16x16x32_bf16 v[42:45], v[150:153], v[174:177], v[42:45]
	s_waitcnt lgkmcnt(0)
	v_mfma_f32_16x16x32_bf16 v[38:41], v[136:139], v[186:189], v[38:41]
	v_mfma_f32_16x16x32_bf16 v[34:37], v[154:157], v[186:189], v[34:37]
	v_mfma_f32_16x16x32_bf16 v[190:193], v[136:139], v[178:181], v[46:49]
	v_mfma_f32_16x16x32_bf16 v[236:239], v[154:157], v[178:181], v[42:45]
	s_setprio 0
	s_setprio 1
	v_mfma_f32_16x16x32_bf16 v[22:25], v[106:109], v[90:93], v[22:25]
	v_mfma_f32_16x16x32_bf16 v[18:21], v[200:203], v[90:93], v[18:21]
	v_mfma_f32_16x16x32_bf16 v[6:9], v[106:109], v[182:185], v[6:9]
	v_mfma_f32_16x16x32_bf16 v[2:5], v[200:203], v[182:185], v[2:5]
	v_mfma_f32_16x16x32_bf16 v[30:33], v[106:109], v[74:77], v[30:33]
	v_mfma_f32_16x16x32_bf16 v[26:29], v[200:203], v[74:77], v[26:29]
	v_mfma_f32_16x16x32_bf16 v[22:25], v[110:113], v[94:97], v[22:25]
	v_mfma_f32_16x16x32_bf16 v[18:21], v[222:225], v[94:97], v[18:21]
	v_mfma_f32_16x16x32_bf16 v[14:17], v[106:109], v[174:177], v[14:17]
	v_mfma_f32_16x16x32_bf16 v[10:13], v[200:203], v[174:177], v[10:13]
	v_mfma_f32_16x16x32_bf16 v[6:9], v[110:113], v[186:189], v[6:9]
	v_mfma_f32_16x16x32_bf16 v[2:5], v[222:225], v[186:189], v[2:5]
	v_mfma_f32_16x16x32_bf16 v[134:137], v[110:113], v[78:81], v[30:33]
	v_mfma_f32_16x16x32_bf16 v[150:153], v[222:225], v[78:81], v[26:29]
	v_mfma_f32_16x16x32_bf16 v[154:157], v[110:113], v[178:181], v[14:17]
	v_mfma_f32_16x16x32_bf16 v[174:177], v[222:225], v[178:181], v[10:13]
	s_setprio 0
	s_barrier
	s_nop 0
	ds_read_b128 v[10:13], v148 offset:32768
	ds_read_b128 v[14:17], v148 offset:33792
	ds_read_b128 v[178:181], v148 offset:34816
	ds_read_b128 v[182:185], v148 offset:35840
	ds_read_b128 v[26:29], v147 offset:32768
	ds_read_b128 v[30:33], v147 offset:33792
	ds_read_b128 v[42:45], v147 offset:34816
	ds_read_b128 v[46:49], v147 offset:35840
	ds_read_b128 v[186:189], v147 offset:36864
	ds_read_b128 v[200:203], v147 offset:37888
	ds_read_b128 v[222:225], v147 offset:38912
	ds_read_b128 v[240:243], v147 offset:39936
	s_waitcnt vmcnt(2)
	s_barrier
	s_waitcnt lgkmcnt(0)
	s_setprio 1
	s_waitcnt lgkmcnt(7)
	v_mfma_f32_16x16x32_bf16 v[74:77], v[10:13], v[26:29], v[126:129]
	s_waitcnt lgkmcnt(6)
	v_mfma_f32_16x16x32_bf16 v[130:133], v[14:17], v[30:33], v[74:77]
	v_mfma_f32_16x16x32_bf16 v[74:77], v[178:181], v[26:29], v[122:125]
	v_mfma_f32_16x16x32_bf16 v[122:125], v[182:185], v[30:33], v[74:77]
	s_waitcnt lgkmcnt(5)
	v_mfma_f32_16x16x32_bf16 v[74:77], v[10:13], v[42:45], v[118:121]
	s_waitcnt lgkmcnt(4)
	v_mfma_f32_16x16x32_bf16 v[110:113], v[14:17], v[46:49], v[74:77]
	v_mfma_f32_16x16x32_bf16 v[74:77], v[178:181], v[42:45], v[114:117]
	v_mfma_f32_16x16x32_bf16 v[106:109], v[182:185], v[46:49], v[74:77]
	s_waitcnt lgkmcnt(3)
	v_mfma_f32_16x16x32_bf16 v[74:77], v[10:13], v[186:189], v[158:161]
	s_waitcnt lgkmcnt(2)
	v_mfma_f32_16x16x32_bf16 v[94:97], v[14:17], v[200:203], v[74:77]
	v_mfma_f32_16x16x32_bf16 v[74:77], v[178:181], v[186:189], v[196:199]
	v_mfma_f32_16x16x32_bf16 v[90:93], v[182:185], v[200:203], v[74:77]
	s_waitcnt lgkmcnt(1)
	v_mfma_f32_16x16x32_bf16 v[74:77], v[10:13], v[222:225], v[102:105]
	s_waitcnt lgkmcnt(0)
	v_mfma_f32_16x16x32_bf16 v[78:81], v[14:17], v[240:243], v[74:77]
	v_mfma_f32_16x16x32_bf16 v[74:77], v[178:181], v[222:225], v[98:101]
	v_mfma_f32_16x16x32_bf16 v[74:77], v[182:185], v[240:243], v[74:77]
	s_setprio 0
	s_barrier
	ds_read_b128 v[126:129], v148 offset:49152
	ds_read_b128 v[158:161], v148 offset:50176
	ds_read_b128 v[194:197], v148 offset:51200
	ds_read_b128 v[244:247], v148 offset:52224
	s_waitcnt vmcnt(0)
	s_barrier
	s_waitcnt lgkmcnt(0)
	s_setprio 1
	s_waitcnt lgkmcnt(3)
	v_mfma_f32_16x16x32_bf16 v[98:101], v[126:129], v[26:29], v[232:235]
	s_waitcnt lgkmcnt(1)
	v_mfma_f32_16x16x32_bf16 v[26:29], v[194:197], v[26:29], v[162:165]
	s_waitcnt lgkmcnt(0)
	v_mfma_f32_16x16x32_bf16 v[114:117], v[244:247], v[30:33], v[26:29]
	v_mfma_f32_16x16x32_bf16 v[26:29], v[126:129], v[42:45], v[86:89]
	v_mfma_f32_16x16x32_bf16 v[102:105], v[158:161], v[46:49], v[26:29]
	v_mfma_f32_16x16x32_bf16 v[26:29], v[194:197], v[42:45], v[82:85]
	v_mfma_f32_16x16x32_bf16 v[118:121], v[158:161], v[30:33], v[98:101]
	v_mfma_f32_16x16x32_bf16 v[98:101], v[244:247], v[46:49], v[26:29]
	v_mfma_f32_16x16x32_bf16 v[26:29], v[126:129], v[186:189], v[166:169]
	v_mfma_f32_16x16x32_bf16 v[86:89], v[158:161], v[200:203], v[26:29]
	v_mfma_f32_16x16x32_bf16 v[26:29], v[194:197], v[186:189], v[170:173]
	v_mfma_f32_16x16x32_bf16 v[82:85], v[244:247], v[200:203], v[26:29]
	v_mfma_f32_16x16x32_bf16 v[26:29], v[126:129], v[222:225], v[70:73]
	v_mfma_f32_16x16x32_bf16 v[70:73], v[158:161], v[240:243], v[26:29]
	v_mfma_f32_16x16x32_bf16 v[26:29], v[194:197], v[222:225], v[66:69]
	v_mfma_f32_16x16x32_bf16 v[66:69], v[244:247], v[240:243], v[26:29]
	s_setprio 0
	s_barrier
	ds_read_b128 v[162:165], v147 offset:49152
	ds_read_b128 v[166:169], v147 offset:50176
	ds_read_b128 v[170:173], v147 offset:51200
	ds_read_b128 v[186:189], v147 offset:52224
	ds_read_b128 v[198:201], v147 offset:53248
	ds_read_b128 v[202:205], v147 offset:54272
	ds_read_b128 v[222:225], v147 offset:55296
	ds_read_b128 v[146:149], v147 offset:56320
	s_barrier
	s_waitcnt lgkmcnt(0)
	s_setprio 1
	s_waitcnt lgkmcnt(7)
	v_mfma_f32_16x16x32_bf16 v[26:29], v[10:13], v[162:165], v[62:65]
	s_waitcnt lgkmcnt(6)
	v_mfma_f32_16x16x32_bf16 v[62:65], v[14:17], v[166:169], v[26:29]
	v_mfma_f32_16x16x32_bf16 v[26:29], v[178:181], v[162:165], v[58:61]
	v_mfma_f32_16x16x32_bf16 v[58:61], v[182:185], v[166:169], v[26:29]
	s_waitcnt lgkmcnt(5)
	v_mfma_f32_16x16x32_bf16 v[26:29], v[10:13], v[170:173], v[54:57]
	s_waitcnt lgkmcnt(4)
	v_mfma_f32_16x16x32_bf16 v[46:49], v[14:17], v[186:189], v[26:29]
	v_mfma_f32_16x16x32_bf16 v[26:29], v[178:181], v[170:173], v[50:53]
	v_mfma_f32_16x16x32_bf16 v[42:45], v[182:185], v[186:189], v[26:29]
	s_waitcnt lgkmcnt(3)
	v_mfma_f32_16x16x32_bf16 v[26:29], v[10:13], v[198:201], v[190:193]
	s_waitcnt lgkmcnt(1)
	v_mfma_f32_16x16x32_bf16 v[10:13], v[10:13], v[222:225], v[38:41]
	v_mfma_f32_16x16x32_bf16 v[30:33], v[14:17], v[202:205], v[26:29]
	v_mfma_f32_16x16x32_bf16 v[26:29], v[178:181], v[198:201], v[236:239]
	s_waitcnt lgkmcnt(0)
	v_mfma_f32_16x16x32_bf16 v[14:17], v[14:17], v[146:149], v[10:13]
	v_mfma_f32_16x16x32_bf16 v[10:13], v[178:181], v[222:225], v[34:37]
	v_mfma_f32_16x16x32_bf16 v[26:29], v[182:185], v[202:205], v[26:29]
	v_mfma_f32_16x16x32_bf16 v[10:13], v[182:185], v[146:149], v[10:13]
	s_setprio 0
	s_setprio 1
	v_mfma_f32_16x16x32_bf16 v[34:37], v[126:129], v[162:165], v[134:137]
	v_mfma_f32_16x16x32_bf16 v[54:57], v[158:161], v[166:169], v[34:37]
	v_mfma_f32_16x16x32_bf16 v[34:37], v[194:197], v[162:165], v[150:153]
	v_mfma_f32_16x16x32_bf16 v[18:21], v[194:197], v[170:173], v[18:21]
	v_mfma_f32_16x16x32_bf16 v[50:53], v[244:247], v[166:169], v[34:37]
	v_mfma_f32_16x16x32_bf16 v[22:25], v[126:129], v[170:173], v[22:25]
	v_mfma_f32_16x16x32_bf16 v[34:37], v[244:247], v[186:189], v[18:21]
	v_mfma_f32_16x16x32_bf16 v[18:21], v[126:129], v[198:201], v[154:157]
	v_mfma_f32_16x16x32_bf16 v[38:41], v[158:161], v[186:189], v[22:25]
	v_mfma_f32_16x16x32_bf16 v[22:25], v[158:161], v[202:205], v[18:21]
	v_mfma_f32_16x16x32_bf16 v[18:21], v[194:197], v[198:201], v[174:177]
	v_mfma_f32_16x16x32_bf16 v[6:9], v[126:129], v[222:225], v[6:9]
	v_mfma_f32_16x16x32_bf16 v[2:5], v[194:197], v[222:225], v[2:5]
	v_mfma_f32_16x16x32_bf16 v[18:21], v[244:247], v[202:205], v[18:21]
	v_mfma_f32_16x16x32_bf16 v[6:9], v[158:161], v[146:149], v[6:9]
	v_mfma_f32_16x16x32_bf16 v[2:5], v[244:247], v[146:149], v[2:5]
	s_setprio 0
	s_movk_i32 s0, 0x100
	v_cmp_gt_u32_e32 vcc, s0, v140
	s_barrier
	s_and_saveexec_b64 s[0:1], vcc
	s_cbranch_execz .LBB0_764
	s_barrier
